# GEMM K-loops: per-phase s_setprio flips replaced by s_nop (priority static 0)
# speedup vs baseline: 1.0056x; 1.0056x over previous
; #define PG8_STAGE(bufoff, gbase, voff) do { _Pragma("unroll") for (int _i = 0; _i < 2; ++_i) \
;         __builtin_amdgcn_global_load_lds((const unsigned*)((const char*)(gbase) + (voff)[_i]), (LAS unsigned*)(lds + (bufoff) + ldsw + _i * 8192), 16, 0, 0); } while (0)
; #define PG8_LDA(dst, b, h) do { _Pragma("unroll") for (int m = 0; m < 4; ++m) _Pragma("unroll") for (int k = 0; k < 2; ++k) dst[m][k] = *(const LAS bf16x8*)(lds + PG8_SA(b, h) + aoff + m * 2048 + k * 1024); } while (0)
; #define PG8_LDB(dst, b, h) do { _Pragma("unroll") for (int n = 0; n < 2; ++n) _Pragma("unroll") for (int k = 0; k < 2; ++k) dst[n][k] = *(const LAS bf16x8*)(lds + PG8_SB(b, h) + boff + n * 2048 + k * 1024); } while (0)
; #define PG8_MMA(ai, bj, At, Bt) do { __builtin_amdgcn_s_setprio(1); _Pragma("unroll") for (int m = 0; m < 4; ++m) _Pragma("unroll") for (int n = 0; n < 2; ++n) _Pragma("unroll") for (int k = 0; k < 2; ++k) \
;         acc[ai][bj][m][n] = __builtin_amdgcn_mfma_f32_16x16x32_bf16(Bt[n][k], At[m][k], acc[ai][bj][m][n], 0, 0, 0); __builtin_amdgcn_s_setprio(0); } while (0)
; #define PG8_WAIT_V(n) asm volatile("s_waitcnt vmcnt(" #n ")" ::: "memory")
; #define PG8_WAIT_L(n) asm volatile("s_waitcnt lgkmcnt(" #n ")" ::: "memory")
; #define PG8_BAR __builtin_amdgcn_s_barrier()
; #define PG8_SCHED __builtin_amdgcn_sched_barrier(0)
; template <class Epi, class Sched>
; DI void gemm_phase(LAS unsigned char* lds, const int K, const Sched& S, const Epi& E) {
;     ...
;         for (int t = 0; t < nt; t += 2) {
;             const bool last = (t == nt - 2);
;             const char* a1 = cA + (size_t)(t + 1) * kstep;
;             const char* a2 = last ? nA : cA + (size_t)(t + 2) * kstep; const char* b2 = last ? nB : cB + (size_t)(t + 2) * kstep;
;             const char* a3 = a2 + kstep; const char* b3 = b2 + kstep;
;             PG8_LDB(B0, 0, 0); PG8_LDB(B1, 0, 1); PG8_SCHED; PG8_LDA(At, 0, 0); PG8_STAGE(PG8_SA(1, 1), a1 + hstep, voffA);
;             PG8_WAIT_V(8); PG8_WAIT_L(0); PG8_BAR; PG8_MMA(0, 0, At, B0); PG8_MMA(0, 1, At, B1); PG8_BAR; PG8_SCHED;
;             PG8_LDA(At, 0, 1); PG8_STAGE(PG8_SB(0, 0), b2, voffB); PG8_STAGE(PG8_SB(0, 1), b2 + hstep, voffB); PG8_STAGE(PG8_SA(0, 0), a2, voffA);
;             PG8_WAIT_V(8); PG8_WAIT_L(0); PG8_BAR; PG8_MMA(1, 0, At, B0); PG8_MMA(1, 1, At, B1); PG8_BAR; PG8_SCHED;
.LBB0_218:
	s_add_u32 s80, s78, 0xfffc0080
	s_addc_u32 s81, s79, -1
	s_add_i32 vcc_lo, 0, 0x10000
	s_cmp_eq_u32 s87, 12
	s_cselect_b32 s83, s45, s81
	s_cselect_b32 s82, s73, s80
	s_cselect_b32 s81, s77, s86
	s_cselect_b32 s80, s84, s85
	s_add_i32 s63, 0, 0x14000
	v_add_u32_e32 v142, vcc_lo, v201
	v_add_u32_e32 v158, s63, v201
	ds_read_b128 v[130:133], v142
	ds_read_b128 v[134:137], v142 offset:1024
	ds_read_b128 v[138:141], v142 offset:2048
	ds_read_b128 v[142:145], v142 offset:3072
	ds_read_b128 v[146:149], v158
	ds_read_b128 v[150:153], v158 offset:1024
	ds_read_b128 v[154:157], v158 offset:2048
	ds_read_b128 v[158:161], v158 offset:3072
	v_lshl_add_u64 v[198:199], s[78:79], 0, v[172:173]
	s_add_i32 m0, s56, 0xc000
	ds_read_b128 v[174:177], v202
	ds_read_b128 v[182:185], v202 offset:1024
	ds_read_b128 v[190:193], v202 offset:2048
	ds_read_b128 v[194:197], v202 offset:3072
	ds_read_b128 v[212:215], v202 offset:4096
	ds_read_b128 v[216:219], v202 offset:5120
	ds_read_b128 v[220:223], v202 offset:6144
	ds_read_b128 v[224:227], v202 offset:7168
	global_load_lds_dwordx4 v[198:199], off
	v_lshl_add_u64 v[198:199], s[78:79], 0, v[170:171]
	s_add_i32 m0, s56, 0xe000
	s_nop 0
	global_load_lds_dwordx4 v[198:199], off
	s_waitcnt vmcnt(8)
	s_waitcnt lgkmcnt(0)
	s_barrier
	s_nop 0
	s_waitcnt lgkmcnt(0)
	v_mfma_f32_16x16x32_bf16 v[126:129], v[130:133], v[174:177], v[126:129]
	v_mfma_f32_16x16x32_bf16 v[122:125], v[138:141], v[174:177], v[122:125]
	v_mfma_f32_16x16x32_bf16 v[110:113], v[130:133], v[190:193], v[110:113]
	v_mfma_f32_16x16x32_bf16 v[106:109], v[138:141], v[190:193], v[106:109]
	v_mfma_f32_16x16x32_bf16 v[94:97], v[130:133], v[212:215], v[94:97]
	v_mfma_f32_16x16x32_bf16 v[90:93], v[138:141], v[212:215], v[90:93]
	v_mfma_f32_16x16x32_bf16 v[78:81], v[130:133], v[220:223], v[78:81]
	v_mfma_f32_16x16x32_bf16 v[74:77], v[138:141], v[220:223], v[74:77]
	v_mfma_f32_16x16x32_bf16 v[126:129], v[134:137], v[182:185], v[126:129]
	v_mfma_f32_16x16x32_bf16 v[122:125], v[142:145], v[182:185], v[122:125]
	v_mfma_f32_16x16x32_bf16 v[110:113], v[134:137], v[194:197], v[110:113]
	v_mfma_f32_16x16x32_bf16 v[106:109], v[142:145], v[194:197], v[106:109]
	v_mfma_f32_16x16x32_bf16 v[94:97], v[134:137], v[216:219], v[94:97]
	v_mfma_f32_16x16x32_bf16 v[90:93], v[142:145], v[216:219], v[90:93]
	v_mfma_f32_16x16x32_bf16 v[78:81], v[134:137], v[224:227], v[78:81]
	v_mfma_f32_16x16x32_bf16 v[74:77], v[142:145], v[224:227], v[74:77]
	s_nop 0
	s_nop 0
	v_mfma_f32_16x16x32_bf16 v[118:121], v[146:149], v[174:177], v[118:121]
	v_mfma_f32_16x16x32_bf16 v[114:117], v[154:157], v[174:177], v[114:117]
	v_mfma_f32_16x16x32_bf16 v[102:105], v[146:149], v[190:193], v[102:105]
	v_mfma_f32_16x16x32_bf16 v[98:101], v[154:157], v[190:193], v[98:101]
	v_mfma_f32_16x16x32_bf16 v[86:89], v[146:149], v[212:215], v[86:89]
	v_mfma_f32_16x16x32_bf16 v[82:85], v[154:157], v[212:215], v[82:85]
	v_mfma_f32_16x16x32_bf16 v[70:73], v[146:149], v[220:223], v[70:73]
	v_mfma_f32_16x16x32_bf16 v[66:69], v[154:157], v[220:223], v[66:69]
	v_mfma_f32_16x16x32_bf16 v[118:121], v[150:153], v[182:185], v[118:121]
	v_mfma_f32_16x16x32_bf16 v[114:117], v[158:161], v[182:185], v[114:117]
	v_mfma_f32_16x16x32_bf16 v[102:105], v[150:153], v[194:197], v[102:105]
	v_mfma_f32_16x16x32_bf16 v[98:101], v[158:161], v[194:197], v[98:101]
	v_mfma_f32_16x16x32_bf16 v[86:89], v[150:153], v[216:219], v[86:89]
	v_mfma_f32_16x16x32_bf16 v[82:85], v[158:161], v[216:219], v[82:85]
	v_mfma_f32_16x16x32_bf16 v[70:73], v[150:153], v[224:227], v[70:73]
	v_mfma_f32_16x16x32_bf16 v[66:69], v[158:161], v[224:227], v[66:69]
	s_nop 0
	s_barrier
	s_add_i32 vcc_lo, vcc_lo, s55
	v_lshl_add_u64 v[198:199], s[80:81], 0, v[164:165]
	s_mov_b32 m0, vcc_lo
	ds_read_b128 v[174:177], v202 offset:16384
	ds_read_b128 v[182:185], v202 offset:17408
	ds_read_b128 v[190:193], v202 offset:18432
	ds_read_b128 v[194:197], v202 offset:19456
	ds_read_b128 v[212:215], v202 offset:20480
	ds_read_b128 v[216:219], v202 offset:21504
	ds_read_b128 v[220:223], v202 offset:22528
	ds_read_b128 v[224:227], v202 offset:23552
	global_load_lds_dwordx4 v[198:199], off
	s_add_i32 m0, vcc_lo, 0x2000
	s_add_u32 vcc_lo, s80, 0x40000
	v_lshl_add_u64 v[204:205], s[80:81], 0, v[168:169]
	s_addc_u32 vcc_hi, s81, 0
	s_add_i32 s63, s63, s55
	global_load_lds_dwordx4 v[204:205], off
	v_lshl_add_u64 v[228:229], vcc, 0, v[164:165]
	s_mov_b32 m0, s63
	v_lshl_add_u64 v[230:231], s[82:83], 0, v[166:167]
	global_load_lds_dwordx4 v[228:229], off
	v_lshl_add_u64 v[228:229], vcc, 0, v[168:169]
	s_add_i32 m0, s63, 0x2000
	s_nop 0
	global_load_lds_dwordx4 v[228:229], off
	v_lshl_add_u64 v[228:229], s[82:83], 0, v[162:163]
	s_mov_b32 m0, s56
	s_nop 0
	global_load_lds_dwordx4 v[228:229], off
	s_mov_b32 m0, s57
	s_nop 0
	global_load_lds_dwordx4 v[230:231], off
	s_waitcnt vmcnt(8)
	s_waitcnt lgkmcnt(0)
	s_barrier
; #define PG8_STAGE(bufoff, gbase, voff) do { _Pragma("unroll") for (int _i = 0; _i < 2; ++_i) \
;         __builtin_amdgcn_global_load_lds((const unsigned*)((const char*)(gbase) + (voff)[_i]), (LAS unsigned*)(lds + (bufoff) + ldsw + _i * 8192), 16, 0, 0); } while (0)
; #define PG8_LDA(dst, b, h) do { _Pragma("unroll") for (int m = 0; m < 4; ++m) _Pragma("unroll") for (int k = 0; k < 2; ++k) dst[m][k] = *(const LAS bf16x8*)(lds + PG8_SA(b, h) + aoff + m * 2048 + k * 1024); } while (0)
; #define PG8_LDB(dst, b, h) do { _Pragma("unroll") for (int n = 0; n < 2; ++n) _Pragma("unroll") for (int k = 0; k < 2; ++k) dst[n][k] = *(const LAS bf16x8*)(lds + PG8_SB(b, h) + boff + n * 2048 + k * 1024); } while (0)
; #define PG8_MMA(ai, bj, At, Bt) do { __builtin_amdgcn_s_setprio(1); _Pragma("unroll") for (int m = 0; m < 4; ++m) _Pragma("unroll") for (int n = 0; n < 2; ++n) _Pragma("unroll") for (int k = 0; k < 2; ++k) \
;         acc[ai][bj][m][n] = __builtin_amdgcn_mfma_f32_16x16x32_bf16(Bt[n][k], At[m][k], acc[ai][bj][m][n], 0, 0, 0); __builtin_amdgcn_s_setprio(0); } while (0)
; #define PG8_WAIT_V(n) asm volatile("s_waitcnt vmcnt(" #n ")" ::: "memory")
; #define PG8_WAIT_L(n) asm volatile("s_waitcnt lgkmcnt(" #n ")" ::: "memory")
; #define PG8_BAR __builtin_amdgcn_s_barrier()
; #define PG8_SCHED __builtin_amdgcn_sched_barrier(0)
; template <class Epi, class Sched>
; DI void gemm_phase(LAS unsigned char* lds, const int K, const Sched& S, const Epi& E) {
;     ...
;             PG8_WAIT_V(8); PG8_WAIT_L(0); PG8_BAR; PG8_MMA(1, 0, At, B0); PG8_MMA(1, 1, At, B1); PG8_BAR; PG8_SCHED;
;             PG8_LDB(B0, 1, 0); PG8_LDB(B1, 1, 1); PG8_SCHED; PG8_LDA(At, 1, 0); PG8_STAGE(PG8_SA(0, 1), a2 + hstep, voffA);
;             PG8_WAIT_V(8); PG8_WAIT_L(0); PG8_BAR; PG8_MMA(0, 0, At, B0); PG8_MMA(0, 1, At, B1); PG8_BAR; PG8_SCHED;
	s_nop 0
	s_waitcnt lgkmcnt(0)
	v_mfma_f32_16x16x32_bf16 v[62:65], v[130:133], v[174:177], v[62:65]
	v_mfma_f32_16x16x32_bf16 v[58:61], v[138:141], v[174:177], v[58:61]
	v_mfma_f32_16x16x32_bf16 v[46:49], v[130:133], v[190:193], v[46:49]
	v_mfma_f32_16x16x32_bf16 v[42:45], v[138:141], v[190:193], v[42:45]
	v_mfma_f32_16x16x32_bf16 v[30:33], v[130:133], v[212:215], v[30:33]
	v_mfma_f32_16x16x32_bf16 v[26:29], v[138:141], v[212:215], v[26:29]
	v_mfma_f32_16x16x32_bf16 v[14:17], v[130:133], v[220:223], v[14:17]
	v_mfma_f32_16x16x32_bf16 v[10:13], v[138:141], v[220:223], v[10:13]
	v_mfma_f32_16x16x32_bf16 v[62:65], v[134:137], v[182:185], v[62:65]
	v_mfma_f32_16x16x32_bf16 v[58:61], v[142:145], v[182:185], v[58:61]
	v_mfma_f32_16x16x32_bf16 v[46:49], v[134:137], v[194:197], v[46:49]
	v_mfma_f32_16x16x32_bf16 v[42:45], v[142:145], v[194:197], v[42:45]
	v_mfma_f32_16x16x32_bf16 v[30:33], v[134:137], v[216:219], v[30:33]
	v_mfma_f32_16x16x32_bf16 v[26:29], v[142:145], v[216:219], v[26:29]
	v_mfma_f32_16x16x32_bf16 v[14:17], v[134:137], v[224:227], v[14:17]
	v_mfma_f32_16x16x32_bf16 v[10:13], v[142:145], v[224:227], v[10:13]
	s_nop 0
	s_nop 0
	v_mfma_f32_16x16x32_bf16 v[54:57], v[146:149], v[174:177], v[54:57]
	v_mfma_f32_16x16x32_bf16 v[50:53], v[154:157], v[174:177], v[50:53]
	v_mfma_f32_16x16x32_bf16 v[38:41], v[146:149], v[190:193], v[38:41]
	v_mfma_f32_16x16x32_bf16 v[34:37], v[154:157], v[190:193], v[34:37]
	v_mfma_f32_16x16x32_bf16 v[22:25], v[146:149], v[212:215], v[22:25]
	v_mfma_f32_16x16x32_bf16 v[18:21], v[154:157], v[212:215], v[18:21]
	v_mfma_f32_16x16x32_bf16 v[6:9], v[146:149], v[220:223], v[6:9]
	v_mfma_f32_16x16x32_bf16 v[2:5], v[154:157], v[220:223], v[2:5]
	v_mfma_f32_16x16x32_bf16 v[54:57], v[150:153], v[182:185], v[54:57]
	v_mfma_f32_16x16x32_bf16 v[50:53], v[158:161], v[182:185], v[50:53]
	v_mfma_f32_16x16x32_bf16 v[38:41], v[150:153], v[194:197], v[38:41]
	v_mfma_f32_16x16x32_bf16 v[34:37], v[158:161], v[194:197], v[34:37]
	v_mfma_f32_16x16x32_bf16 v[22:25], v[150:153], v[216:219], v[22:25]
	v_mfma_f32_16x16x32_bf16 v[18:21], v[158:161], v[216:219], v[18:21]
	v_mfma_f32_16x16x32_bf16 v[6:9], v[150:153], v[224:227], v[6:9]
	v_mfma_f32_16x16x32_bf16 v[2:5], v[158:161], v[224:227], v[2:5]
	s_nop 0
	s_barrier
	s_add_i32 s63, 0, 0x18000
	s_add_i32 vcc_lo, 0, 0x1c000
	v_add_u32_e32 v142, s63, v201
	v_add_u32_e32 v158, vcc_lo, v201
	ds_read_b128 v[130:133], v142
	ds_read_b128 v[134:137], v142 offset:1024
	ds_read_b128 v[138:141], v142 offset:2048
	ds_read_b128 v[142:145], v142 offset:3072
	ds_read_b128 v[146:149], v158
	ds_read_b128 v[150:153], v158 offset:1024
	ds_read_b128 v[154:157], v158 offset:2048
	ds_read_b128 v[158:161], v158 offset:3072
	s_add_u32 s82, s82, 0x40000
	s_addc_u32 s83, s83, 0
	s_mov_b32 m0, s58
	v_lshl_add_u64 v[232:233], s[82:83], 0, v[162:163]
	ds_read_b128 v[174:177], v202 offset:32768
	ds_read_b128 v[182:185], v202 offset:33792
	ds_read_b128 v[190:193], v202 offset:34816
	ds_read_b128 v[194:197], v202 offset:35840
	ds_read_b128 v[212:215], v202 offset:36864
	ds_read_b128 v[216:219], v202 offset:37888
	ds_read_b128 v[220:223], v202 offset:38912
	ds_read_b128 v[224:227], v202 offset:39936
	global_load_lds_dwordx4 v[232:233], off
	v_lshl_add_u64 v[232:233], s[82:83], 0, v[166:167]
	s_mov_b32 m0, s59
	s_nop 0
	global_load_lds_dwordx4 v[232:233], off
	s_waitcnt vmcnt(8)
	s_waitcnt lgkmcnt(0)
	s_barrier
	s_nop 0
	s_waitcnt lgkmcnt(0)
	v_mfma_f32_16x16x32_bf16 v[126:129], v[130:133], v[174:177], v[126:129]
	v_mfma_f32_16x16x32_bf16 v[122:125], v[138:141], v[174:177], v[122:125]
	v_mfma_f32_16x16x32_bf16 v[110:113], v[130:133], v[190:193], v[110:113]
	v_mfma_f32_16x16x32_bf16 v[106:109], v[138:141], v[190:193], v[106:109]
	v_mfma_f32_16x16x32_bf16 v[94:97], v[130:133], v[212:215], v[94:97]
	v_mfma_f32_16x16x32_bf16 v[90:93], v[138:141], v[212:215], v[90:93]
	v_mfma_f32_16x16x32_bf16 v[78:81], v[130:133], v[220:223], v[78:81]
	v_mfma_f32_16x16x32_bf16 v[74:77], v[138:141], v[220:223], v[74:77]
	v_mfma_f32_16x16x32_bf16 v[126:129], v[134:137], v[182:185], v[126:129]
	v_mfma_f32_16x16x32_bf16 v[122:125], v[142:145], v[182:185], v[122:125]
	v_mfma_f32_16x16x32_bf16 v[110:113], v[134:137], v[194:197], v[110:113]
	v_mfma_f32_16x16x32_bf16 v[106:109], v[142:145], v[194:197], v[106:109]
	v_mfma_f32_16x16x32_bf16 v[94:97], v[134:137], v[216:219], v[94:97]
	v_mfma_f32_16x16x32_bf16 v[90:93], v[142:145], v[216:219], v[90:93]
	v_mfma_f32_16x16x32_bf16 v[78:81], v[134:137], v[224:227], v[78:81]
	v_mfma_f32_16x16x32_bf16 v[74:77], v[142:145], v[224:227], v[74:77]
	s_nop 0
	s_nop 0
	v_mfma_f32_16x16x32_bf16 v[118:121], v[146:149], v[174:177], v[118:121]
	v_mfma_f32_16x16x32_bf16 v[114:117], v[154:157], v[174:177], v[114:117]
	v_mfma_f32_16x16x32_bf16 v[102:105], v[146:149], v[190:193], v[102:105]
	v_mfma_f32_16x16x32_bf16 v[98:101], v[154:157], v[190:193], v[98:101]
	v_mfma_f32_16x16x32_bf16 v[86:89], v[146:149], v[212:215], v[86:89]
	v_mfma_f32_16x16x32_bf16 v[82:85], v[154:157], v[212:215], v[82:85]
	v_mfma_f32_16x16x32_bf16 v[70:73], v[146:149], v[220:223], v[70:73]
	v_mfma_f32_16x16x32_bf16 v[66:69], v[154:157], v[220:223], v[66:69]
	v_mfma_f32_16x16x32_bf16 v[118:121], v[150:153], v[182:185], v[118:121]
	v_mfma_f32_16x16x32_bf16 v[114:117], v[158:161], v[182:185], v[114:117]
	v_mfma_f32_16x16x32_bf16 v[102:105], v[150:153], v[194:197], v[102:105]
	v_mfma_f32_16x16x32_bf16 v[98:101], v[158:161], v[194:197], v[98:101]
	v_mfma_f32_16x16x32_bf16 v[86:89], v[150:153], v[216:219], v[86:89]
	v_mfma_f32_16x16x32_bf16 v[82:85], v[158:161], v[216:219], v[82:85]
	v_mfma_f32_16x16x32_bf16 v[70:73], v[150:153], v[224:227], v[70:73]
	v_mfma_f32_16x16x32_bf16 v[66:69], v[158:161], v[224:227], v[66:69]
	s_nop 0
	s_barrier
; #define PG8_STAGE(bufoff, gbase, voff) do { _Pragma("unroll") for (int _i = 0; _i < 2; ++_i) \
;         __builtin_amdgcn_global_load_lds((const unsigned*)((const char*)(gbase) + (voff)[_i]), (LAS unsigned*)(lds + (bufoff) + ldsw + _i * 8192), 16, 0, 0); } while (0)
; #define PG8_LDA(dst, b, h) do { _Pragma("unroll") for (int m = 0; m < 4; ++m) _Pragma("unroll") for (int k = 0; k < 2; ++k) dst[m][k] = *(const LAS bf16x8*)(lds + PG8_SA(b, h) + aoff + m * 2048 + k * 1024); } while (0)
; #define PG8_MMA(ai, bj, At, Bt) do { __builtin_amdgcn_s_setprio(1); _Pragma("unroll") for (int m = 0; m < 4; ++m) _Pragma("unroll") for (int n = 0; n < 2; ++n) _Pragma("unroll") for (int k = 0; k < 2; ++k) \
;         acc[ai][bj][m][n] = __builtin_amdgcn_mfma_f32_16x16x32_bf16(Bt[n][k], At[m][k], acc[ai][bj][m][n], 0, 0, 0); __builtin_amdgcn_s_setprio(0); } while (0)
; #define PG8_WAIT_V(n) asm volatile("s_waitcnt vmcnt(" #n ")" ::: "memory")
; #define PG8_WAIT_L(n) asm volatile("s_waitcnt lgkmcnt(" #n ")" ::: "memory")
; #define PG8_BAR __builtin_amdgcn_s_barrier()
; #define PG8_SCHED __builtin_amdgcn_sched_barrier(0)
; template <class Epi, class Sched>
; DI void gemm_phase(LAS unsigned char* lds, const int K, const Sched& S, const Epi& E) {
;     ...
;             PG8_LDA(At, 1, 1); PG8_STAGE(PG8_SB(1, 0), b3, voffB); PG8_STAGE(PG8_SB(1, 1), b3 + hstep, voffB); PG8_STAGE(PG8_SA(1, 0), a3, voffA);
;             PG8_WAIT_V(8); PG8_WAIT_L(0); PG8_BAR; PG8_MMA(1, 0, At, B0); PG8_MMA(1, 1, At, B1); PG8_BAR; PG8_SCHED;
;         }
;         if (wr == 0) PG8_BAR;
	s_add_i32 s63, s63, s55
	v_lshl_add_u64 v[198:199], v[198:199], 0, s[90:91]
	s_mov_b32 m0, s63
	ds_read_b128 v[174:177], v202 offset:49152
	ds_read_b128 v[182:185], v202 offset:50176
	ds_read_b128 v[190:193], v202 offset:51200
	ds_read_b128 v[194:197], v202 offset:52224
	ds_read_b128 v[212:215], v202 offset:53248
	ds_read_b128 v[216:219], v202 offset:54272
	ds_read_b128 v[220:223], v202 offset:55296
	ds_read_b128 v[224:227], v202 offset:56320
	global_load_lds_dwordx4 v[198:199], off
	s_add_i32 m0, s63, 0x2000
	s_add_u32 s80, s80, 0x40080
	v_lshl_add_u64 v[198:199], v[204:205], 0, s[90:91]
	s_addc_u32 s81, s81, 0
	s_add_i32 s63, vcc_lo, s55
	global_load_lds_dwordx4 v[198:199], off
	v_lshl_add_u64 v[198:199], s[80:81], 0, v[164:165]
	s_mov_b32 m0, s63
	s_nop 0
	global_load_lds_dwordx4 v[198:199], off
	v_lshl_add_u64 v[198:199], s[80:81], 0, v[168:169]
	s_add_i32 m0, s63, 0x2000
	s_nop 0
	global_load_lds_dwordx4 v[198:199], off
	v_lshl_add_u64 v[198:199], v[228:229], 0, s[90:91]
	s_mov_b32 m0, s47
	s_nop 0
	global_load_lds_dwordx4 v[198:199], off
	v_lshl_add_u64 v[198:199], v[230:231], 0, s[90:91]
	s_mov_b32 m0, s62
	s_nop 0
	global_load_lds_dwordx4 v[198:199], off
	s_waitcnt vmcnt(8)
	s_waitcnt lgkmcnt(0)
	s_barrier
	s_nop 0
	s_waitcnt lgkmcnt(0)
	v_mfma_f32_16x16x32_bf16 v[62:65], v[130:133], v[174:177], v[62:65]
	v_mfma_f32_16x16x32_bf16 v[58:61], v[138:141], v[174:177], v[58:61]
	v_mfma_f32_16x16x32_bf16 v[46:49], v[130:133], v[190:193], v[46:49]
	v_mfma_f32_16x16x32_bf16 v[42:45], v[138:141], v[190:193], v[42:45]
	v_mfma_f32_16x16x32_bf16 v[30:33], v[130:133], v[212:215], v[30:33]
	v_mfma_f32_16x16x32_bf16 v[26:29], v[138:141], v[212:215], v[26:29]
	v_mfma_f32_16x16x32_bf16 v[14:17], v[130:133], v[220:223], v[14:17]
	v_mfma_f32_16x16x32_bf16 v[10:13], v[138:141], v[220:223], v[10:13]
	v_mfma_f32_16x16x32_bf16 v[62:65], v[134:137], v[182:185], v[62:65]
	v_mfma_f32_16x16x32_bf16 v[58:61], v[142:145], v[182:185], v[58:61]
	v_mfma_f32_16x16x32_bf16 v[46:49], v[134:137], v[194:197], v[46:49]
	v_mfma_f32_16x16x32_bf16 v[42:45], v[142:145], v[194:197], v[42:45]
	v_mfma_f32_16x16x32_bf16 v[30:33], v[134:137], v[216:219], v[30:33]
	v_mfma_f32_16x16x32_bf16 v[26:29], v[142:145], v[216:219], v[26:29]
	v_mfma_f32_16x16x32_bf16 v[14:17], v[134:137], v[224:227], v[14:17]
	v_mfma_f32_16x16x32_bf16 v[10:13], v[142:145], v[224:227], v[10:13]
	s_nop 0
	s_nop 0
	v_mfma_f32_16x16x32_bf16 v[54:57], v[146:149], v[174:177], v[54:57]
	v_mfma_f32_16x16x32_bf16 v[50:53], v[154:157], v[174:177], v[50:53]
	v_mfma_f32_16x16x32_bf16 v[38:41], v[146:149], v[190:193], v[38:41]
	v_mfma_f32_16x16x32_bf16 v[34:37], v[154:157], v[190:193], v[34:37]
	v_mfma_f32_16x16x32_bf16 v[22:25], v[146:149], v[212:215], v[22:25]
	v_mfma_f32_16x16x32_bf16 v[18:21], v[154:157], v[212:215], v[18:21]
	v_mfma_f32_16x16x32_bf16 v[6:9], v[146:149], v[220:223], v[6:9]
	v_mfma_f32_16x16x32_bf16 v[2:5], v[154:157], v[220:223], v[2:5]
	v_mfma_f32_16x16x32_bf16 v[54:57], v[150:153], v[182:185], v[54:57]
	v_mfma_f32_16x16x32_bf16 v[50:53], v[158:161], v[182:185], v[50:53]
	v_mfma_f32_16x16x32_bf16 v[38:41], v[150:153], v[194:197], v[38:41]
	v_mfma_f32_16x16x32_bf16 v[34:37], v[158:161], v[194:197], v[34:37]
	v_mfma_f32_16x16x32_bf16 v[22:25], v[150:153], v[216:219], v[22:25]
	v_mfma_f32_16x16x32_bf16 v[18:21], v[158:161], v[216:219], v[18:21]
	v_mfma_f32_16x16x32_bf16 v[6:9], v[150:153], v[224:227], v[6:9]
	v_mfma_f32_16x16x32_bf16 v[2:5], v[158:161], v[224:227], v[2:5]
	s_nop 0
	s_barrier
	s_add_i32 s87, s87, 2
	s_add_u32 s85, s85, 0x100
	s_addc_u32 s86, s86, 0
	s_add_u32 s78, s78, 0x100
	s_addc_u32 s79, s79, 0
	s_cmp_gt_u32 s87, 13
	s_cbranch_scc0 .LBB0_218
	s_and_b64 vcc, exec, s[50:51]
	s_cbranch_vccz .LBB0_221
	s_barrier

; #define PG8_STAGE(bufoff, gbase, voff) do { _Pragma("unroll") for (int _i = 0; _i < 2; ++_i) \
;         __builtin_amdgcn_global_load_lds((const unsigned*)((const char*)(gbase) + (voff)[_i]), (LAS unsigned*)(lds + (bufoff) + ldsw + _i * 8192), 16, 0, 0); } while (0)
; #define PG8_LDA(dst, b, h) do { _Pragma("unroll") for (int m = 0; m < 4; ++m) _Pragma("unroll") for (int k = 0; k < 2; ++k) dst[m][k] = *(const LAS bf16x8*)(lds + PG8_SA(b, h) + aoff + m * 2048 + k * 1024); } while (0)
; #define PG8_LDB(dst, b, h) do { _Pragma("unroll") for (int n = 0; n < 2; ++n) _Pragma("unroll") for (int k = 0; k < 2; ++k) dst[n][k] = *(const LAS bf16x8*)(lds + PG8_SB(b, h) + boff + n * 2048 + k * 1024); } while (0)
; #define PG8_MMA(ai, bj, At, Bt) do { __builtin_amdgcn_s_setprio(1); _Pragma("unroll") for (int m = 0; m < 4; ++m) _Pragma("unroll") for (int n = 0; n < 2; ++n) _Pragma("unroll") for (int k = 0; k < 2; ++k) \
;         acc[ai][bj][m][n] = __builtin_amdgcn_mfma_f32_16x16x32_bf16(Bt[n][k], At[m][k], acc[ai][bj][m][n], 0, 0, 0); __builtin_amdgcn_s_setprio(0); } while (0)
; #define PG8_WAIT_V(n) asm volatile("s_waitcnt vmcnt(" #n ")" ::: "memory")
; #define PG8_WAIT_L(n) asm volatile("s_waitcnt lgkmcnt(" #n ")" ::: "memory")
; #define PG8_BAR __builtin_amdgcn_s_barrier()
; #define PG8_SCHED __builtin_amdgcn_sched_barrier(0)
; template <class Epi, class Sched>
; DI void gemm_phase(LAS unsigned char* lds, const int K, const Sched& S, const Epi& E) {
;     ...
;         for (int t = 0; t < nt; t += 2) {
;             const bool last = (t == nt - 2);
;             const char* a1 = cA + (size_t)(t + 1) * kstep;
;             const char* a2 = last ? nA : cA + (size_t)(t + 2) * kstep; const char* b2 = last ? nB : cB + (size_t)(t + 2) * kstep;
;             const char* a3 = a2 + kstep; const char* b3 = b2 + kstep;
;             PG8_LDB(B0, 0, 0); PG8_LDB(B1, 0, 1); PG8_SCHED; PG8_LDA(At, 0, 0); PG8_STAGE(PG8_SA(1, 1), a1 + hstep, voffA);
;             PG8_WAIT_V(8); PG8_WAIT_L(0); PG8_BAR; PG8_MMA(0, 0, At, B0); PG8_MMA(0, 1, At, B1); PG8_BAR; PG8_SCHED;
;             PG8_LDA(At, 0, 1); PG8_STAGE(PG8_SB(0, 0), b2, voffB); PG8_STAGE(PG8_SB(0, 1), b2 + hstep, voffB); PG8_STAGE(PG8_SA(0, 0), a2, voffA);
;             PG8_WAIT_V(8); PG8_WAIT_L(0); PG8_BAR; PG8_MMA(1, 0, At, B0); PG8_MMA(1, 1, At, B1); PG8_BAR; PG8_SCHED;
.LBB0_338:
	s_add_u32 s58, s56, 0xfffc0080
	s_addc_u32 s59, s57, -1
	s_add_i32 s79, 0, 0x10000
	s_cmp_eq_u32 s78, 12
	s_cselect_b32 s61, s53, s59
	s_cselect_b32 s60, s52, s58
	v_add_u32_e32 v142, s79, v145
	s_cselect_b32 s59, s55, s51
	s_cselect_b32 s58, s54, s49
	s_add_i32 s82, 0, 0x14000
	ds_read_b128 v[148:151], v142
	ds_read_b128 v[152:155], v142 offset:1024
	ds_read_b128 v[156:159], v142 offset:2048
	ds_read_b128 v[160:163], v142 offset:3072
	v_add_u32_e32 v142, s82, v145
	ds_read_b128 v[164:167], v142
	ds_read_b128 v[168:171], v142 offset:1024
	ds_read_b128 v[172:175], v142 offset:2048
	ds_read_b128 v[182:185], v142 offset:3072
	v_lshl_add_u64 v[142:143], s[56:57], 0, v[140:141]
	s_add_i32 m0, s67, 0xc000
	ds_read_b128 v[190:193], v146
	ds_read_b128 v[194:197], v146 offset:1024
	ds_read_b128 v[198:201], v146 offset:2048
	ds_read_b128 v[202:205], v146 offset:3072
	ds_read_b128 v[212:215], v146 offset:4096
	ds_read_b128 v[216:219], v146 offset:5120
	ds_read_b128 v[220:223], v146 offset:6144
	ds_read_b128 v[224:227], v146 offset:7168
	global_load_lds_dwordx4 v[142:143], off
	v_lshl_add_u64 v[142:143], s[56:57], 0, v[138:139]
	s_add_i32 m0, s67, 0xe000
	s_nop 0
	global_load_lds_dwordx4 v[142:143], off
	s_waitcnt vmcnt(8)
	s_waitcnt lgkmcnt(0)
	s_barrier
	s_nop 0
	s_waitcnt lgkmcnt(0)
	v_mfma_f32_16x16x32_bf16 v[126:129], v[148:151], v[190:193], v[126:129]
	v_mfma_f32_16x16x32_bf16 v[122:125], v[156:159], v[190:193], v[122:125]
	v_mfma_f32_16x16x32_bf16 v[110:113], v[148:151], v[198:201], v[110:113]
	v_mfma_f32_16x16x32_bf16 v[106:109], v[156:159], v[198:201], v[106:109]
	v_mfma_f32_16x16x32_bf16 v[94:97], v[148:151], v[212:215], v[94:97]
	v_mfma_f32_16x16x32_bf16 v[90:93], v[156:159], v[212:215], v[90:93]
	v_mfma_f32_16x16x32_bf16 v[78:81], v[148:151], v[220:223], v[78:81]
	v_mfma_f32_16x16x32_bf16 v[74:77], v[156:159], v[220:223], v[74:77]
	v_mfma_f32_16x16x32_bf16 v[126:129], v[152:155], v[194:197], v[126:129]
	v_mfma_f32_16x16x32_bf16 v[122:125], v[160:163], v[194:197], v[122:125]
	v_mfma_f32_16x16x32_bf16 v[110:113], v[152:155], v[202:205], v[110:113]
	v_mfma_f32_16x16x32_bf16 v[106:109], v[160:163], v[202:205], v[106:109]
	v_mfma_f32_16x16x32_bf16 v[94:97], v[152:155], v[216:219], v[94:97]
	v_mfma_f32_16x16x32_bf16 v[90:93], v[160:163], v[216:219], v[90:93]
	v_mfma_f32_16x16x32_bf16 v[78:81], v[152:155], v[224:227], v[78:81]
	v_mfma_f32_16x16x32_bf16 v[74:77], v[160:163], v[224:227], v[74:77]
	s_nop 0
	s_nop 0
	v_mfma_f32_16x16x32_bf16 v[118:121], v[164:167], v[190:193], v[118:121]
	v_mfma_f32_16x16x32_bf16 v[114:117], v[172:175], v[190:193], v[114:117]
	v_mfma_f32_16x16x32_bf16 v[102:105], v[164:167], v[198:201], v[102:105]
	v_mfma_f32_16x16x32_bf16 v[98:101], v[172:175], v[198:201], v[98:101]
	v_mfma_f32_16x16x32_bf16 v[86:89], v[164:167], v[212:215], v[86:89]
	v_mfma_f32_16x16x32_bf16 v[82:85], v[172:175], v[212:215], v[82:85]
	v_mfma_f32_16x16x32_bf16 v[70:73], v[164:167], v[220:223], v[70:73]
	v_mfma_f32_16x16x32_bf16 v[66:69], v[172:175], v[220:223], v[66:69]
	v_mfma_f32_16x16x32_bf16 v[118:121], v[168:171], v[194:197], v[118:121]
	v_mfma_f32_16x16x32_bf16 v[114:117], v[182:185], v[194:197], v[114:117]
	v_mfma_f32_16x16x32_bf16 v[102:105], v[168:171], v[202:205], v[102:105]
	v_mfma_f32_16x16x32_bf16 v[98:101], v[182:185], v[202:205], v[98:101]
	v_mfma_f32_16x16x32_bf16 v[86:89], v[168:171], v[216:219], v[86:89]
	v_mfma_f32_16x16x32_bf16 v[82:85], v[182:185], v[216:219], v[82:85]
	v_mfma_f32_16x16x32_bf16 v[70:73], v[168:171], v[224:227], v[70:73]
	v_mfma_f32_16x16x32_bf16 v[66:69], v[182:185], v[224:227], v[66:69]
	s_nop 0
	s_barrier
	s_add_i32 s79, s79, s66
	v_lshl_add_u64 v[142:143], s[58:59], 0, v[134:135]
	s_mov_b32 m0, s79
	ds_read_b128 v[190:193], v146 offset:16384
	ds_read_b128 v[194:197], v146 offset:17408
	ds_read_b128 v[198:201], v146 offset:18432
	ds_read_b128 v[202:205], v146 offset:19456
	ds_read_b128 v[212:215], v146 offset:20480
	ds_read_b128 v[216:219], v146 offset:21504
	ds_read_b128 v[220:223], v146 offset:22528
	ds_read_b128 v[224:227], v146 offset:23552
	global_load_lds_dwordx4 v[142:143], off
	s_add_i32 m0, s79, 0x2000
	s_add_u32 s80, s58, 0x40000
	v_lshl_add_u64 v[176:177], s[58:59], 0, v[130:131]
	s_addc_u32 s81, s59, 0
	s_add_i32 s79, s82, s66
	global_load_lds_dwordx4 v[176:177], off
	v_lshl_add_u64 v[228:229], s[80:81], 0, v[134:135]
	s_mov_b32 m0, s79
	v_lshl_add_u64 v[230:231], s[60:61], 0, v[132:133]
	global_load_lds_dwordx4 v[228:229], off
	v_lshl_add_u64 v[228:229], s[80:81], 0, v[130:131]
	s_add_i32 m0, s79, 0x2000
	s_nop 0
	global_load_lds_dwordx4 v[228:229], off
	v_lshl_add_u64 v[228:229], s[60:61], 0, v[136:137]
	s_mov_b32 m0, s67
	s_nop 0
	global_load_lds_dwordx4 v[228:229], off
	s_mov_b32 m0, s68
	s_nop 0
	global_load_lds_dwordx4 v[230:231], off
	s_waitcnt vmcnt(8)
	s_waitcnt lgkmcnt(0)
	s_barrier
; #define PG8_STAGE(bufoff, gbase, voff) do { _Pragma("unroll") for (int _i = 0; _i < 2; ++_i) \
;         __builtin_amdgcn_global_load_lds((const unsigned*)((const char*)(gbase) + (voff)[_i]), (LAS unsigned*)(lds + (bufoff) + ldsw + _i * 8192), 16, 0, 0); } while (0)
; #define PG8_LDA(dst, b, h) do { _Pragma("unroll") for (int m = 0; m < 4; ++m) _Pragma("unroll") for (int k = 0; k < 2; ++k) dst[m][k] = *(const LAS bf16x8*)(lds + PG8_SA(b, h) + aoff + m * 2048 + k * 1024); } while (0)
; #define PG8_LDB(dst, b, h) do { _Pragma("unroll") for (int n = 0; n < 2; ++n) _Pragma("unroll") for (int k = 0; k < 2; ++k) dst[n][k] = *(const LAS bf16x8*)(lds + PG8_SB(b, h) + boff + n * 2048 + k * 1024); } while (0)
; #define PG8_MMA(ai, bj, At, Bt) do { __builtin_amdgcn_s_setprio(1); _Pragma("unroll") for (int m = 0; m < 4; ++m) _Pragma("unroll") for (int n = 0; n < 2; ++n) _Pragma("unroll") for (int k = 0; k < 2; ++k) \
;         acc[ai][bj][m][n] = __builtin_amdgcn_mfma_f32_16x16x32_bf16(Bt[n][k], At[m][k], acc[ai][bj][m][n], 0, 0, 0); __builtin_amdgcn_s_setprio(0); } while (0)
; #define PG8_WAIT_V(n) asm volatile("s_waitcnt vmcnt(" #n ")" ::: "memory")
; #define PG8_WAIT_L(n) asm volatile("s_waitcnt lgkmcnt(" #n ")" ::: "memory")
; #define PG8_BAR __builtin_amdgcn_s_barrier()
; #define PG8_SCHED __builtin_amdgcn_sched_barrier(0)
; template <class Epi, class Sched>
; DI void gemm_phase(LAS unsigned char* lds, const int K, const Sched& S, const Epi& E) {
;     ...
;             PG8_WAIT_V(8); PG8_WAIT_L(0); PG8_BAR; PG8_MMA(1, 0, At, B0); PG8_MMA(1, 1, At, B1); PG8_BAR; PG8_SCHED;
;             PG8_LDB(B0, 1, 0); PG8_LDB(B1, 1, 1); PG8_SCHED; PG8_LDA(At, 1, 0); PG8_STAGE(PG8_SA(0, 1), a2 + hstep, voffA);
;             PG8_WAIT_V(8); PG8_WAIT_L(0); PG8_BAR; PG8_MMA(0, 0, At, B0); PG8_MMA(0, 1, At, B1); PG8_BAR; PG8_SCHED;
	s_nop 0
	s_waitcnt lgkmcnt(0)
	v_mfma_f32_16x16x32_bf16 v[62:65], v[148:151], v[190:193], v[62:65]
	v_mfma_f32_16x16x32_bf16 v[58:61], v[156:159], v[190:193], v[58:61]
	v_mfma_f32_16x16x32_bf16 v[46:49], v[148:151], v[198:201], v[46:49]
	v_mfma_f32_16x16x32_bf16 v[42:45], v[156:159], v[198:201], v[42:45]
	v_mfma_f32_16x16x32_bf16 v[30:33], v[148:151], v[212:215], v[30:33]
	v_mfma_f32_16x16x32_bf16 v[26:29], v[156:159], v[212:215], v[26:29]
	v_mfma_f32_16x16x32_bf16 v[14:17], v[148:151], v[220:223], v[14:17]
	v_mfma_f32_16x16x32_bf16 v[10:13], v[156:159], v[220:223], v[10:13]
	v_mfma_f32_16x16x32_bf16 v[62:65], v[152:155], v[194:197], v[62:65]
	v_mfma_f32_16x16x32_bf16 v[58:61], v[160:163], v[194:197], v[58:61]
	v_mfma_f32_16x16x32_bf16 v[46:49], v[152:155], v[202:205], v[46:49]
	v_mfma_f32_16x16x32_bf16 v[42:45], v[160:163], v[202:205], v[42:45]
	v_mfma_f32_16x16x32_bf16 v[30:33], v[152:155], v[216:219], v[30:33]
	v_mfma_f32_16x16x32_bf16 v[26:29], v[160:163], v[216:219], v[26:29]
	v_mfma_f32_16x16x32_bf16 v[14:17], v[152:155], v[224:227], v[14:17]
	v_mfma_f32_16x16x32_bf16 v[10:13], v[160:163], v[224:227], v[10:13]
	s_nop 0
	s_nop 0
	v_mfma_f32_16x16x32_bf16 v[54:57], v[164:167], v[190:193], v[54:57]
	v_mfma_f32_16x16x32_bf16 v[50:53], v[172:175], v[190:193], v[50:53]
	v_mfma_f32_16x16x32_bf16 v[38:41], v[164:167], v[198:201], v[38:41]
	v_mfma_f32_16x16x32_bf16 v[34:37], v[172:175], v[198:201], v[34:37]
	v_mfma_f32_16x16x32_bf16 v[22:25], v[164:167], v[212:215], v[22:25]
	v_mfma_f32_16x16x32_bf16 v[18:21], v[172:175], v[212:215], v[18:21]
	v_mfma_f32_16x16x32_bf16 v[6:9], v[164:167], v[220:223], v[6:9]
	v_mfma_f32_16x16x32_bf16 v[2:5], v[172:175], v[220:223], v[2:5]
	v_mfma_f32_16x16x32_bf16 v[54:57], v[168:171], v[194:197], v[54:57]
	v_mfma_f32_16x16x32_bf16 v[50:53], v[182:185], v[194:197], v[50:53]
	v_mfma_f32_16x16x32_bf16 v[38:41], v[168:171], v[202:205], v[38:41]
	v_mfma_f32_16x16x32_bf16 v[34:37], v[182:185], v[202:205], v[34:37]
	v_mfma_f32_16x16x32_bf16 v[22:25], v[168:171], v[216:219], v[22:25]
	v_mfma_f32_16x16x32_bf16 v[18:21], v[182:185], v[216:219], v[18:21]
	v_mfma_f32_16x16x32_bf16 v[6:9], v[168:171], v[224:227], v[6:9]
	v_mfma_f32_16x16x32_bf16 v[2:5], v[182:185], v[224:227], v[2:5]
	s_nop 0
	s_barrier
	s_add_i32 s79, 0, 0x18000
	v_add_u32_e32 v147, s79, v145
	s_add_i32 s80, 0, 0x1c000
	ds_read_b128 v[148:151], v147
	ds_read_b128 v[152:155], v147 offset:1024
	ds_read_b128 v[156:159], v147 offset:2048
	ds_read_b128 v[160:163], v147 offset:3072
	v_add_u32_e32 v147, s80, v145
	ds_read_b128 v[164:167], v147
	ds_read_b128 v[168:171], v147 offset:1024
	ds_read_b128 v[172:175], v147 offset:2048
	ds_read_b128 v[182:185], v147 offset:3072
	s_add_u32 s60, s60, 0x40000
	s_addc_u32 s61, s61, 0
	s_mov_b32 m0, s69
	v_lshl_add_u64 v[232:233], s[60:61], 0, v[136:137]
	ds_read_b128 v[190:193], v146 offset:32768
	ds_read_b128 v[194:197], v146 offset:33792
	ds_read_b128 v[198:201], v146 offset:34816
	ds_read_b128 v[202:205], v146 offset:35840
	ds_read_b128 v[212:215], v146 offset:36864
	ds_read_b128 v[216:219], v146 offset:37888
	ds_read_b128 v[220:223], v146 offset:38912
	ds_read_b128 v[224:227], v146 offset:39936
	global_load_lds_dwordx4 v[232:233], off
	v_lshl_add_u64 v[232:233], s[60:61], 0, v[132:133]
	s_mov_b32 m0, s70
	s_nop 0
	global_load_lds_dwordx4 v[232:233], off
	s_waitcnt vmcnt(8)
	s_waitcnt lgkmcnt(0)
	s_barrier
	s_nop 0
	s_waitcnt lgkmcnt(0)
	v_mfma_f32_16x16x32_bf16 v[126:129], v[148:151], v[190:193], v[126:129]
	v_mfma_f32_16x16x32_bf16 v[122:125], v[156:159], v[190:193], v[122:125]
	v_mfma_f32_16x16x32_bf16 v[110:113], v[148:151], v[198:201], v[110:113]
	v_mfma_f32_16x16x32_bf16 v[106:109], v[156:159], v[198:201], v[106:109]
	v_mfma_f32_16x16x32_bf16 v[94:97], v[148:151], v[212:215], v[94:97]
	v_mfma_f32_16x16x32_bf16 v[90:93], v[156:159], v[212:215], v[90:93]
	v_mfma_f32_16x16x32_bf16 v[78:81], v[148:151], v[220:223], v[78:81]
	v_mfma_f32_16x16x32_bf16 v[74:77], v[156:159], v[220:223], v[74:77]
	v_mfma_f32_16x16x32_bf16 v[126:129], v[152:155], v[194:197], v[126:129]
	v_mfma_f32_16x16x32_bf16 v[122:125], v[160:163], v[194:197], v[122:125]
	v_mfma_f32_16x16x32_bf16 v[110:113], v[152:155], v[202:205], v[110:113]
	v_mfma_f32_16x16x32_bf16 v[106:109], v[160:163], v[202:205], v[106:109]
	v_mfma_f32_16x16x32_bf16 v[94:97], v[152:155], v[216:219], v[94:97]
	v_mfma_f32_16x16x32_bf16 v[90:93], v[160:163], v[216:219], v[90:93]
	v_mfma_f32_16x16x32_bf16 v[78:81], v[152:155], v[224:227], v[78:81]
	v_mfma_f32_16x16x32_bf16 v[74:77], v[160:163], v[224:227], v[74:77]
	s_nop 0
	s_nop 0
	v_mfma_f32_16x16x32_bf16 v[118:121], v[164:167], v[190:193], v[118:121]
	v_mfma_f32_16x16x32_bf16 v[114:117], v[172:175], v[190:193], v[114:117]
	v_mfma_f32_16x16x32_bf16 v[102:105], v[164:167], v[198:201], v[102:105]
	v_mfma_f32_16x16x32_bf16 v[98:101], v[172:175], v[198:201], v[98:101]
	v_mfma_f32_16x16x32_bf16 v[86:89], v[164:167], v[212:215], v[86:89]
	v_mfma_f32_16x16x32_bf16 v[82:85], v[172:175], v[212:215], v[82:85]
	v_mfma_f32_16x16x32_bf16 v[70:73], v[164:167], v[220:223], v[70:73]
	v_mfma_f32_16x16x32_bf16 v[66:69], v[172:175], v[220:223], v[66:69]
	v_mfma_f32_16x16x32_bf16 v[118:121], v[168:171], v[194:197], v[118:121]
	v_mfma_f32_16x16x32_bf16 v[114:117], v[182:185], v[194:197], v[114:117]
	v_mfma_f32_16x16x32_bf16 v[102:105], v[168:171], v[202:205], v[102:105]
	v_mfma_f32_16x16x32_bf16 v[98:101], v[182:185], v[202:205], v[98:101]
	v_mfma_f32_16x16x32_bf16 v[86:89], v[168:171], v[216:219], v[86:89]
	v_mfma_f32_16x16x32_bf16 v[82:85], v[182:185], v[216:219], v[82:85]
	v_mfma_f32_16x16x32_bf16 v[70:73], v[168:171], v[224:227], v[70:73]
	v_mfma_f32_16x16x32_bf16 v[66:69], v[182:185], v[224:227], v[66:69]
	s_nop 0
	s_barrier
; #define PG8_STAGE(bufoff, gbase, voff) do { _Pragma("unroll") for (int _i = 0; _i < 2; ++_i) \
;         __builtin_amdgcn_global_load_lds((const unsigned*)((const char*)(gbase) + (voff)[_i]), (LAS unsigned*)(lds + (bufoff) + ldsw + _i * 8192), 16, 0, 0); } while (0)
; #define PG8_LDA(dst, b, h) do { _Pragma("unroll") for (int m = 0; m < 4; ++m) _Pragma("unroll") for (int k = 0; k < 2; ++k) dst[m][k] = *(const LAS bf16x8*)(lds + PG8_SA(b, h) + aoff + m * 2048 + k * 1024); } while (0)
; #define PG8_MMA(ai, bj, At, Bt) do { __builtin_amdgcn_s_setprio(1); _Pragma("unroll") for (int m = 0; m < 4; ++m) _Pragma("unroll") for (int n = 0; n < 2; ++n) _Pragma("unroll") for (int k = 0; k < 2; ++k) \
;         acc[ai][bj][m][n] = __builtin_amdgcn_mfma_f32_16x16x32_bf16(Bt[n][k], At[m][k], acc[ai][bj][m][n], 0, 0, 0); __builtin_amdgcn_s_setprio(0); } while (0)
; #define PG8_WAIT_V(n) asm volatile("s_waitcnt vmcnt(" #n ")" ::: "memory")
; #define PG8_WAIT_L(n) asm volatile("s_waitcnt lgkmcnt(" #n ")" ::: "memory")
; #define PG8_BAR __builtin_amdgcn_s_barrier()
; #define PG8_SCHED __builtin_amdgcn_sched_barrier(0)
; template <class Epi, class Sched>
; DI void gemm_phase(LAS unsigned char* lds, const int K, const Sched& S, const Epi& E) {
;     ...
;             PG8_LDA(At, 1, 1); PG8_STAGE(PG8_SB(1, 0), b3, voffB); PG8_STAGE(PG8_SB(1, 1), b3 + hstep, voffB); PG8_STAGE(PG8_SA(1, 0), a3, voffA);
;             PG8_WAIT_V(8); PG8_WAIT_L(0); PG8_BAR; PG8_MMA(1, 0, At, B0); PG8_MMA(1, 1, At, B1); PG8_BAR; PG8_SCHED;
;         }
;         if (wr == 0) PG8_BAR;
	s_add_i32 s60, s79, s66
	v_lshl_add_u64 v[142:143], v[142:143], 0, s[90:91]
	s_mov_b32 m0, s60
	ds_read_b128 v[190:193], v146 offset:49152
	ds_read_b128 v[194:197], v146 offset:50176
	ds_read_b128 v[198:201], v146 offset:51200
	ds_read_b128 v[202:205], v146 offset:52224
	ds_read_b128 v[212:215], v146 offset:53248
	ds_read_b128 v[216:219], v146 offset:54272
	ds_read_b128 v[220:223], v146 offset:55296
	ds_read_b128 v[224:227], v146 offset:56320
	global_load_lds_dwordx4 v[142:143], off
	s_add_i32 m0, s60, 0x2000
	s_add_u32 s58, s58, 0x40080
	v_lshl_add_u64 v[142:143], v[176:177], 0, s[90:91]
	s_addc_u32 s59, s59, 0
	s_add_i32 s60, s80, s66
	global_load_lds_dwordx4 v[142:143], off
	v_lshl_add_u64 v[142:143], s[58:59], 0, v[134:135]
	s_mov_b32 m0, s60
	s_nop 0
	global_load_lds_dwordx4 v[142:143], off
	v_lshl_add_u64 v[142:143], s[58:59], 0, v[130:131]
	s_add_i32 m0, s60, 0x2000
	s_nop 0
	global_load_lds_dwordx4 v[142:143], off
	v_lshl_add_u64 v[142:143], v[228:229], 0, s[90:91]
	s_mov_b32 m0, s73
	s_nop 0
	global_load_lds_dwordx4 v[142:143], off
	v_lshl_add_u64 v[142:143], v[230:231], 0, s[90:91]
	s_mov_b32 m0, s74
	s_nop 0
	global_load_lds_dwordx4 v[142:143], off
	s_waitcnt vmcnt(8)
	s_waitcnt lgkmcnt(0)
	s_barrier
	s_nop 0
	s_waitcnt lgkmcnt(0)
	v_mfma_f32_16x16x32_bf16 v[62:65], v[148:151], v[190:193], v[62:65]
	v_mfma_f32_16x16x32_bf16 v[58:61], v[156:159], v[190:193], v[58:61]
	v_mfma_f32_16x16x32_bf16 v[46:49], v[148:151], v[198:201], v[46:49]
	v_mfma_f32_16x16x32_bf16 v[42:45], v[156:159], v[198:201], v[42:45]
	v_mfma_f32_16x16x32_bf16 v[30:33], v[148:151], v[212:215], v[30:33]
	v_mfma_f32_16x16x32_bf16 v[26:29], v[156:159], v[212:215], v[26:29]
	v_mfma_f32_16x16x32_bf16 v[14:17], v[148:151], v[220:223], v[14:17]
	v_mfma_f32_16x16x32_bf16 v[10:13], v[156:159], v[220:223], v[10:13]
	v_mfma_f32_16x16x32_bf16 v[62:65], v[152:155], v[194:197], v[62:65]
	v_mfma_f32_16x16x32_bf16 v[58:61], v[160:163], v[194:197], v[58:61]
	v_mfma_f32_16x16x32_bf16 v[46:49], v[152:155], v[202:205], v[46:49]
	v_mfma_f32_16x16x32_bf16 v[42:45], v[160:163], v[202:205], v[42:45]
	v_mfma_f32_16x16x32_bf16 v[30:33], v[152:155], v[216:219], v[30:33]
	v_mfma_f32_16x16x32_bf16 v[26:29], v[160:163], v[216:219], v[26:29]
	v_mfma_f32_16x16x32_bf16 v[14:17], v[152:155], v[224:227], v[14:17]
	v_mfma_f32_16x16x32_bf16 v[10:13], v[160:163], v[224:227], v[10:13]
	s_nop 0
	s_nop 0
	v_mfma_f32_16x16x32_bf16 v[54:57], v[164:167], v[190:193], v[54:57]
	v_mfma_f32_16x16x32_bf16 v[50:53], v[172:175], v[190:193], v[50:53]
	v_mfma_f32_16x16x32_bf16 v[38:41], v[164:167], v[198:201], v[38:41]
	v_mfma_f32_16x16x32_bf16 v[34:37], v[172:175], v[198:201], v[34:37]
	v_mfma_f32_16x16x32_bf16 v[22:25], v[164:167], v[212:215], v[22:25]
	v_mfma_f32_16x16x32_bf16 v[18:21], v[172:175], v[212:215], v[18:21]
	v_mfma_f32_16x16x32_bf16 v[6:9], v[164:167], v[220:223], v[6:9]
	v_mfma_f32_16x16x32_bf16 v[2:5], v[172:175], v[220:223], v[2:5]
	v_mfma_f32_16x16x32_bf16 v[54:57], v[168:171], v[194:197], v[54:57]
	v_mfma_f32_16x16x32_bf16 v[50:53], v[182:185], v[194:197], v[50:53]
	v_mfma_f32_16x16x32_bf16 v[38:41], v[168:171], v[202:205], v[38:41]
	v_mfma_f32_16x16x32_bf16 v[34:37], v[182:185], v[202:205], v[34:37]
	v_mfma_f32_16x16x32_bf16 v[22:25], v[168:171], v[216:219], v[22:25]
	v_mfma_f32_16x16x32_bf16 v[18:21], v[182:185], v[216:219], v[18:21]
	v_mfma_f32_16x16x32_bf16 v[6:9], v[168:171], v[224:227], v[6:9]
	v_mfma_f32_16x16x32_bf16 v[2:5], v[182:185], v[224:227], v[2:5]
	s_nop 0
	s_barrier
	s_add_i32 s78, s78, 2
	s_add_u32 s49, s49, 0x100
	s_addc_u32 s51, s51, 0
	s_add_u32 s56, s56, 0x100
	s_addc_u32 s57, s57, 0
	s_cmp_gt_u32 s78, 13
	s_cbranch_scc0 .LBB0_338
	s_and_b64 vcc, exec, s[44:45]
	s_cbranch_vccz .LBB0_341
	s_barrier

; #define PG8_STAGE(bufoff, gbase, voff) do { _Pragma("unroll") for (int _i = 0; _i < 2; ++_i) \
;         __builtin_amdgcn_global_load_lds((const unsigned*)((const char*)(gbase) + (voff)[_i]), (LAS unsigned*)(lds + (bufoff) + ldsw + _i * 8192), 16, 0, 0); } while (0)
; #define PG8_LDA(dst, b, h) do { _Pragma("unroll") for (int m = 0; m < 4; ++m) _Pragma("unroll") for (int k = 0; k < 2; ++k) dst[m][k] = *(const LAS bf16x8*)(lds + PG8_SA(b, h) + aoff + m * 2048 + k * 1024); } while (0)
; #define PG8_LDB(dst, b, h) do { _Pragma("unroll") for (int n = 0; n < 2; ++n) _Pragma("unroll") for (int k = 0; k < 2; ++k) dst[n][k] = *(const LAS bf16x8*)(lds + PG8_SB(b, h) + boff + n * 2048 + k * 1024); } while (0)
; #define PG8_MMA(ai, bj, At, Bt) do { __builtin_amdgcn_s_setprio(1); _Pragma("unroll") for (int m = 0; m < 4; ++m) _Pragma("unroll") for (int n = 0; n < 2; ++n) _Pragma("unroll") for (int k = 0; k < 2; ++k) \
;         acc[ai][bj][m][n] = __builtin_amdgcn_mfma_f32_16x16x32_bf16(Bt[n][k], At[m][k], acc[ai][bj][m][n], 0, 0, 0); __builtin_amdgcn_s_setprio(0); } while (0)
; #define PG8_WAIT_V(n) asm volatile("s_waitcnt vmcnt(" #n ")" ::: "memory")
; #define PG8_WAIT_L(n) asm volatile("s_waitcnt lgkmcnt(" #n ")" ::: "memory")
; #define PG8_BAR __builtin_amdgcn_s_barrier()
; #define PG8_SCHED __builtin_amdgcn_sched_barrier(0)
; template <class Epi, class Sched>
; DI void gemm_phase(LAS unsigned char* lds, const int K, const Sched& S, const Epi& E) {
;     ...
;         for (int t = 0; t < nt; t += 2) {
;             const bool last = (t == nt - 2);
;             const char* a1 = cA + (size_t)(t + 1) * kstep;
;             const char* a2 = last ? nA : cA + (size_t)(t + 2) * kstep; const char* b2 = last ? nB : cB + (size_t)(t + 2) * kstep;
;             const char* a3 = a2 + kstep; const char* b3 = b2 + kstep;
;             PG8_LDB(B0, 0, 0); PG8_LDB(B1, 0, 1); PG8_SCHED; PG8_LDA(At, 0, 0); PG8_STAGE(PG8_SA(1, 1), a1 + hstep, voffA);
;             PG8_WAIT_V(8); PG8_WAIT_L(0); PG8_BAR; PG8_MMA(0, 0, At, B0); PG8_MMA(0, 1, At, B1); PG8_BAR; PG8_SCHED;
;             PG8_LDA(At, 0, 1); PG8_STAGE(PG8_SB(0, 0), b2, voffB); PG8_STAGE(PG8_SB(0, 1), b2 + hstep, voffB); PG8_STAGE(PG8_SA(0, 0), a2, voffA);
;             PG8_WAIT_V(8); PG8_WAIT_L(0); PG8_BAR; PG8_MMA(1, 0, At, B0); PG8_MMA(1, 1, At, B1); PG8_BAR; PG8_SCHED;
.LBB0_465:
	s_add_u32 s70, s68, 0xfffc0080
	s_addc_u32 s71, s69, -1
	s_add_i32 vcc_lo, 0, 0x10000
	s_cmp_eq_u32 s79, 12
	s_cselect_b32 s73, s65, s71
	s_cselect_b32 s72, s67, s70
	s_cselect_b32 s71, s74, s78
	s_cselect_b32 s70, s76, s77
	s_add_i32 s42, 0, 0x14000
	v_add_u32_e32 v142, vcc_lo, v203
	v_add_u32_e32 v158, s42, v203
	ds_read_b128 v[130:133], v142
	ds_read_b128 v[134:137], v142 offset:1024
	ds_read_b128 v[138:141], v142 offset:2048
	ds_read_b128 v[142:145], v142 offset:3072
	ds_read_b128 v[146:149], v158
	ds_read_b128 v[150:153], v158 offset:1024
	ds_read_b128 v[154:157], v158 offset:2048
	ds_read_b128 v[158:161], v158 offset:3072
	v_lshl_add_u64 v[224:225], s[68:69], 0, v[172:173]
	s_add_i32 m0, s86, 0xc000
	ds_read_b128 v[174:177], v204
	ds_read_b128 v[182:185], v204 offset:1024
	ds_read_b128 v[190:193], v204 offset:2048
	ds_read_b128 v[194:197], v204 offset:3072
	ds_read_b128 v[198:201], v204 offset:4096
	ds_read_b128 v[212:215], v204 offset:5120
	ds_read_b128 v[216:219], v204 offset:6144
	ds_read_b128 v[220:223], v204 offset:7168
	global_load_lds_dwordx4 v[224:225], off
	v_lshl_add_u64 v[224:225], s[68:69], 0, v[170:171]
	s_add_i32 m0, s86, 0xe000
	s_nop 0
	global_load_lds_dwordx4 v[224:225], off
	s_waitcnt vmcnt(8)
	s_waitcnt lgkmcnt(0)
	s_barrier
	s_nop 0
	s_waitcnt lgkmcnt(0)
	v_mfma_f32_16x16x32_bf16 v[126:129], v[130:133], v[174:177], v[126:129]
	v_mfma_f32_16x16x32_bf16 v[122:125], v[138:141], v[174:177], v[122:125]
	v_mfma_f32_16x16x32_bf16 v[110:113], v[130:133], v[190:193], v[110:113]
	v_mfma_f32_16x16x32_bf16 v[106:109], v[138:141], v[190:193], v[106:109]
	v_mfma_f32_16x16x32_bf16 v[94:97], v[130:133], v[198:201], v[94:97]
	v_mfma_f32_16x16x32_bf16 v[90:93], v[138:141], v[198:201], v[90:93]
	v_mfma_f32_16x16x32_bf16 v[78:81], v[130:133], v[216:219], v[78:81]
	v_mfma_f32_16x16x32_bf16 v[74:77], v[138:141], v[216:219], v[74:77]
	v_mfma_f32_16x16x32_bf16 v[126:129], v[134:137], v[182:185], v[126:129]
	v_mfma_f32_16x16x32_bf16 v[122:125], v[142:145], v[182:185], v[122:125]
	v_mfma_f32_16x16x32_bf16 v[110:113], v[134:137], v[194:197], v[110:113]
	v_mfma_f32_16x16x32_bf16 v[106:109], v[142:145], v[194:197], v[106:109]
	v_mfma_f32_16x16x32_bf16 v[94:97], v[134:137], v[212:215], v[94:97]
	v_mfma_f32_16x16x32_bf16 v[90:93], v[142:145], v[212:215], v[90:93]
	v_mfma_f32_16x16x32_bf16 v[78:81], v[134:137], v[220:223], v[78:81]
	v_mfma_f32_16x16x32_bf16 v[74:77], v[142:145], v[220:223], v[74:77]
	s_nop 0
	s_nop 0
	v_mfma_f32_16x16x32_bf16 v[118:121], v[146:149], v[174:177], v[118:121]
	v_mfma_f32_16x16x32_bf16 v[114:117], v[154:157], v[174:177], v[114:117]
	v_mfma_f32_16x16x32_bf16 v[102:105], v[146:149], v[190:193], v[102:105]
	v_mfma_f32_16x16x32_bf16 v[98:101], v[154:157], v[190:193], v[98:101]
	v_mfma_f32_16x16x32_bf16 v[86:89], v[146:149], v[198:201], v[86:89]
	v_mfma_f32_16x16x32_bf16 v[82:85], v[154:157], v[198:201], v[82:85]
	v_mfma_f32_16x16x32_bf16 v[70:73], v[146:149], v[216:219], v[70:73]
	v_mfma_f32_16x16x32_bf16 v[66:69], v[154:157], v[216:219], v[66:69]
	v_mfma_f32_16x16x32_bf16 v[118:121], v[150:153], v[182:185], v[118:121]
	v_mfma_f32_16x16x32_bf16 v[114:117], v[158:161], v[182:185], v[114:117]
	v_mfma_f32_16x16x32_bf16 v[102:105], v[150:153], v[194:197], v[102:105]
	v_mfma_f32_16x16x32_bf16 v[98:101], v[158:161], v[194:197], v[98:101]
	v_mfma_f32_16x16x32_bf16 v[86:89], v[150:153], v[212:215], v[86:89]
	v_mfma_f32_16x16x32_bf16 v[82:85], v[158:161], v[212:215], v[82:85]
	v_mfma_f32_16x16x32_bf16 v[70:73], v[150:153], v[220:223], v[70:73]
	v_mfma_f32_16x16x32_bf16 v[66:69], v[158:161], v[220:223], v[66:69]
	s_nop 0
	s_barrier
	s_add_i32 s43, vcc_lo, s85
	v_lshl_add_u64 v[224:225], s[70:71], 0, v[164:165]
	s_mov_b32 m0, s43
	ds_read_b128 v[174:177], v204 offset:16384
	ds_read_b128 v[182:185], v204 offset:17408
	ds_read_b128 v[190:193], v204 offset:18432
	ds_read_b128 v[194:197], v204 offset:19456
	ds_read_b128 v[198:201], v204 offset:20480
	ds_read_b128 v[212:215], v204 offset:21504
	ds_read_b128 v[216:219], v204 offset:22528
	ds_read_b128 v[220:223], v204 offset:23552
	global_load_lds_dwordx4 v[224:225], off
	s_add_i32 m0, s43, 0x2000
	s_add_u32 vcc_lo, s70, 0x40000
	v_lshl_add_u64 v[226:227], s[70:71], 0, v[168:169]
	s_addc_u32 vcc_hi, s71, 0
	s_add_i32 s42, s42, s85
	global_load_lds_dwordx4 v[226:227], off
	v_lshl_add_u64 v[228:229], vcc, 0, v[164:165]
	s_mov_b32 m0, s42
	v_lshl_add_u64 v[230:231], s[72:73], 0, v[166:167]
	global_load_lds_dwordx4 v[228:229], off
	v_lshl_add_u64 v[228:229], vcc, 0, v[168:169]
	s_add_i32 m0, s42, 0x2000
	s_nop 0
	global_load_lds_dwordx4 v[228:229], off
	v_lshl_add_u64 v[228:229], s[72:73], 0, v[162:163]
	s_mov_b32 m0, s86
	s_nop 0
	global_load_lds_dwordx4 v[228:229], off
	s_mov_b32 m0, s87
	s_nop 0
	global_load_lds_dwordx4 v[230:231], off
	s_waitcnt vmcnt(8)
	s_waitcnt lgkmcnt(0)
	s_barrier
; #define PG8_STAGE(bufoff, gbase, voff) do { _Pragma("unroll") for (int _i = 0; _i < 2; ++_i) \
;         __builtin_amdgcn_global_load_lds((const unsigned*)((const char*)(gbase) + (voff)[_i]), (LAS unsigned*)(lds + (bufoff) + ldsw + _i * 8192), 16, 0, 0); } while (0)
; #define PG8_LDA(dst, b, h) do { _Pragma("unroll") for (int m = 0; m < 4; ++m) _Pragma("unroll") for (int k = 0; k < 2; ++k) dst[m][k] = *(const LAS bf16x8*)(lds + PG8_SA(b, h) + aoff + m * 2048 + k * 1024); } while (0)
; #define PG8_LDB(dst, b, h) do { _Pragma("unroll") for (int n = 0; n < 2; ++n) _Pragma("unroll") for (int k = 0; k < 2; ++k) dst[n][k] = *(const LAS bf16x8*)(lds + PG8_SB(b, h) + boff + n * 2048 + k * 1024); } while (0)
; #define PG8_MMA(ai, bj, At, Bt) do { __builtin_amdgcn_s_setprio(1); _Pragma("unroll") for (int m = 0; m < 4; ++m) _Pragma("unroll") for (int n = 0; n < 2; ++n) _Pragma("unroll") for (int k = 0; k < 2; ++k) \
;         acc[ai][bj][m][n] = __builtin_amdgcn_mfma_f32_16x16x32_bf16(Bt[n][k], At[m][k], acc[ai][bj][m][n], 0, 0, 0); __builtin_amdgcn_s_setprio(0); } while (0)
; #define PG8_WAIT_V(n) asm volatile("s_waitcnt vmcnt(" #n ")" ::: "memory")
; #define PG8_WAIT_L(n) asm volatile("s_waitcnt lgkmcnt(" #n ")" ::: "memory")
; #define PG8_BAR __builtin_amdgcn_s_barrier()
; #define PG8_SCHED __builtin_amdgcn_sched_barrier(0)
; template <class Epi, class Sched>
; DI void gemm_phase(LAS unsigned char* lds, const int K, const Sched& S, const Epi& E) {
;     ...
;             PG8_WAIT_V(8); PG8_WAIT_L(0); PG8_BAR; PG8_MMA(1, 0, At, B0); PG8_MMA(1, 1, At, B1); PG8_BAR; PG8_SCHED;
;             PG8_LDB(B0, 1, 0); PG8_LDB(B1, 1, 1); PG8_SCHED; PG8_LDA(At, 1, 0); PG8_STAGE(PG8_SA(0, 1), a2 + hstep, voffA);
;             PG8_WAIT_V(8); PG8_WAIT_L(0); PG8_BAR; PG8_MMA(0, 0, At, B0); PG8_MMA(0, 1, At, B1); PG8_BAR; PG8_SCHED;
	s_nop 0
	s_waitcnt lgkmcnt(0)
	v_mfma_f32_16x16x32_bf16 v[62:65], v[130:133], v[174:177], v[62:65]
	v_mfma_f32_16x16x32_bf16 v[58:61], v[138:141], v[174:177], v[58:61]
	v_mfma_f32_16x16x32_bf16 v[46:49], v[130:133], v[190:193], v[46:49]
	v_mfma_f32_16x16x32_bf16 v[42:45], v[138:141], v[190:193], v[42:45]
	v_mfma_f32_16x16x32_bf16 v[30:33], v[130:133], v[198:201], v[30:33]
	v_mfma_f32_16x16x32_bf16 v[26:29], v[138:141], v[198:201], v[26:29]
	v_mfma_f32_16x16x32_bf16 v[14:17], v[130:133], v[216:219], v[14:17]
	v_mfma_f32_16x16x32_bf16 v[10:13], v[138:141], v[216:219], v[10:13]
	v_mfma_f32_16x16x32_bf16 v[62:65], v[134:137], v[182:185], v[62:65]
	v_mfma_f32_16x16x32_bf16 v[58:61], v[142:145], v[182:185], v[58:61]
	v_mfma_f32_16x16x32_bf16 v[46:49], v[134:137], v[194:197], v[46:49]
	v_mfma_f32_16x16x32_bf16 v[42:45], v[142:145], v[194:197], v[42:45]
	v_mfma_f32_16x16x32_bf16 v[30:33], v[134:137], v[212:215], v[30:33]
	v_mfma_f32_16x16x32_bf16 v[26:29], v[142:145], v[212:215], v[26:29]
	v_mfma_f32_16x16x32_bf16 v[14:17], v[134:137], v[220:223], v[14:17]
	v_mfma_f32_16x16x32_bf16 v[10:13], v[142:145], v[220:223], v[10:13]
	s_nop 0
	s_nop 0
	v_mfma_f32_16x16x32_bf16 v[54:57], v[146:149], v[174:177], v[54:57]
	v_mfma_f32_16x16x32_bf16 v[50:53], v[154:157], v[174:177], v[50:53]
	v_mfma_f32_16x16x32_bf16 v[38:41], v[146:149], v[190:193], v[38:41]
	v_mfma_f32_16x16x32_bf16 v[34:37], v[154:157], v[190:193], v[34:37]
	v_mfma_f32_16x16x32_bf16 v[22:25], v[146:149], v[198:201], v[22:25]
	v_mfma_f32_16x16x32_bf16 v[18:21], v[154:157], v[198:201], v[18:21]
	v_mfma_f32_16x16x32_bf16 v[6:9], v[146:149], v[216:219], v[6:9]
	v_mfma_f32_16x16x32_bf16 v[2:5], v[154:157], v[216:219], v[2:5]
	v_mfma_f32_16x16x32_bf16 v[54:57], v[150:153], v[182:185], v[54:57]
	v_mfma_f32_16x16x32_bf16 v[50:53], v[158:161], v[182:185], v[50:53]
	v_mfma_f32_16x16x32_bf16 v[38:41], v[150:153], v[194:197], v[38:41]
	v_mfma_f32_16x16x32_bf16 v[34:37], v[158:161], v[194:197], v[34:37]
	v_mfma_f32_16x16x32_bf16 v[22:25], v[150:153], v[212:215], v[22:25]
	v_mfma_f32_16x16x32_bf16 v[18:21], v[158:161], v[212:215], v[18:21]
	v_mfma_f32_16x16x32_bf16 v[6:9], v[150:153], v[220:223], v[6:9]
	v_mfma_f32_16x16x32_bf16 v[2:5], v[158:161], v[220:223], v[2:5]
	s_nop 0
	s_barrier
	s_add_i32 s42, 0, 0x18000
	s_add_i32 s43, 0, 0x1c000
	v_add_u32_e32 v142, s42, v203
	v_add_u32_e32 v158, s43, v203
	ds_read_b128 v[130:133], v142
	ds_read_b128 v[134:137], v142 offset:1024
	ds_read_b128 v[138:141], v142 offset:2048
	ds_read_b128 v[142:145], v142 offset:3072
	ds_read_b128 v[146:149], v158
	ds_read_b128 v[150:153], v158 offset:1024
	ds_read_b128 v[154:157], v158 offset:2048
	ds_read_b128 v[158:161], v158 offset:3072
	s_add_u32 s72, s72, 0x40000
	s_addc_u32 s73, s73, 0
	s_mov_b32 m0, s92
	v_lshl_add_u64 v[232:233], s[72:73], 0, v[162:163]
	ds_read_b128 v[174:177], v204 offset:32768
	ds_read_b128 v[182:185], v204 offset:33792
	ds_read_b128 v[190:193], v204 offset:34816
	ds_read_b128 v[194:197], v204 offset:35840
	ds_read_b128 v[198:201], v204 offset:36864
	ds_read_b128 v[212:215], v204 offset:37888
	ds_read_b128 v[216:219], v204 offset:38912
	ds_read_b128 v[220:223], v204 offset:39936
	global_load_lds_dwordx4 v[232:233], off
	v_lshl_add_u64 v[232:233], s[72:73], 0, v[166:167]
	s_mov_b32 m0, s94
	s_nop 0
	global_load_lds_dwordx4 v[232:233], off
	s_waitcnt vmcnt(8)
	s_waitcnt lgkmcnt(0)
	s_barrier
	s_nop 0
	s_waitcnt lgkmcnt(0)
	v_mfma_f32_16x16x32_bf16 v[126:129], v[130:133], v[174:177], v[126:129]
	v_mfma_f32_16x16x32_bf16 v[122:125], v[138:141], v[174:177], v[122:125]
	v_mfma_f32_16x16x32_bf16 v[110:113], v[130:133], v[190:193], v[110:113]
	v_mfma_f32_16x16x32_bf16 v[106:109], v[138:141], v[190:193], v[106:109]
	v_mfma_f32_16x16x32_bf16 v[94:97], v[130:133], v[198:201], v[94:97]
	v_mfma_f32_16x16x32_bf16 v[90:93], v[138:141], v[198:201], v[90:93]
	v_mfma_f32_16x16x32_bf16 v[78:81], v[130:133], v[216:219], v[78:81]
	v_mfma_f32_16x16x32_bf16 v[74:77], v[138:141], v[216:219], v[74:77]
	v_mfma_f32_16x16x32_bf16 v[126:129], v[134:137], v[182:185], v[126:129]
	v_mfma_f32_16x16x32_bf16 v[122:125], v[142:145], v[182:185], v[122:125]
	v_mfma_f32_16x16x32_bf16 v[110:113], v[134:137], v[194:197], v[110:113]
	v_mfma_f32_16x16x32_bf16 v[106:109], v[142:145], v[194:197], v[106:109]
	v_mfma_f32_16x16x32_bf16 v[94:97], v[134:137], v[212:215], v[94:97]
	v_mfma_f32_16x16x32_bf16 v[90:93], v[142:145], v[212:215], v[90:93]
	v_mfma_f32_16x16x32_bf16 v[78:81], v[134:137], v[220:223], v[78:81]
	v_mfma_f32_16x16x32_bf16 v[74:77], v[142:145], v[220:223], v[74:77]
	s_nop 0
	s_nop 0
	v_mfma_f32_16x16x32_bf16 v[118:121], v[146:149], v[174:177], v[118:121]
	v_mfma_f32_16x16x32_bf16 v[114:117], v[154:157], v[174:177], v[114:117]
	v_mfma_f32_16x16x32_bf16 v[102:105], v[146:149], v[190:193], v[102:105]
	v_mfma_f32_16x16x32_bf16 v[98:101], v[154:157], v[190:193], v[98:101]
	v_mfma_f32_16x16x32_bf16 v[86:89], v[146:149], v[198:201], v[86:89]
	v_mfma_f32_16x16x32_bf16 v[82:85], v[154:157], v[198:201], v[82:85]
	v_mfma_f32_16x16x32_bf16 v[70:73], v[146:149], v[216:219], v[70:73]
	v_mfma_f32_16x16x32_bf16 v[66:69], v[154:157], v[216:219], v[66:69]
	v_mfma_f32_16x16x32_bf16 v[118:121], v[150:153], v[182:185], v[118:121]
	v_mfma_f32_16x16x32_bf16 v[114:117], v[158:161], v[182:185], v[114:117]
	v_mfma_f32_16x16x32_bf16 v[102:105], v[150:153], v[194:197], v[102:105]
	v_mfma_f32_16x16x32_bf16 v[98:101], v[158:161], v[194:197], v[98:101]
	v_mfma_f32_16x16x32_bf16 v[86:89], v[150:153], v[212:215], v[86:89]
	v_mfma_f32_16x16x32_bf16 v[82:85], v[158:161], v[212:215], v[82:85]
	v_mfma_f32_16x16x32_bf16 v[70:73], v[150:153], v[220:223], v[70:73]
	v_mfma_f32_16x16x32_bf16 v[66:69], v[158:161], v[220:223], v[66:69]
	s_nop 0
	s_barrier
; #define PG8_STAGE(bufoff, gbase, voff) do { _Pragma("unroll") for (int _i = 0; _i < 2; ++_i) \
;         __builtin_amdgcn_global_load_lds((const unsigned*)((const char*)(gbase) + (voff)[_i]), (LAS unsigned*)(lds + (bufoff) + ldsw + _i * 8192), 16, 0, 0); } while (0)
; #define PG8_LDA(dst, b, h) do { _Pragma("unroll") for (int m = 0; m < 4; ++m) _Pragma("unroll") for (int k = 0; k < 2; ++k) dst[m][k] = *(const LAS bf16x8*)(lds + PG8_SA(b, h) + aoff + m * 2048 + k * 1024); } while (0)
; #define PG8_MMA(ai, bj, At, Bt) do { __builtin_amdgcn_s_setprio(1); _Pragma("unroll") for (int m = 0; m < 4; ++m) _Pragma("unroll") for (int n = 0; n < 2; ++n) _Pragma("unroll") for (int k = 0; k < 2; ++k) \
;         acc[ai][bj][m][n] = __builtin_amdgcn_mfma_f32_16x16x32_bf16(Bt[n][k], At[m][k], acc[ai][bj][m][n], 0, 0, 0); __builtin_amdgcn_s_setprio(0); } while (0)
; #define PG8_WAIT_V(n) asm volatile("s_waitcnt vmcnt(" #n ")" ::: "memory")
; #define PG8_WAIT_L(n) asm volatile("s_waitcnt lgkmcnt(" #n ")" ::: "memory")
; #define PG8_BAR __builtin_amdgcn_s_barrier()
; #define PG8_SCHED __builtin_amdgcn_sched_barrier(0)
; template <class Epi, class Sched>
; DI void gemm_phase(LAS unsigned char* lds, const int K, const Sched& S, const Epi& E) {
;     ...
;             PG8_LDA(At, 1, 1); PG8_STAGE(PG8_SB(1, 0), b3, voffB); PG8_STAGE(PG8_SB(1, 1), b3 + hstep, voffB); PG8_STAGE(PG8_SA(1, 0), a3, voffA);
;             PG8_WAIT_V(8); PG8_WAIT_L(0); PG8_BAR; PG8_MMA(1, 0, At, B0); PG8_MMA(1, 1, At, B1); PG8_BAR; PG8_SCHED;
;         }
;         if (wr == 0) PG8_BAR;
	s_add_i32 s42, s42, s85
	v_lshl_add_u64 v[224:225], v[224:225], 0, s[90:91]
	s_mov_b32 m0, s42
	ds_read_b128 v[174:177], v204 offset:49152
	ds_read_b128 v[182:185], v204 offset:50176
	ds_read_b128 v[190:193], v204 offset:51200
	ds_read_b128 v[194:197], v204 offset:52224
	ds_read_b128 v[198:201], v204 offset:53248
	ds_read_b128 v[212:215], v204 offset:54272
	ds_read_b128 v[216:219], v204 offset:55296
	ds_read_b128 v[220:223], v204 offset:56320
	global_load_lds_dwordx4 v[224:225], off
	s_add_i32 m0, s42, 0x2000
	s_add_u32 s70, s70, 0x40080
	v_lshl_add_u64 v[224:225], v[226:227], 0, s[90:91]
	s_addc_u32 s71, s71, 0
	s_add_i32 s42, s43, s85
	global_load_lds_dwordx4 v[224:225], off
	v_lshl_add_u64 v[224:225], s[70:71], 0, v[164:165]
	s_mov_b32 m0, s42
	s_nop 0
	global_load_lds_dwordx4 v[224:225], off
	v_lshl_add_u64 v[224:225], s[70:71], 0, v[168:169]
	s_add_i32 m0, s42, 0x2000
	s_nop 0
	global_load_lds_dwordx4 v[224:225], off
	v_lshl_add_u64 v[224:225], v[228:229], 0, s[90:91]
	s_mov_b32 m0, s45
	s_nop 0
	global_load_lds_dwordx4 v[224:225], off
	v_lshl_add_u64 v[224:225], v[230:231], 0, s[90:91]
	s_mov_b32 m0, s50
	s_nop 0
	global_load_lds_dwordx4 v[224:225], off
	s_waitcnt vmcnt(8)
	s_waitcnt lgkmcnt(0)
	s_barrier
	s_nop 0
	s_waitcnt lgkmcnt(0)
	v_mfma_f32_16x16x32_bf16 v[62:65], v[130:133], v[174:177], v[62:65]
	v_mfma_f32_16x16x32_bf16 v[58:61], v[138:141], v[174:177], v[58:61]
	v_mfma_f32_16x16x32_bf16 v[46:49], v[130:133], v[190:193], v[46:49]
	v_mfma_f32_16x16x32_bf16 v[42:45], v[138:141], v[190:193], v[42:45]
	v_mfma_f32_16x16x32_bf16 v[30:33], v[130:133], v[198:201], v[30:33]
	v_mfma_f32_16x16x32_bf16 v[26:29], v[138:141], v[198:201], v[26:29]
	v_mfma_f32_16x16x32_bf16 v[14:17], v[130:133], v[216:219], v[14:17]
	v_mfma_f32_16x16x32_bf16 v[10:13], v[138:141], v[216:219], v[10:13]
	v_mfma_f32_16x16x32_bf16 v[62:65], v[134:137], v[182:185], v[62:65]
	v_mfma_f32_16x16x32_bf16 v[58:61], v[142:145], v[182:185], v[58:61]
	v_mfma_f32_16x16x32_bf16 v[46:49], v[134:137], v[194:197], v[46:49]
	v_mfma_f32_16x16x32_bf16 v[42:45], v[142:145], v[194:197], v[42:45]
	v_mfma_f32_16x16x32_bf16 v[30:33], v[134:137], v[212:215], v[30:33]
	v_mfma_f32_16x16x32_bf16 v[26:29], v[142:145], v[212:215], v[26:29]
	v_mfma_f32_16x16x32_bf16 v[14:17], v[134:137], v[220:223], v[14:17]
	v_mfma_f32_16x16x32_bf16 v[10:13], v[142:145], v[220:223], v[10:13]
	s_nop 0
	s_nop 0
	v_mfma_f32_16x16x32_bf16 v[54:57], v[146:149], v[174:177], v[54:57]
	v_mfma_f32_16x16x32_bf16 v[50:53], v[154:157], v[174:177], v[50:53]
	v_mfma_f32_16x16x32_bf16 v[38:41], v[146:149], v[190:193], v[38:41]
	v_mfma_f32_16x16x32_bf16 v[34:37], v[154:157], v[190:193], v[34:37]
	v_mfma_f32_16x16x32_bf16 v[22:25], v[146:149], v[198:201], v[22:25]
	v_mfma_f32_16x16x32_bf16 v[18:21], v[154:157], v[198:201], v[18:21]
	v_mfma_f32_16x16x32_bf16 v[6:9], v[146:149], v[216:219], v[6:9]
	v_mfma_f32_16x16x32_bf16 v[2:5], v[154:157], v[216:219], v[2:5]
	v_mfma_f32_16x16x32_bf16 v[54:57], v[150:153], v[182:185], v[54:57]
	v_mfma_f32_16x16x32_bf16 v[50:53], v[158:161], v[182:185], v[50:53]
	v_mfma_f32_16x16x32_bf16 v[38:41], v[150:153], v[194:197], v[38:41]
	v_mfma_f32_16x16x32_bf16 v[34:37], v[158:161], v[194:197], v[34:37]
	v_mfma_f32_16x16x32_bf16 v[22:25], v[150:153], v[212:215], v[22:25]
	v_mfma_f32_16x16x32_bf16 v[18:21], v[158:161], v[212:215], v[18:21]
	v_mfma_f32_16x16x32_bf16 v[6:9], v[150:153], v[220:223], v[6:9]
	v_mfma_f32_16x16x32_bf16 v[2:5], v[158:161], v[220:223], v[2:5]
	s_nop 0
	s_barrier
	s_add_i32 s79, s79, 2
	s_add_u32 s77, s77, 0x100
	s_addc_u32 s78, s78, 0
	s_add_u32 s68, s68, 0x100
	s_addc_u32 s69, s69, 0
	s_cmp_gt_u32 s79, 13
	s_cbranch_scc0 .LBB0_465
	s_and_b64 vcc, exec, s[48:49]
	s_cbranch_vccz .LBB0_468
	s_barrier

; #define PG8_STAGE(bufoff, gbase, voff) do { _Pragma("unroll") for (int _i = 0; _i < 2; ++_i) \
;         __builtin_amdgcn_global_load_lds((const unsigned*)((const char*)(gbase) + (voff)[_i]), (LAS unsigned*)(lds + (bufoff) + ldsw + _i * 8192), 16, 0, 0); } while (0)
; #define PG8_LDA(dst, b, h) do { _Pragma("unroll") for (int m = 0; m < 4; ++m) _Pragma("unroll") for (int k = 0; k < 2; ++k) dst[m][k] = *(const LAS bf16x8*)(lds + PG8_SA(b, h) + aoff + m * 2048 + k * 1024); } while (0)
; #define PG8_LDB(dst, b, h) do { _Pragma("unroll") for (int n = 0; n < 2; ++n) _Pragma("unroll") for (int k = 0; k < 2; ++k) dst[n][k] = *(const LAS bf16x8*)(lds + PG8_SB(b, h) + boff + n * 2048 + k * 1024); } while (0)
; #define PG8_MMA(ai, bj, At, Bt) do { __builtin_amdgcn_s_setprio(1); _Pragma("unroll") for (int m = 0; m < 4; ++m) _Pragma("unroll") for (int n = 0; n < 2; ++n) _Pragma("unroll") for (int k = 0; k < 2; ++k) \
;         acc[ai][bj][m][n] = __builtin_amdgcn_mfma_f32_16x16x32_bf16(Bt[n][k], At[m][k], acc[ai][bj][m][n], 0, 0, 0); __builtin_amdgcn_s_setprio(0); } while (0)
; #define PG8_WAIT_V(n) asm volatile("s_waitcnt vmcnt(" #n ")" ::: "memory")
; #define PG8_WAIT_L(n) asm volatile("s_waitcnt lgkmcnt(" #n ")" ::: "memory")
; #define PG8_BAR __builtin_amdgcn_s_barrier()
; #define PG8_SCHED __builtin_amdgcn_sched_barrier(0)
; template <class Epi, class Sched>
; DI void gemm_phase(LAS unsigned char* lds, const int K, const Sched& S, const Epi& E) {
;     ...
;         for (int t = 0; t < nt; t += 2) {
;             const bool last = (t == nt - 2);
;             const char* a1 = cA + (size_t)(t + 1) * kstep;
;             const char* a2 = last ? nA : cA + (size_t)(t + 2) * kstep; const char* b2 = last ? nB : cB + (size_t)(t + 2) * kstep;
;             const char* a3 = a2 + kstep; const char* b3 = b2 + kstep;
;             PG8_LDB(B0, 0, 0); PG8_LDB(B1, 0, 1); PG8_SCHED; PG8_LDA(At, 0, 0); PG8_STAGE(PG8_SA(1, 1), a1 + hstep, voffA);
;             PG8_WAIT_V(8); PG8_WAIT_L(0); PG8_BAR; PG8_MMA(0, 0, At, B0); PG8_MMA(0, 1, At, B1); PG8_BAR; PG8_SCHED;
;             PG8_LDA(At, 0, 1); PG8_STAGE(PG8_SB(0, 0), b2, voffB); PG8_STAGE(PG8_SB(0, 1), b2 + hstep, voffB); PG8_STAGE(PG8_SA(0, 0), a2, voffA);
;             PG8_WAIT_V(8); PG8_WAIT_L(0); PG8_BAR; PG8_MMA(1, 0, At, B0); PG8_MMA(1, 1, At, B1); PG8_BAR; PG8_SCHED;
.LBB0_648:
	s_add_u32 s66, s64, 0xfffc0080
	s_addc_u32 s67, s65, -1
	s_add_i32 s92, 0, 0x10000
	s_cmp_eq_u32 s63, 12
	s_cselect_b32 s69, s59, s67
	s_cselect_b32 s68, s58, s66
	v_add_u32_e32 v1, s92, v154
	s_cselect_b32 s67, s61, s57
	s_cselect_b32 s66, s60, s55
	s_add_i32 s95, 0, 0x14000
	ds_read_b128 v[142:145], v1
	s_waitcnt lgkmcnt(0)
	ds_read_b128 v[146:149], v1 offset:1024
	ds_read_b128 v[156:159], v1 offset:2048
	ds_read_b128 v[160:163], v1 offset:3072
	v_add_u32_e32 v1, s95, v154
	ds_read_b128 v[164:167], v1
	ds_read_b128 v[168:171], v1 offset:1024
	ds_read_b128 v[172:175], v1 offset:2048
	ds_read_b128 v[182:185], v1 offset:3072
	v_lshl_add_u64 v[150:151], s[64:65], 0, v[140:141]
	s_add_i32 m0, s76, 0xc000
	ds_read_b128 v[190:193], v155
	ds_read_b128 v[194:197], v155 offset:1024
	ds_read_b128 v[198:201], v155 offset:2048
	ds_read_b128 v[202:205], v155 offset:3072
	ds_read_b128 v[212:215], v155 offset:4096
	ds_read_b128 v[216:219], v155 offset:5120
	ds_read_b128 v[220:223], v155 offset:6144
	ds_read_b128 v[224:227], v155 offset:7168
	global_load_lds_dwordx4 v[150:151], off
	v_lshl_add_u64 v[150:151], s[64:65], 0, v[138:139]
	s_add_i32 m0, s76, 0xe000
	s_nop 0
	global_load_lds_dwordx4 v[150:151], off
	s_waitcnt vmcnt(8)
	s_waitcnt lgkmcnt(0)
	s_barrier
	s_nop 0
	s_waitcnt lgkmcnt(0)
	v_mfma_f32_16x16x32_bf16 v[126:129], v[142:145], v[190:193], v[126:129]
	v_mfma_f32_16x16x32_bf16 v[122:125], v[156:159], v[190:193], v[122:125]
	v_mfma_f32_16x16x32_bf16 v[110:113], v[142:145], v[198:201], v[110:113]
	v_mfma_f32_16x16x32_bf16 v[106:109], v[156:159], v[198:201], v[106:109]
	v_mfma_f32_16x16x32_bf16 v[94:97], v[142:145], v[212:215], v[94:97]
	v_mfma_f32_16x16x32_bf16 v[90:93], v[156:159], v[212:215], v[90:93]
	v_mfma_f32_16x16x32_bf16 v[78:81], v[142:145], v[220:223], v[78:81]
	v_mfma_f32_16x16x32_bf16 v[74:77], v[156:159], v[220:223], v[74:77]
	v_mfma_f32_16x16x32_bf16 v[126:129], v[146:149], v[194:197], v[126:129]
	v_mfma_f32_16x16x32_bf16 v[122:125], v[160:163], v[194:197], v[122:125]
	v_mfma_f32_16x16x32_bf16 v[110:113], v[146:149], v[202:205], v[110:113]
	v_mfma_f32_16x16x32_bf16 v[106:109], v[160:163], v[202:205], v[106:109]
	v_mfma_f32_16x16x32_bf16 v[94:97], v[146:149], v[216:219], v[94:97]
	v_mfma_f32_16x16x32_bf16 v[90:93], v[160:163], v[216:219], v[90:93]
	v_mfma_f32_16x16x32_bf16 v[78:81], v[146:149], v[224:227], v[78:81]
	v_mfma_f32_16x16x32_bf16 v[74:77], v[160:163], v[224:227], v[74:77]
	s_nop 0
	s_nop 0
	v_mfma_f32_16x16x32_bf16 v[118:121], v[164:167], v[190:193], v[118:121]
	v_mfma_f32_16x16x32_bf16 v[114:117], v[172:175], v[190:193], v[114:117]
	v_mfma_f32_16x16x32_bf16 v[102:105], v[164:167], v[198:201], v[102:105]
	v_mfma_f32_16x16x32_bf16 v[98:101], v[172:175], v[198:201], v[98:101]
	v_mfma_f32_16x16x32_bf16 v[86:89], v[164:167], v[212:215], v[86:89]
	v_mfma_f32_16x16x32_bf16 v[82:85], v[172:175], v[212:215], v[82:85]
	v_mfma_f32_16x16x32_bf16 v[70:73], v[164:167], v[220:223], v[70:73]
	v_mfma_f32_16x16x32_bf16 v[66:69], v[172:175], v[220:223], v[66:69]
	v_mfma_f32_16x16x32_bf16 v[118:121], v[168:171], v[194:197], v[118:121]
	v_mfma_f32_16x16x32_bf16 v[114:117], v[182:185], v[194:197], v[114:117]
	v_mfma_f32_16x16x32_bf16 v[102:105], v[168:171], v[202:205], v[102:105]
	v_mfma_f32_16x16x32_bf16 v[98:101], v[182:185], v[202:205], v[98:101]
	v_mfma_f32_16x16x32_bf16 v[86:89], v[168:171], v[216:219], v[86:89]
	v_mfma_f32_16x16x32_bf16 v[82:85], v[182:185], v[216:219], v[82:85]
	v_mfma_f32_16x16x32_bf16 v[70:73], v[168:171], v[224:227], v[70:73]
	v_mfma_f32_16x16x32_bf16 v[66:69], v[182:185], v[224:227], v[66:69]
	s_nop 0
	s_barrier
	s_add_i32 s92, s92, s75
	v_lshl_add_u64 v[150:151], s[66:67], 0, v[132:133]
	s_mov_b32 m0, s92
	ds_read_b128 v[190:193], v155 offset:16384
	ds_read_b128 v[194:197], v155 offset:17408
	ds_read_b128 v[198:201], v155 offset:18432
	ds_read_b128 v[202:205], v155 offset:19456
	ds_read_b128 v[212:215], v155 offset:20480
	ds_read_b128 v[216:219], v155 offset:21504
	ds_read_b128 v[220:223], v155 offset:22528
	ds_read_b128 v[224:227], v155 offset:23552
	global_load_lds_dwordx4 v[150:151], off
	s_add_i32 m0, s92, 0x2000
	s_add_u32 vcc_lo, s66, 0x40000
	v_lshl_add_u64 v[176:177], s[66:67], 0, v[136:137]
	s_addc_u32 vcc_hi, s67, 0
	s_add_i32 s92, s95, s75
	global_load_lds_dwordx4 v[176:177], off
	v_lshl_add_u64 v[228:229], vcc, 0, v[132:133]
	s_mov_b32 m0, s92
	v_lshl_add_u64 v[230:231], s[68:69], 0, v[134:135]
	global_load_lds_dwordx4 v[228:229], off
	v_lshl_add_u64 v[228:229], vcc, 0, v[136:137]
	s_add_i32 m0, s92, 0x2000
	s_nop 0
	global_load_lds_dwordx4 v[228:229], off
	v_lshl_add_u64 v[228:229], s[68:69], 0, v[130:131]
	s_mov_b32 m0, s76
	s_nop 0
	global_load_lds_dwordx4 v[228:229], off
	s_mov_b32 m0, s77
	s_nop 0
	global_load_lds_dwordx4 v[230:231], off
	s_waitcnt vmcnt(8)
	s_waitcnt lgkmcnt(0)
	s_barrier
; #define PG8_STAGE(bufoff, gbase, voff) do { _Pragma("unroll") for (int _i = 0; _i < 2; ++_i) \
;         __builtin_amdgcn_global_load_lds((const unsigned*)((const char*)(gbase) + (voff)[_i]), (LAS unsigned*)(lds + (bufoff) + ldsw + _i * 8192), 16, 0, 0); } while (0)
; #define PG8_LDA(dst, b, h) do { _Pragma("unroll") for (int m = 0; m < 4; ++m) _Pragma("unroll") for (int k = 0; k < 2; ++k) dst[m][k] = *(const LAS bf16x8*)(lds + PG8_SA(b, h) + aoff + m * 2048 + k * 1024); } while (0)
; #define PG8_LDB(dst, b, h) do { _Pragma("unroll") for (int n = 0; n < 2; ++n) _Pragma("unroll") for (int k = 0; k < 2; ++k) dst[n][k] = *(const LAS bf16x8*)(lds + PG8_SB(b, h) + boff + n * 2048 + k * 1024); } while (0)
; #define PG8_MMA(ai, bj, At, Bt) do { __builtin_amdgcn_s_setprio(1); _Pragma("unroll") for (int m = 0; m < 4; ++m) _Pragma("unroll") for (int n = 0; n < 2; ++n) _Pragma("unroll") for (int k = 0; k < 2; ++k) \
;         acc[ai][bj][m][n] = __builtin_amdgcn_mfma_f32_16x16x32_bf16(Bt[n][k], At[m][k], acc[ai][bj][m][n], 0, 0, 0); __builtin_amdgcn_s_setprio(0); } while (0)
; #define PG8_WAIT_V(n) asm volatile("s_waitcnt vmcnt(" #n ")" ::: "memory")
; #define PG8_WAIT_L(n) asm volatile("s_waitcnt lgkmcnt(" #n ")" ::: "memory")
; #define PG8_BAR __builtin_amdgcn_s_barrier()
; #define PG8_SCHED __builtin_amdgcn_sched_barrier(0)
; template <class Epi, class Sched>
; DI void gemm_phase(LAS unsigned char* lds, const int K, const Sched& S, const Epi& E) {
;     ...
;             PG8_WAIT_V(8); PG8_WAIT_L(0); PG8_BAR; PG8_MMA(1, 0, At, B0); PG8_MMA(1, 1, At, B1); PG8_BAR; PG8_SCHED;
;             PG8_LDB(B0, 1, 0); PG8_LDB(B1, 1, 1); PG8_SCHED; PG8_LDA(At, 1, 0); PG8_STAGE(PG8_SA(0, 1), a2 + hstep, voffA);
;             PG8_WAIT_V(8); PG8_WAIT_L(0); PG8_BAR; PG8_MMA(0, 0, At, B0); PG8_MMA(0, 1, At, B1); PG8_BAR; PG8_SCHED;
	s_nop 0
	s_waitcnt lgkmcnt(0)
	v_mfma_f32_16x16x32_bf16 v[62:65], v[142:145], v[190:193], v[62:65]
	v_mfma_f32_16x16x32_bf16 v[58:61], v[156:159], v[190:193], v[58:61]
	v_mfma_f32_16x16x32_bf16 v[46:49], v[142:145], v[198:201], v[46:49]
	v_mfma_f32_16x16x32_bf16 v[42:45], v[156:159], v[198:201], v[42:45]
	v_mfma_f32_16x16x32_bf16 v[30:33], v[142:145], v[212:215], v[30:33]
	v_mfma_f32_16x16x32_bf16 v[26:29], v[156:159], v[212:215], v[26:29]
	v_mfma_f32_16x16x32_bf16 v[14:17], v[142:145], v[220:223], v[14:17]
	v_mfma_f32_16x16x32_bf16 v[10:13], v[156:159], v[220:223], v[10:13]
	v_mfma_f32_16x16x32_bf16 v[62:65], v[146:149], v[194:197], v[62:65]
	v_mfma_f32_16x16x32_bf16 v[58:61], v[160:163], v[194:197], v[58:61]
	v_mfma_f32_16x16x32_bf16 v[46:49], v[146:149], v[202:205], v[46:49]
	v_mfma_f32_16x16x32_bf16 v[42:45], v[160:163], v[202:205], v[42:45]
	v_mfma_f32_16x16x32_bf16 v[30:33], v[146:149], v[216:219], v[30:33]
	v_mfma_f32_16x16x32_bf16 v[26:29], v[160:163], v[216:219], v[26:29]
	v_mfma_f32_16x16x32_bf16 v[14:17], v[146:149], v[224:227], v[14:17]
	v_mfma_f32_16x16x32_bf16 v[10:13], v[160:163], v[224:227], v[10:13]
	s_nop 0
	s_nop 0
	v_mfma_f32_16x16x32_bf16 v[54:57], v[164:167], v[190:193], v[54:57]
	v_mfma_f32_16x16x32_bf16 v[50:53], v[172:175], v[190:193], v[50:53]
	v_mfma_f32_16x16x32_bf16 v[38:41], v[164:167], v[198:201], v[38:41]
	v_mfma_f32_16x16x32_bf16 v[34:37], v[172:175], v[198:201], v[34:37]
	v_mfma_f32_16x16x32_bf16 v[22:25], v[164:167], v[212:215], v[22:25]
	v_mfma_f32_16x16x32_bf16 v[18:21], v[172:175], v[212:215], v[18:21]
	v_mfma_f32_16x16x32_bf16 v[6:9], v[164:167], v[220:223], v[6:9]
	v_mfma_f32_16x16x32_bf16 v[2:5], v[172:175], v[220:223], v[2:5]
	v_mfma_f32_16x16x32_bf16 v[54:57], v[168:171], v[194:197], v[54:57]
	v_mfma_f32_16x16x32_bf16 v[50:53], v[182:185], v[194:197], v[50:53]
	v_mfma_f32_16x16x32_bf16 v[38:41], v[168:171], v[202:205], v[38:41]
	v_mfma_f32_16x16x32_bf16 v[34:37], v[182:185], v[202:205], v[34:37]
	v_mfma_f32_16x16x32_bf16 v[22:25], v[168:171], v[216:219], v[22:25]
	v_mfma_f32_16x16x32_bf16 v[18:21], v[182:185], v[216:219], v[18:21]
	v_mfma_f32_16x16x32_bf16 v[6:9], v[168:171], v[224:227], v[6:9]
	v_mfma_f32_16x16x32_bf16 v[2:5], v[182:185], v[224:227], v[2:5]
	s_nop 0
	s_barrier
	s_add_i32 s92, 0, 0x18000
	v_add_u32_e32 v1, s92, v154
	s_add_i32 s95, 0, 0x1c000
	ds_read_b128 v[142:145], v1
	ds_read_b128 v[146:149], v1 offset:1024
	ds_read_b128 v[156:159], v1 offset:2048
	ds_read_b128 v[160:163], v1 offset:3072
	v_add_u32_e32 v1, s95, v154
	ds_read_b128 v[164:167], v1
	ds_read_b128 v[168:171], v1 offset:1024
	ds_read_b128 v[172:175], v1 offset:2048
	ds_read_b128 v[182:185], v1 offset:3072
	s_add_u32 s68, s68, 0x40000
	s_addc_u32 s69, s69, 0
	s_mov_b32 m0, s78
	v_lshl_add_u64 v[232:233], s[68:69], 0, v[130:131]
	ds_read_b128 v[190:193], v155 offset:32768
	ds_read_b128 v[194:197], v155 offset:33792
	ds_read_b128 v[198:201], v155 offset:34816
	ds_read_b128 v[202:205], v155 offset:35840
	ds_read_b128 v[212:215], v155 offset:36864
	ds_read_b128 v[216:219], v155 offset:37888
	ds_read_b128 v[220:223], v155 offset:38912
	ds_read_b128 v[224:227], v155 offset:39936
	global_load_lds_dwordx4 v[232:233], off
	v_lshl_add_u64 v[232:233], s[68:69], 0, v[134:135]
	s_mov_b32 m0, s79
	s_nop 0
	global_load_lds_dwordx4 v[232:233], off
	s_waitcnt vmcnt(8)
	s_waitcnt lgkmcnt(0)
	s_barrier
	s_nop 0
	s_waitcnt lgkmcnt(0)
	v_mfma_f32_16x16x32_bf16 v[126:129], v[142:145], v[190:193], v[126:129]
	v_mfma_f32_16x16x32_bf16 v[122:125], v[156:159], v[190:193], v[122:125]
	v_mfma_f32_16x16x32_bf16 v[110:113], v[142:145], v[198:201], v[110:113]
	v_mfma_f32_16x16x32_bf16 v[106:109], v[156:159], v[198:201], v[106:109]
	v_mfma_f32_16x16x32_bf16 v[94:97], v[142:145], v[212:215], v[94:97]
	v_mfma_f32_16x16x32_bf16 v[90:93], v[156:159], v[212:215], v[90:93]
	v_mfma_f32_16x16x32_bf16 v[78:81], v[142:145], v[220:223], v[78:81]
	v_mfma_f32_16x16x32_bf16 v[74:77], v[156:159], v[220:223], v[74:77]
	v_mfma_f32_16x16x32_bf16 v[126:129], v[146:149], v[194:197], v[126:129]
	v_mfma_f32_16x16x32_bf16 v[122:125], v[160:163], v[194:197], v[122:125]
	v_mfma_f32_16x16x32_bf16 v[110:113], v[146:149], v[202:205], v[110:113]
	v_mfma_f32_16x16x32_bf16 v[106:109], v[160:163], v[202:205], v[106:109]
	v_mfma_f32_16x16x32_bf16 v[94:97], v[146:149], v[216:219], v[94:97]
	v_mfma_f32_16x16x32_bf16 v[90:93], v[160:163], v[216:219], v[90:93]
	v_mfma_f32_16x16x32_bf16 v[78:81], v[146:149], v[224:227], v[78:81]
	v_mfma_f32_16x16x32_bf16 v[74:77], v[160:163], v[224:227], v[74:77]
	s_nop 0
	s_nop 0
	v_mfma_f32_16x16x32_bf16 v[118:121], v[164:167], v[190:193], v[118:121]
	v_mfma_f32_16x16x32_bf16 v[114:117], v[172:175], v[190:193], v[114:117]
	v_mfma_f32_16x16x32_bf16 v[102:105], v[164:167], v[198:201], v[102:105]
	v_mfma_f32_16x16x32_bf16 v[98:101], v[172:175], v[198:201], v[98:101]
	v_mfma_f32_16x16x32_bf16 v[86:89], v[164:167], v[212:215], v[86:89]
	v_mfma_f32_16x16x32_bf16 v[82:85], v[172:175], v[212:215], v[82:85]
	v_mfma_f32_16x16x32_bf16 v[70:73], v[164:167], v[220:223], v[70:73]
	v_mfma_f32_16x16x32_bf16 v[66:69], v[172:175], v[220:223], v[66:69]
	v_mfma_f32_16x16x32_bf16 v[118:121], v[168:171], v[194:197], v[118:121]
	v_mfma_f32_16x16x32_bf16 v[114:117], v[182:185], v[194:197], v[114:117]
	v_mfma_f32_16x16x32_bf16 v[102:105], v[168:171], v[202:205], v[102:105]
	v_mfma_f32_16x16x32_bf16 v[98:101], v[182:185], v[202:205], v[98:101]
	v_mfma_f32_16x16x32_bf16 v[86:89], v[168:171], v[216:219], v[86:89]
	v_mfma_f32_16x16x32_bf16 v[82:85], v[182:185], v[216:219], v[82:85]
	v_mfma_f32_16x16x32_bf16 v[70:73], v[168:171], v[224:227], v[70:73]
	v_mfma_f32_16x16x32_bf16 v[66:69], v[182:185], v[224:227], v[66:69]
	s_nop 0
	s_barrier
; #define PG8_STAGE(bufoff, gbase, voff) do { _Pragma("unroll") for (int _i = 0; _i < 2; ++_i) \
;         __builtin_amdgcn_global_load_lds((const unsigned*)((const char*)(gbase) + (voff)[_i]), (LAS unsigned*)(lds + (bufoff) + ldsw + _i * 8192), 16, 0, 0); } while (0)
; #define PG8_LDA(dst, b, h) do { _Pragma("unroll") for (int m = 0; m < 4; ++m) _Pragma("unroll") for (int k = 0; k < 2; ++k) dst[m][k] = *(const LAS bf16x8*)(lds + PG8_SA(b, h) + aoff + m * 2048 + k * 1024); } while (0)
; #define PG8_MMA(ai, bj, At, Bt) do { __builtin_amdgcn_s_setprio(1); _Pragma("unroll") for (int m = 0; m < 4; ++m) _Pragma("unroll") for (int n = 0; n < 2; ++n) _Pragma("unroll") for (int k = 0; k < 2; ++k) \
;         acc[ai][bj][m][n] = __builtin_amdgcn_mfma_f32_16x16x32_bf16(Bt[n][k], At[m][k], acc[ai][bj][m][n], 0, 0, 0); __builtin_amdgcn_s_setprio(0); } while (0)
; #define PG8_WAIT_V(n) asm volatile("s_waitcnt vmcnt(" #n ")" ::: "memory")
; #define PG8_WAIT_L(n) asm volatile("s_waitcnt lgkmcnt(" #n ")" ::: "memory")
; #define PG8_BAR __builtin_amdgcn_s_barrier()
; #define PG8_SCHED __builtin_amdgcn_sched_barrier(0)
; template <class Epi, class Sched>
; DI void gemm_phase(LAS unsigned char* lds, const int K, const Sched& S, const Epi& E) {
;     ...
;             PG8_LDA(At, 1, 1); PG8_STAGE(PG8_SB(1, 0), b3, voffB); PG8_STAGE(PG8_SB(1, 1), b3 + hstep, voffB); PG8_STAGE(PG8_SA(1, 0), a3, voffA);
;             PG8_WAIT_V(8); PG8_WAIT_L(0); PG8_BAR; PG8_MMA(1, 0, At, B0); PG8_MMA(1, 1, At, B1); PG8_BAR; PG8_SCHED;
;         }
	s_add_i32 s68, s92, s75
	v_lshl_add_u64 v[150:151], v[150:151], 0, s[90:91]
	s_mov_b32 m0, s68
	ds_read_b128 v[190:193], v155 offset:49152
	ds_read_b128 v[194:197], v155 offset:50176
	ds_read_b128 v[198:201], v155 offset:51200
	ds_read_b128 v[202:205], v155 offset:52224
	ds_read_b128 v[212:215], v155 offset:53248
	ds_read_b128 v[216:219], v155 offset:54272
	ds_read_b128 v[220:223], v155 offset:55296
	ds_read_b128 v[224:227], v155 offset:56320
	global_load_lds_dwordx4 v[150:151], off
	s_add_i32 m0, s68, 0x2000
	s_add_u32 s66, s66, 0x40080
	v_lshl_add_u64 v[150:151], v[176:177], 0, s[90:91]
	s_addc_u32 s67, s67, 0
	s_add_i32 s68, s95, s75
	global_load_lds_dwordx4 v[150:151], off
	v_lshl_add_u64 v[150:151], s[66:67], 0, v[132:133]
	s_mov_b32 m0, s68
	s_nop 0
	global_load_lds_dwordx4 v[150:151], off
	v_lshl_add_u64 v[150:151], s[66:67], 0, v[136:137]
	s_add_i32 m0, s68, 0x2000
	s_nop 0
	global_load_lds_dwordx4 v[150:151], off
	v_lshl_add_u64 v[150:151], v[228:229], 0, s[90:91]
	s_mov_b32 m0, s83
	s_nop 0
	global_load_lds_dwordx4 v[150:151], off
	v_lshl_add_u64 v[150:151], v[230:231], 0, s[90:91]
	s_mov_b32 m0, s84
	s_nop 0
	global_load_lds_dwordx4 v[150:151], off
	s_waitcnt vmcnt(8)
	s_waitcnt lgkmcnt(0)
	s_barrier
	s_nop 0
	s_waitcnt lgkmcnt(0)
	v_mfma_f32_16x16x32_bf16 v[62:65], v[142:145], v[190:193], v[62:65]
	v_mfma_f32_16x16x32_bf16 v[58:61], v[156:159], v[190:193], v[58:61]
	v_mfma_f32_16x16x32_bf16 v[46:49], v[142:145], v[198:201], v[46:49]
	v_mfma_f32_16x16x32_bf16 v[42:45], v[156:159], v[198:201], v[42:45]
	v_mfma_f32_16x16x32_bf16 v[30:33], v[142:145], v[212:215], v[30:33]
	v_mfma_f32_16x16x32_bf16 v[26:29], v[156:159], v[212:215], v[26:29]
	v_mfma_f32_16x16x32_bf16 v[14:17], v[142:145], v[220:223], v[14:17]
	v_mfma_f32_16x16x32_bf16 v[10:13], v[156:159], v[220:223], v[10:13]
	v_mfma_f32_16x16x32_bf16 v[62:65], v[146:149], v[194:197], v[62:65]
	v_mfma_f32_16x16x32_bf16 v[58:61], v[160:163], v[194:197], v[58:61]
	v_mfma_f32_16x16x32_bf16 v[46:49], v[146:149], v[202:205], v[46:49]
	v_mfma_f32_16x16x32_bf16 v[42:45], v[160:163], v[202:205], v[42:45]
	v_mfma_f32_16x16x32_bf16 v[30:33], v[146:149], v[216:219], v[30:33]
	v_mfma_f32_16x16x32_bf16 v[26:29], v[160:163], v[216:219], v[26:29]
	v_mfma_f32_16x16x32_bf16 v[14:17], v[146:149], v[224:227], v[14:17]
	v_mfma_f32_16x16x32_bf16 v[10:13], v[160:163], v[224:227], v[10:13]
	s_nop 0
	s_nop 0
	v_mfma_f32_16x16x32_bf16 v[54:57], v[164:167], v[190:193], v[54:57]
	v_mfma_f32_16x16x32_bf16 v[50:53], v[172:175], v[190:193], v[50:53]
	v_mfma_f32_16x16x32_bf16 v[38:41], v[164:167], v[198:201], v[38:41]
	v_mfma_f32_16x16x32_bf16 v[34:37], v[172:175], v[198:201], v[34:37]
	v_mfma_f32_16x16x32_bf16 v[22:25], v[164:167], v[212:215], v[22:25]
	v_mfma_f32_16x16x32_bf16 v[18:21], v[172:175], v[212:215], v[18:21]
	v_mfma_f32_16x16x32_bf16 v[6:9], v[164:167], v[220:223], v[6:9]
	v_mfma_f32_16x16x32_bf16 v[2:5], v[172:175], v[220:223], v[2:5]
	v_mfma_f32_16x16x32_bf16 v[54:57], v[168:171], v[194:197], v[54:57]
	v_mfma_f32_16x16x32_bf16 v[50:53], v[182:185], v[194:197], v[50:53]
	v_mfma_f32_16x16x32_bf16 v[38:41], v[168:171], v[202:205], v[38:41]
	v_mfma_f32_16x16x32_bf16 v[34:37], v[182:185], v[202:205], v[34:37]
	v_mfma_f32_16x16x32_bf16 v[22:25], v[168:171], v[216:219], v[22:25]
	v_mfma_f32_16x16x32_bf16 v[18:21], v[182:185], v[216:219], v[18:21]
	v_mfma_f32_16x16x32_bf16 v[6:9], v[168:171], v[224:227], v[6:9]
	v_mfma_f32_16x16x32_bf16 v[2:5], v[182:185], v[224:227], v[2:5]
	s_nop 0
	s_barrier
	s_add_i32 s63, s63, 2
	s_add_u32 s55, s55, 0x100
	s_addc_u32 s57, s57, 0
	s_add_u32 s64, s64, 0x100
	s_addc_u32 s65, s65, 0
	s_cmp_gt_u32 s63, 13
	s_cbranch_scc0 .LBB0_648
	s_and_b64 vcc, exec, s[46:47]
	s_cbranch_vccz .LBB0_651
	s_barrier

; #define PG8_STAGE(bufoff, gbase, voff) do { _Pragma("unroll") for (int _i = 0; _i < 2; ++_i) \
;         __builtin_amdgcn_global_load_lds((const unsigned*)((const char*)(gbase) + (voff)[_i]), (LAS unsigned*)(lds + (bufoff) + ldsw + _i * 8192), 16, 0, 0); } while (0)
; #define PG8_LDA(dst, b, h) do { _Pragma("unroll") for (int m = 0; m < 4; ++m) _Pragma("unroll") for (int k = 0; k < 2; ++k) dst[m][k] = *(const LAS bf16x8*)(lds + PG8_SA(b, h) + aoff + m * 2048 + k * 1024); } while (0)
; #define PG8_LDB(dst, b, h) do { _Pragma("unroll") for (int n = 0; n < 2; ++n) _Pragma("unroll") for (int k = 0; k < 2; ++k) dst[n][k] = *(const LAS bf16x8*)(lds + PG8_SB(b, h) + boff + n * 2048 + k * 1024); } while (0)
; #define PG8_MMA(ai, bj, At, Bt) do { __builtin_amdgcn_s_setprio(1); _Pragma("unroll") for (int m = 0; m < 4; ++m) _Pragma("unroll") for (int n = 0; n < 2; ++n) _Pragma("unroll") for (int k = 0; k < 2; ++k) \
;         acc[ai][bj][m][n] = __builtin_amdgcn_mfma_f32_16x16x32_bf16(Bt[n][k], At[m][k], acc[ai][bj][m][n], 0, 0, 0); __builtin_amdgcn_s_setprio(0); } while (0)
; #define PG8_WAIT_V(n) asm volatile("s_waitcnt vmcnt(" #n ")" ::: "memory")
; #define PG8_WAIT_L(n) asm volatile("s_waitcnt lgkmcnt(" #n ")" ::: "memory")
; #define PG8_BAR __builtin_amdgcn_s_barrier()
; #define PG8_SCHED __builtin_amdgcn_sched_barrier(0)
; template <class Epi, class Sched>
; DI void gemm_phase(LAS unsigned char* lds, const int K, const Sched& S, const Epi& E) {
;     ...
;             const bool last = (t == nt - 2);
;             const char* a1 = cA + (size_t)(t + 1) * kstep;
;             const char* a2 = last ? nA : cA + (size_t)(t + 2) * kstep; const char* b2 = last ? nB : cB + (size_t)(t + 2) * kstep;
;             const char* a3 = a2 + kstep; const char* b3 = b2 + kstep;
;             PG8_LDB(B0, 0, 0); PG8_LDB(B1, 0, 1); PG8_SCHED; PG8_LDA(At, 0, 0); PG8_STAGE(PG8_SA(1, 1), a1 + hstep, voffA);
;             PG8_WAIT_V(8); PG8_WAIT_L(0); PG8_BAR; PG8_MMA(0, 0, At, B0); PG8_MMA(0, 1, At, B1); PG8_BAR; PG8_SCHED;
;             PG8_LDA(At, 0, 1); PG8_STAGE(PG8_SB(0, 0), b2, voffB); PG8_STAGE(PG8_SB(0, 1), b2 + hstep, voffB); PG8_STAGE(PG8_SA(0, 0), a2, voffA);
.LBB0_784:
	s_add_u32 s48, s44, 0xfffc0080
	s_addc_u32 s49, s45, -1
	s_add_i32 s77, 0, 0x10000
	s_cmp_eq_u32 s76, 12
	s_cselect_b32 s75, s69, s49
	s_cselect_b32 s74, s68, s48
	s_cselect_b32 s73, s71, s67
	s_cselect_b32 s72, s70, s65
	s_add_i32 s48, 0, 0x14000
	v_add_u32_e32 v142, s77, v199
	v_add_u32_e32 v158, s48, v199
	ds_read_b128 v[130:133], v142
	ds_read_b128 v[134:137], v142 offset:1024
	ds_read_b128 v[138:141], v142 offset:2048
	ds_read_b128 v[142:145], v142 offset:3072
	ds_read_b128 v[146:149], v158
	ds_read_b128 v[150:153], v158 offset:1024
	ds_read_b128 v[154:157], v158 offset:2048
	ds_read_b128 v[158:161], v158 offset:3072
	v_lshl_add_u64 v[224:225], s[44:45], 0, v[172:173]
	s_add_i32 m0, s80, 0xc000
	ds_read_b128 v[174:177], v200
	ds_read_b128 v[182:185], v200 offset:1024
	ds_read_b128 v[190:193], v200 offset:2048
	ds_read_b128 v[194:197], v200 offset:3072
	ds_read_b128 v[202:205], v200 offset:4096
	ds_read_b128 v[212:215], v200 offset:5120
	ds_read_b128 v[216:219], v200 offset:6144
	ds_read_b128 v[220:223], v200 offset:7168
	global_load_lds_dwordx4 v[224:225], off
	v_lshl_add_u64 v[224:225], s[44:45], 0, v[170:171]
	s_add_i32 m0, s80, 0xe000
	s_nop 0
	global_load_lds_dwordx4 v[224:225], off
	s_waitcnt vmcnt(8)
	s_waitcnt lgkmcnt(0)
	s_barrier
	s_nop 0
	s_waitcnt lgkmcnt(0)
	v_mfma_f32_16x16x32_bf16 v[126:129], v[130:133], v[174:177], v[126:129]
	v_mfma_f32_16x16x32_bf16 v[122:125], v[138:141], v[174:177], v[122:125]
	v_mfma_f32_16x16x32_bf16 v[118:121], v[130:133], v[190:193], v[118:121]
	v_mfma_f32_16x16x32_bf16 v[114:117], v[138:141], v[190:193], v[114:117]
	v_mfma_f32_16x16x32_bf16 v[110:113], v[130:133], v[202:205], v[110:113]
	v_mfma_f32_16x16x32_bf16 v[106:109], v[138:141], v[202:205], v[106:109]
	v_mfma_f32_16x16x32_bf16 v[102:105], v[130:133], v[216:219], v[102:105]
	v_mfma_f32_16x16x32_bf16 v[98:101], v[138:141], v[216:219], v[98:101]
	v_mfma_f32_16x16x32_bf16 v[126:129], v[134:137], v[182:185], v[126:129]
	v_mfma_f32_16x16x32_bf16 v[122:125], v[142:145], v[182:185], v[122:125]
	v_mfma_f32_16x16x32_bf16 v[118:121], v[134:137], v[194:197], v[118:121]
	v_mfma_f32_16x16x32_bf16 v[114:117], v[142:145], v[194:197], v[114:117]
	v_mfma_f32_16x16x32_bf16 v[110:113], v[134:137], v[212:215], v[110:113]
	v_mfma_f32_16x16x32_bf16 v[106:109], v[142:145], v[212:215], v[106:109]
	v_mfma_f32_16x16x32_bf16 v[102:105], v[134:137], v[220:223], v[102:105]
	v_mfma_f32_16x16x32_bf16 v[98:101], v[142:145], v[220:223], v[98:101]
	s_nop 0
	s_nop 0
	v_mfma_f32_16x16x32_bf16 v[94:97], v[146:149], v[174:177], v[94:97]
	v_mfma_f32_16x16x32_bf16 v[90:93], v[154:157], v[174:177], v[90:93]
	v_mfma_f32_16x16x32_bf16 v[86:89], v[146:149], v[190:193], v[86:89]
	v_mfma_f32_16x16x32_bf16 v[82:85], v[154:157], v[190:193], v[82:85]
	v_mfma_f32_16x16x32_bf16 v[78:81], v[146:149], v[202:205], v[78:81]
	v_mfma_f32_16x16x32_bf16 v[74:77], v[154:157], v[202:205], v[74:77]
	v_mfma_f32_16x16x32_bf16 v[70:73], v[146:149], v[216:219], v[70:73]
	v_mfma_f32_16x16x32_bf16 v[66:69], v[154:157], v[216:219], v[66:69]
	v_mfma_f32_16x16x32_bf16 v[94:97], v[150:153], v[182:185], v[94:97]
	v_mfma_f32_16x16x32_bf16 v[90:93], v[158:161], v[182:185], v[90:93]
	v_mfma_f32_16x16x32_bf16 v[86:89], v[150:153], v[194:197], v[86:89]
	v_mfma_f32_16x16x32_bf16 v[82:85], v[158:161], v[194:197], v[82:85]
	v_mfma_f32_16x16x32_bf16 v[78:81], v[150:153], v[212:215], v[78:81]
	v_mfma_f32_16x16x32_bf16 v[74:77], v[158:161], v[212:215], v[74:77]
	v_mfma_f32_16x16x32_bf16 v[70:73], v[150:153], v[220:223], v[70:73]
	v_mfma_f32_16x16x32_bf16 v[66:69], v[158:161], v[220:223], v[66:69]
	s_nop 0
	s_barrier
	s_add_i32 s49, s77, s79
	v_lshl_add_u64 v[224:225], s[72:73], 0, v[164:165]
	s_mov_b32 m0, s49
	ds_read_b128 v[174:177], v200 offset:16384
	ds_read_b128 v[182:185], v200 offset:17408
	ds_read_b128 v[190:193], v200 offset:18432
	ds_read_b128 v[194:197], v200 offset:19456
	ds_read_b128 v[202:205], v200 offset:20480
	ds_read_b128 v[212:215], v200 offset:21504
	ds_read_b128 v[216:219], v200 offset:22528
	ds_read_b128 v[220:223], v200 offset:23552
	global_load_lds_dwordx4 v[224:225], off
	s_add_i32 m0, s49, 0x2000
	s_add_u32 vcc_lo, s72, 0x40000
	v_lshl_add_u64 v[226:227], s[72:73], 0, v[168:169]
	s_addc_u32 vcc_hi, s73, 0
	s_add_i32 s48, s48, s79
	global_load_lds_dwordx4 v[226:227], off
	v_lshl_add_u64 v[228:229], vcc, 0, v[164:165]
	s_mov_b32 m0, s48
	v_lshl_add_u64 v[230:231], s[74:75], 0, v[166:167]
	global_load_lds_dwordx4 v[228:229], off
	v_lshl_add_u64 v[228:229], vcc, 0, v[168:169]
	s_add_i32 m0, s48, 0x2000
	s_nop 0
	global_load_lds_dwordx4 v[228:229], off
	v_lshl_add_u64 v[228:229], s[74:75], 0, v[162:163]
	s_mov_b32 m0, s80
	s_nop 0
	global_load_lds_dwordx4 v[228:229], off
	s_mov_b32 m0, s81
	s_nop 0
	global_load_lds_dwordx4 v[230:231], off
	s_waitcnt vmcnt(8)
	s_waitcnt lgkmcnt(0)
	s_barrier
; #define PG8_STAGE(bufoff, gbase, voff) do { _Pragma("unroll") for (int _i = 0; _i < 2; ++_i) \
;         __builtin_amdgcn_global_load_lds((const unsigned*)((const char*)(gbase) + (voff)[_i]), (LAS unsigned*)(lds + (bufoff) + ldsw + _i * 8192), 16, 0, 0); } while (0)
; #define PG8_LDA(dst, b, h) do { _Pragma("unroll") for (int m = 0; m < 4; ++m) _Pragma("unroll") for (int k = 0; k < 2; ++k) dst[m][k] = *(const LAS bf16x8*)(lds + PG8_SA(b, h) + aoff + m * 2048 + k * 1024); } while (0)
; #define PG8_LDB(dst, b, h) do { _Pragma("unroll") for (int n = 0; n < 2; ++n) _Pragma("unroll") for (int k = 0; k < 2; ++k) dst[n][k] = *(const LAS bf16x8*)(lds + PG8_SB(b, h) + boff + n * 2048 + k * 1024); } while (0)
; #define PG8_MMA(ai, bj, At, Bt) do { __builtin_amdgcn_s_setprio(1); _Pragma("unroll") for (int m = 0; m < 4; ++m) _Pragma("unroll") for (int n = 0; n < 2; ++n) _Pragma("unroll") for (int k = 0; k < 2; ++k) \
;         acc[ai][bj][m][n] = __builtin_amdgcn_mfma_f32_16x16x32_bf16(Bt[n][k], At[m][k], acc[ai][bj][m][n], 0, 0, 0); __builtin_amdgcn_s_setprio(0); } while (0)
; #define PG8_WAIT_V(n) asm volatile("s_waitcnt vmcnt(" #n ")" ::: "memory")
; #define PG8_WAIT_L(n) asm volatile("s_waitcnt lgkmcnt(" #n ")" ::: "memory")
; #define PG8_BAR __builtin_amdgcn_s_barrier()
; #define PG8_SCHED __builtin_amdgcn_sched_barrier(0)
; template <class Epi, class Sched>
; DI void gemm_phase(LAS unsigned char* lds, const int K, const Sched& S, const Epi& E) {
;     ...
;             PG8_WAIT_V(8); PG8_WAIT_L(0); PG8_BAR; PG8_MMA(1, 0, At, B0); PG8_MMA(1, 1, At, B1); PG8_BAR; PG8_SCHED;
;             PG8_LDB(B0, 1, 0); PG8_LDB(B1, 1, 1); PG8_SCHED; PG8_LDA(At, 1, 0); PG8_STAGE(PG8_SA(0, 1), a2 + hstep, voffA);
;             PG8_WAIT_V(8); PG8_WAIT_L(0); PG8_BAR; PG8_MMA(0, 0, At, B0); PG8_MMA(0, 1, At, B1); PG8_BAR; PG8_SCHED;
	s_nop 0
	s_waitcnt lgkmcnt(0)
	v_mfma_f32_16x16x32_bf16 v[62:65], v[130:133], v[174:177], v[62:65]
	v_mfma_f32_16x16x32_bf16 v[58:61], v[138:141], v[174:177], v[58:61]
	v_mfma_f32_16x16x32_bf16 v[54:57], v[130:133], v[190:193], v[54:57]
	v_mfma_f32_16x16x32_bf16 v[50:53], v[138:141], v[190:193], v[50:53]
	v_mfma_f32_16x16x32_bf16 v[46:49], v[130:133], v[202:205], v[46:49]
	v_mfma_f32_16x16x32_bf16 v[42:45], v[138:141], v[202:205], v[42:45]
	v_mfma_f32_16x16x32_bf16 v[38:41], v[130:133], v[216:219], v[38:41]
	v_mfma_f32_16x16x32_bf16 v[34:37], v[138:141], v[216:219], v[34:37]
	v_mfma_f32_16x16x32_bf16 v[62:65], v[134:137], v[182:185], v[62:65]
	v_mfma_f32_16x16x32_bf16 v[58:61], v[142:145], v[182:185], v[58:61]
	v_mfma_f32_16x16x32_bf16 v[54:57], v[134:137], v[194:197], v[54:57]
	v_mfma_f32_16x16x32_bf16 v[50:53], v[142:145], v[194:197], v[50:53]
	v_mfma_f32_16x16x32_bf16 v[46:49], v[134:137], v[212:215], v[46:49]
	v_mfma_f32_16x16x32_bf16 v[42:45], v[142:145], v[212:215], v[42:45]
	v_mfma_f32_16x16x32_bf16 v[38:41], v[134:137], v[220:223], v[38:41]
	v_mfma_f32_16x16x32_bf16 v[34:37], v[142:145], v[220:223], v[34:37]
	s_nop 0
	s_nop 0
	v_mfma_f32_16x16x32_bf16 v[30:33], v[146:149], v[174:177], v[30:33]
	v_mfma_f32_16x16x32_bf16 v[26:29], v[154:157], v[174:177], v[26:29]
	v_mfma_f32_16x16x32_bf16 v[22:25], v[146:149], v[190:193], v[22:25]
	v_mfma_f32_16x16x32_bf16 v[18:21], v[154:157], v[190:193], v[18:21]
	v_mfma_f32_16x16x32_bf16 v[14:17], v[146:149], v[202:205], v[14:17]
	v_mfma_f32_16x16x32_bf16 v[10:13], v[154:157], v[202:205], v[10:13]
	v_mfma_f32_16x16x32_bf16 v[6:9], v[146:149], v[216:219], v[6:9]
	v_mfma_f32_16x16x32_bf16 v[2:5], v[154:157], v[216:219], v[2:5]
	v_mfma_f32_16x16x32_bf16 v[30:33], v[150:153], v[182:185], v[30:33]
	v_mfma_f32_16x16x32_bf16 v[26:29], v[158:161], v[182:185], v[26:29]
	v_mfma_f32_16x16x32_bf16 v[22:25], v[150:153], v[194:197], v[22:25]
	v_mfma_f32_16x16x32_bf16 v[18:21], v[158:161], v[194:197], v[18:21]
	v_mfma_f32_16x16x32_bf16 v[14:17], v[150:153], v[212:215], v[14:17]
	v_mfma_f32_16x16x32_bf16 v[10:13], v[158:161], v[212:215], v[10:13]
	v_mfma_f32_16x16x32_bf16 v[6:9], v[150:153], v[220:223], v[6:9]
	v_mfma_f32_16x16x32_bf16 v[2:5], v[158:161], v[220:223], v[2:5]
	s_nop 0
	s_barrier
	s_add_i32 s48, 0, 0x18000
	s_add_i32 s49, 0, 0x1c000
	v_add_u32_e32 v142, s48, v199
	v_add_u32_e32 v158, s49, v199
	ds_read_b128 v[130:133], v142
	ds_read_b128 v[134:137], v142 offset:1024
	ds_read_b128 v[138:141], v142 offset:2048
	ds_read_b128 v[142:145], v142 offset:3072
	ds_read_b128 v[146:149], v158
	ds_read_b128 v[150:153], v158 offset:1024
	ds_read_b128 v[154:157], v158 offset:2048
	ds_read_b128 v[158:161], v158 offset:3072
	s_add_u32 s74, s74, 0x40000
	s_addc_u32 s75, s75, 0
	s_mov_b32 m0, s85
	v_lshl_add_u64 v[232:233], s[74:75], 0, v[162:163]
	ds_read_b128 v[174:177], v200 offset:32768
	ds_read_b128 v[182:185], v200 offset:33792
	ds_read_b128 v[190:193], v200 offset:34816
	ds_read_b128 v[194:197], v200 offset:35840
	ds_read_b128 v[202:205], v200 offset:36864
	ds_read_b128 v[212:215], v200 offset:37888
	ds_read_b128 v[216:219], v200 offset:38912
	ds_read_b128 v[220:223], v200 offset:39936
	global_load_lds_dwordx4 v[232:233], off
	v_lshl_add_u64 v[232:233], s[74:75], 0, v[166:167]
	s_mov_b32 m0, s86
	s_nop 0
	global_load_lds_dwordx4 v[232:233], off
	s_waitcnt vmcnt(8)
	s_waitcnt lgkmcnt(0)
	s_barrier
	s_nop 0
	s_waitcnt lgkmcnt(0)
	v_mfma_f32_16x16x32_bf16 v[126:129], v[130:133], v[174:177], v[126:129]
	v_mfma_f32_16x16x32_bf16 v[122:125], v[138:141], v[174:177], v[122:125]
	v_mfma_f32_16x16x32_bf16 v[118:121], v[130:133], v[190:193], v[118:121]
	v_mfma_f32_16x16x32_bf16 v[114:117], v[138:141], v[190:193], v[114:117]
	v_mfma_f32_16x16x32_bf16 v[110:113], v[130:133], v[202:205], v[110:113]
	v_mfma_f32_16x16x32_bf16 v[106:109], v[138:141], v[202:205], v[106:109]
	v_mfma_f32_16x16x32_bf16 v[102:105], v[130:133], v[216:219], v[102:105]
	v_mfma_f32_16x16x32_bf16 v[98:101], v[138:141], v[216:219], v[98:101]
	v_mfma_f32_16x16x32_bf16 v[126:129], v[134:137], v[182:185], v[126:129]
	v_mfma_f32_16x16x32_bf16 v[122:125], v[142:145], v[182:185], v[122:125]
	v_mfma_f32_16x16x32_bf16 v[118:121], v[134:137], v[194:197], v[118:121]
	v_mfma_f32_16x16x32_bf16 v[114:117], v[142:145], v[194:197], v[114:117]
	v_mfma_f32_16x16x32_bf16 v[110:113], v[134:137], v[212:215], v[110:113]
	v_mfma_f32_16x16x32_bf16 v[106:109], v[142:145], v[212:215], v[106:109]
	v_mfma_f32_16x16x32_bf16 v[102:105], v[134:137], v[220:223], v[102:105]
	v_mfma_f32_16x16x32_bf16 v[98:101], v[142:145], v[220:223], v[98:101]
	s_nop 0
	s_nop 0
	v_mfma_f32_16x16x32_bf16 v[94:97], v[146:149], v[174:177], v[94:97]
	v_mfma_f32_16x16x32_bf16 v[90:93], v[154:157], v[174:177], v[90:93]
	v_mfma_f32_16x16x32_bf16 v[86:89], v[146:149], v[190:193], v[86:89]
	v_mfma_f32_16x16x32_bf16 v[82:85], v[154:157], v[190:193], v[82:85]
	v_mfma_f32_16x16x32_bf16 v[78:81], v[146:149], v[202:205], v[78:81]
	v_mfma_f32_16x16x32_bf16 v[74:77], v[154:157], v[202:205], v[74:77]
	v_mfma_f32_16x16x32_bf16 v[70:73], v[146:149], v[216:219], v[70:73]
	v_mfma_f32_16x16x32_bf16 v[66:69], v[154:157], v[216:219], v[66:69]
	v_mfma_f32_16x16x32_bf16 v[94:97], v[150:153], v[182:185], v[94:97]
	v_mfma_f32_16x16x32_bf16 v[90:93], v[158:161], v[182:185], v[90:93]
	v_mfma_f32_16x16x32_bf16 v[86:89], v[150:153], v[194:197], v[86:89]
	v_mfma_f32_16x16x32_bf16 v[82:85], v[158:161], v[194:197], v[82:85]
	v_mfma_f32_16x16x32_bf16 v[78:81], v[150:153], v[212:215], v[78:81]
	v_mfma_f32_16x16x32_bf16 v[74:77], v[158:161], v[212:215], v[74:77]
	v_mfma_f32_16x16x32_bf16 v[70:73], v[150:153], v[220:223], v[70:73]
	v_mfma_f32_16x16x32_bf16 v[66:69], v[158:161], v[220:223], v[66:69]
	s_nop 0
	s_barrier
; #define PG8_STAGE(bufoff, gbase, voff) do { _Pragma("unroll") for (int _i = 0; _i < 2; ++_i) \
;         __builtin_amdgcn_global_load_lds((const unsigned*)((const char*)(gbase) + (voff)[_i]), (LAS unsigned*)(lds + (bufoff) + ldsw + _i * 8192), 16, 0, 0); } while (0)
; #define PG8_LDA(dst, b, h) do { _Pragma("unroll") for (int m = 0; m < 4; ++m) _Pragma("unroll") for (int k = 0; k < 2; ++k) dst[m][k] = *(const LAS bf16x8*)(lds + PG8_SA(b, h) + aoff + m * 2048 + k * 1024); } while (0)
; #define PG8_MMA(ai, bj, At, Bt) do { __builtin_amdgcn_s_setprio(1); _Pragma("unroll") for (int m = 0; m < 4; ++m) _Pragma("unroll") for (int n = 0; n < 2; ++n) _Pragma("unroll") for (int k = 0; k < 2; ++k) \
;         acc[ai][bj][m][n] = __builtin_amdgcn_mfma_f32_16x16x32_bf16(Bt[n][k], At[m][k], acc[ai][bj][m][n], 0, 0, 0); __builtin_amdgcn_s_setprio(0); } while (0)
; #define PG8_WAIT_V(n) asm volatile("s_waitcnt vmcnt(" #n ")" ::: "memory")
; #define PG8_WAIT_L(n) asm volatile("s_waitcnt lgkmcnt(" #n ")" ::: "memory")
; #define PG8_BAR __builtin_amdgcn_s_barrier()
; #define PG8_SCHED __builtin_amdgcn_sched_barrier(0)
; template <class Epi, class Sched>
; DI void gemm_phase(LAS unsigned char* lds, const int K, const Sched& S, const Epi& E) {
;     ...
;             PG8_LDA(At, 1, 1); PG8_STAGE(PG8_SB(1, 0), b3, voffB); PG8_STAGE(PG8_SB(1, 1), b3 + hstep, voffB); PG8_STAGE(PG8_SA(1, 0), a3, voffA);
;             PG8_WAIT_V(8); PG8_WAIT_L(0); PG8_BAR; PG8_MMA(1, 0, At, B0); PG8_MMA(1, 1, At, B1); PG8_BAR; PG8_SCHED;
;         }
	s_add_i32 s48, s48, s79
	v_lshl_add_u64 v[224:225], v[224:225], 0, s[90:91]
	s_mov_b32 m0, s48
	ds_read_b128 v[174:177], v200 offset:49152
	ds_read_b128 v[182:185], v200 offset:50176
	ds_read_b128 v[190:193], v200 offset:51200
	ds_read_b128 v[194:197], v200 offset:52224
	ds_read_b128 v[202:205], v200 offset:53248
	ds_read_b128 v[212:215], v200 offset:54272
	ds_read_b128 v[216:219], v200 offset:55296
	ds_read_b128 v[220:223], v200 offset:56320
	global_load_lds_dwordx4 v[224:225], off
	s_add_i32 m0, s48, 0x2000
	s_add_u32 s72, s72, 0x40080
	v_lshl_add_u64 v[224:225], v[226:227], 0, s[90:91]
	s_addc_u32 s73, s73, 0
	s_add_i32 s48, s49, s79
	global_load_lds_dwordx4 v[224:225], off
	v_lshl_add_u64 v[224:225], s[72:73], 0, v[164:165]
	s_mov_b32 m0, s48
	s_nop 0
	global_load_lds_dwordx4 v[224:225], off
	v_lshl_add_u64 v[224:225], s[72:73], 0, v[168:169]
	s_add_i32 m0, s48, 0x2000
	s_nop 0
	global_load_lds_dwordx4 v[224:225], off
	v_lshl_add_u64 v[224:225], v[228:229], 0, s[90:91]
	s_mov_b32 m0, s94
	s_nop 0
	global_load_lds_dwordx4 v[224:225], off
	v_lshl_add_u64 v[224:225], v[230:231], 0, s[90:91]
	s_mov_b32 m0, s95
	s_nop 0
	global_load_lds_dwordx4 v[224:225], off
	s_waitcnt vmcnt(8)
	s_waitcnt lgkmcnt(0)
	s_barrier
	s_nop 0
	s_waitcnt lgkmcnt(0)
	v_mfma_f32_16x16x32_bf16 v[62:65], v[130:133], v[174:177], v[62:65]
	v_mfma_f32_16x16x32_bf16 v[58:61], v[138:141], v[174:177], v[58:61]
	v_mfma_f32_16x16x32_bf16 v[54:57], v[130:133], v[190:193], v[54:57]
	v_mfma_f32_16x16x32_bf16 v[50:53], v[138:141], v[190:193], v[50:53]
	v_mfma_f32_16x16x32_bf16 v[46:49], v[130:133], v[202:205], v[46:49]
	v_mfma_f32_16x16x32_bf16 v[42:45], v[138:141], v[202:205], v[42:45]
	v_mfma_f32_16x16x32_bf16 v[38:41], v[130:133], v[216:219], v[38:41]
	v_mfma_f32_16x16x32_bf16 v[34:37], v[138:141], v[216:219], v[34:37]
	v_mfma_f32_16x16x32_bf16 v[62:65], v[134:137], v[182:185], v[62:65]
	v_mfma_f32_16x16x32_bf16 v[58:61], v[142:145], v[182:185], v[58:61]
	v_mfma_f32_16x16x32_bf16 v[54:57], v[134:137], v[194:197], v[54:57]
	v_mfma_f32_16x16x32_bf16 v[50:53], v[142:145], v[194:197], v[50:53]
	v_mfma_f32_16x16x32_bf16 v[46:49], v[134:137], v[212:215], v[46:49]
	v_mfma_f32_16x16x32_bf16 v[42:45], v[142:145], v[212:215], v[42:45]
	v_mfma_f32_16x16x32_bf16 v[38:41], v[134:137], v[220:223], v[38:41]
	v_mfma_f32_16x16x32_bf16 v[34:37], v[142:145], v[220:223], v[34:37]
	s_nop 0
	s_nop 0
	v_mfma_f32_16x16x32_bf16 v[30:33], v[146:149], v[174:177], v[30:33]
	v_mfma_f32_16x16x32_bf16 v[26:29], v[154:157], v[174:177], v[26:29]
	v_mfma_f32_16x16x32_bf16 v[22:25], v[146:149], v[190:193], v[22:25]
	v_mfma_f32_16x16x32_bf16 v[18:21], v[154:157], v[190:193], v[18:21]
	v_mfma_f32_16x16x32_bf16 v[14:17], v[146:149], v[202:205], v[14:17]
	v_mfma_f32_16x16x32_bf16 v[10:13], v[154:157], v[202:205], v[10:13]
	v_mfma_f32_16x16x32_bf16 v[6:9], v[146:149], v[216:219], v[6:9]
	v_mfma_f32_16x16x32_bf16 v[2:5], v[154:157], v[216:219], v[2:5]
	v_mfma_f32_16x16x32_bf16 v[30:33], v[150:153], v[182:185], v[30:33]
	v_mfma_f32_16x16x32_bf16 v[26:29], v[158:161], v[182:185], v[26:29]
	v_mfma_f32_16x16x32_bf16 v[22:25], v[150:153], v[194:197], v[22:25]
	v_mfma_f32_16x16x32_bf16 v[18:21], v[158:161], v[194:197], v[18:21]
	v_mfma_f32_16x16x32_bf16 v[14:17], v[150:153], v[212:215], v[14:17]
	v_mfma_f32_16x16x32_bf16 v[10:13], v[158:161], v[212:215], v[10:13]
	v_mfma_f32_16x16x32_bf16 v[6:9], v[150:153], v[220:223], v[6:9]
	v_mfma_f32_16x16x32_bf16 v[2:5], v[158:161], v[220:223], v[2:5]
	s_nop 0
	s_barrier
	s_add_i32 s76, s76, 2
	s_add_u32 s65, s65, 0x100
	s_addc_u32 s67, s67, 0
	s_add_u32 s44, s44, 0x100
	s_addc_u32 s45, s45, 0
	s_cmp_gt_u32 s76, 13
	s_cbranch_scc0 .LBB0_784
	s_and_b64 vcc, exec, s[58:59]
	s_cbranch_vccz .LBB0_787
	s_barrier

; #define PG8_STAGE(bufoff, gbase, voff) do { _Pragma("unroll") for (int _i = 0; _i < 2; ++_i) \
;         __builtin_amdgcn_global_load_lds((const unsigned*)((const char*)(gbase) + (voff)[_i]), (LAS unsigned*)(lds + (bufoff) + ldsw + _i * 8192), 16, 0, 0); } while (0)
; #define PG8_LDA(dst, b, h) do { _Pragma("unroll") for (int m = 0; m < 4; ++m) _Pragma("unroll") for (int k = 0; k < 2; ++k) dst[m][k] = *(const LAS bf16x8*)(lds + PG8_SA(b, h) + aoff + m * 2048 + k * 1024); } while (0)
; #define PG8_LDB(dst, b, h) do { _Pragma("unroll") for (int n = 0; n < 2; ++n) _Pragma("unroll") for (int k = 0; k < 2; ++k) dst[n][k] = *(const LAS bf16x8*)(lds + PG8_SB(b, h) + boff + n * 2048 + k * 1024); } while (0)
; #define PG8_MMA(ai, bj, At, Bt) do { __builtin_amdgcn_s_setprio(1); _Pragma("unroll") for (int m = 0; m < 4; ++m) _Pragma("unroll") for (int n = 0; n < 2; ++n) _Pragma("unroll") for (int k = 0; k < 2; ++k) \
;         acc[ai][bj][m][n] = __builtin_amdgcn_mfma_f32_16x16x32_bf16(Bt[n][k], At[m][k], acc[ai][bj][m][n], 0, 0, 0); __builtin_amdgcn_s_setprio(0); } while (0)
; #define PG8_WAIT_V(n) asm volatile("s_waitcnt vmcnt(" #n ")" ::: "memory")
; #define PG8_WAIT_L(n) asm volatile("s_waitcnt lgkmcnt(" #n ")" ::: "memory")
; #define PG8_BAR __builtin_amdgcn_s_barrier()
; #define PG8_SCHED __builtin_amdgcn_sched_barrier(0)
; template <class Epi, class Sched>
; DI void gemm_phase(LAS unsigned char* lds, const int K, const Sched& S, const Epi& E) {
;     ...
;             const bool last = (t == nt - 2);
;             const char* a1 = cA + (size_t)(t + 1) * kstep;
;             const char* a2 = last ? nA : cA + (size_t)(t + 2) * kstep; const char* b2 = last ? nB : cB + (size_t)(t + 2) * kstep;
;             const char* a3 = a2 + kstep; const char* b3 = b2 + kstep;
;             PG8_LDB(B0, 0, 0); PG8_LDB(B1, 0, 1); PG8_SCHED; PG8_LDA(At, 0, 0); PG8_STAGE(PG8_SA(1, 1), a1 + hstep, voffA);
;             PG8_WAIT_V(8); PG8_WAIT_L(0); PG8_BAR; PG8_MMA(0, 0, At, B0); PG8_MMA(0, 1, At, B1); PG8_BAR; PG8_SCHED;
;             PG8_LDA(At, 0, 1); PG8_STAGE(PG8_SB(0, 0), b2, voffB); PG8_STAGE(PG8_SB(0, 1), b2 + hstep, voffB); PG8_STAGE(PG8_SA(0, 0), a2, voffA);
.LBB0_945:
	s_add_u32 s48, s62, 0xfffc0080
	s_addc_u32 s49, s63, -1
	s_add_i32 s84, 0, 0x10000
	s_cmp_eq_u32 s83, 12
	s_cselect_b32 s67, s59, s49
	s_cselect_b32 s66, s58, s48
	v_add_u32_e32 v145, s84, v143
	s_cselect_b32 s65, s61, s57
	s_cselect_b32 s64, s60, s55
	s_add_i32 s48, 0, 0x14000
	ds_read_b128 v[146:149], v145
	ds_read_b128 v[150:153], v145 offset:1024
	ds_read_b128 v[154:157], v145 offset:2048
	ds_read_b128 v[158:161], v145 offset:3072
	v_add_u32_e32 v145, s48, v143
	ds_read_b128 v[162:165], v145
	ds_read_b128 v[166:169], v145 offset:1024
	ds_read_b128 v[170:173], v145 offset:2048
	ds_read_b128 v[174:177], v145 offset:3072
	v_lshl_add_u64 v[224:225], s[62:63], 0, v[140:141]
	s_add_i32 m0, s53, 0xc000
	ds_read_b128 v[182:185], v144
	ds_read_b128 v[190:193], v144 offset:1024
	ds_read_b128 v[194:197], v144 offset:2048
	ds_read_b128 v[198:201], v144 offset:3072
	ds_read_b128 v[202:205], v144 offset:4096
	ds_read_b128 v[212:215], v144 offset:5120
	ds_read_b128 v[216:219], v144 offset:6144
	ds_read_b128 v[220:223], v144 offset:7168
	global_load_lds_dwordx4 v[224:225], off
	v_lshl_add_u64 v[224:225], s[62:63], 0, v[138:139]
	s_add_i32 m0, s53, 0xe000
	s_nop 0
	global_load_lds_dwordx4 v[224:225], off
	s_waitcnt vmcnt(8)
	s_waitcnt lgkmcnt(0)
	s_barrier
	s_nop 0
	s_waitcnt lgkmcnt(0)
	v_mfma_f32_16x16x32_bf16 v[126:129], v[146:149], v[182:185], v[126:129]
	v_mfma_f32_16x16x32_bf16 v[122:125], v[154:157], v[182:185], v[122:125]
	v_mfma_f32_16x16x32_bf16 v[118:121], v[146:149], v[194:197], v[118:121]
	v_mfma_f32_16x16x32_bf16 v[114:117], v[154:157], v[194:197], v[114:117]
	v_mfma_f32_16x16x32_bf16 v[102:105], v[146:149], v[202:205], v[102:105]
	v_mfma_f32_16x16x32_bf16 v[98:101], v[154:157], v[202:205], v[98:101]
	v_mfma_f32_16x16x32_bf16 v[86:89], v[146:149], v[216:219], v[86:89]
	v_mfma_f32_16x16x32_bf16 v[82:85], v[154:157], v[216:219], v[82:85]
	v_mfma_f32_16x16x32_bf16 v[126:129], v[150:153], v[190:193], v[126:129]
	v_mfma_f32_16x16x32_bf16 v[122:125], v[158:161], v[190:193], v[122:125]
	v_mfma_f32_16x16x32_bf16 v[118:121], v[150:153], v[198:201], v[118:121]
	v_mfma_f32_16x16x32_bf16 v[114:117], v[158:161], v[198:201], v[114:117]
	v_mfma_f32_16x16x32_bf16 v[102:105], v[150:153], v[212:215], v[102:105]
	v_mfma_f32_16x16x32_bf16 v[98:101], v[158:161], v[212:215], v[98:101]
	v_mfma_f32_16x16x32_bf16 v[86:89], v[150:153], v[220:223], v[86:89]
	v_mfma_f32_16x16x32_bf16 v[82:85], v[158:161], v[220:223], v[82:85]
	s_nop 0
	s_nop 0
	v_mfma_f32_16x16x32_bf16 v[110:113], v[162:165], v[182:185], v[110:113]
	v_mfma_f32_16x16x32_bf16 v[106:109], v[170:173], v[182:185], v[106:109]
	v_mfma_f32_16x16x32_bf16 v[94:97], v[162:165], v[194:197], v[94:97]
	v_mfma_f32_16x16x32_bf16 v[90:93], v[170:173], v[194:197], v[90:93]
	v_mfma_f32_16x16x32_bf16 v[78:81], v[162:165], v[202:205], v[78:81]
	v_mfma_f32_16x16x32_bf16 v[74:77], v[170:173], v[202:205], v[74:77]
	v_mfma_f32_16x16x32_bf16 v[70:73], v[162:165], v[216:219], v[70:73]
	v_mfma_f32_16x16x32_bf16 v[66:69], v[170:173], v[216:219], v[66:69]
	v_mfma_f32_16x16x32_bf16 v[110:113], v[166:169], v[190:193], v[110:113]
	v_mfma_f32_16x16x32_bf16 v[106:109], v[174:177], v[190:193], v[106:109]
	v_mfma_f32_16x16x32_bf16 v[94:97], v[166:169], v[198:201], v[94:97]
	v_mfma_f32_16x16x32_bf16 v[90:93], v[174:177], v[198:201], v[90:93]
	v_mfma_f32_16x16x32_bf16 v[78:81], v[166:169], v[212:215], v[78:81]
	v_mfma_f32_16x16x32_bf16 v[74:77], v[174:177], v[212:215], v[74:77]
	v_mfma_f32_16x16x32_bf16 v[70:73], v[166:169], v[220:223], v[70:73]
	v_mfma_f32_16x16x32_bf16 v[66:69], v[174:177], v[220:223], v[66:69]
	s_nop 0
	s_barrier
	s_add_i32 s49, s84, s71
	v_lshl_add_u64 v[224:225], s[64:65], 0, v[134:135]
	s_mov_b32 m0, s49
	ds_read_b128 v[182:185], v144 offset:16384
	ds_read_b128 v[190:193], v144 offset:17408
	ds_read_b128 v[194:197], v144 offset:18432
	ds_read_b128 v[198:201], v144 offset:19456
	ds_read_b128 v[202:205], v144 offset:20480
	ds_read_b128 v[212:215], v144 offset:21504
	ds_read_b128 v[216:219], v144 offset:22528
	ds_read_b128 v[220:223], v144 offset:23552
	global_load_lds_dwordx4 v[224:225], off
	s_add_i32 m0, s49, 0x2000
	s_add_u32 s84, s64, 0x40000
	v_lshl_add_u64 v[226:227], s[64:65], 0, v[130:131]
	s_addc_u32 s85, s65, 0
	s_add_i32 s48, s48, s71
	global_load_lds_dwordx4 v[226:227], off
	v_lshl_add_u64 v[228:229], s[84:85], 0, v[134:135]
	s_mov_b32 m0, s48
	v_lshl_add_u64 v[230:231], s[66:67], 0, v[132:133]
	global_load_lds_dwordx4 v[228:229], off
	v_lshl_add_u64 v[228:229], s[84:85], 0, v[130:131]
	s_add_i32 m0, s48, 0x2000
	s_nop 0
	global_load_lds_dwordx4 v[228:229], off
	v_lshl_add_u64 v[228:229], s[66:67], 0, v[136:137]
	s_mov_b32 m0, s53
	s_nop 0
	global_load_lds_dwordx4 v[228:229], off
	s_mov_b32 m0, s73
	s_nop 0
	global_load_lds_dwordx4 v[230:231], off
	s_waitcnt vmcnt(8)
	s_waitcnt lgkmcnt(0)
	s_barrier
; #define PG8_STAGE(bufoff, gbase, voff) do { _Pragma("unroll") for (int _i = 0; _i < 2; ++_i) \
;         __builtin_amdgcn_global_load_lds((const unsigned*)((const char*)(gbase) + (voff)[_i]), (LAS unsigned*)(lds + (bufoff) + ldsw + _i * 8192), 16, 0, 0); } while (0)
; #define PG8_LDA(dst, b, h) do { _Pragma("unroll") for (int m = 0; m < 4; ++m) _Pragma("unroll") for (int k = 0; k < 2; ++k) dst[m][k] = *(const LAS bf16x8*)(lds + PG8_SA(b, h) + aoff + m * 2048 + k * 1024); } while (0)
; #define PG8_LDB(dst, b, h) do { _Pragma("unroll") for (int n = 0; n < 2; ++n) _Pragma("unroll") for (int k = 0; k < 2; ++k) dst[n][k] = *(const LAS bf16x8*)(lds + PG8_SB(b, h) + boff + n * 2048 + k * 1024); } while (0)
; #define PG8_MMA(ai, bj, At, Bt) do { __builtin_amdgcn_s_setprio(1); _Pragma("unroll") for (int m = 0; m < 4; ++m) _Pragma("unroll") for (int n = 0; n < 2; ++n) _Pragma("unroll") for (int k = 0; k < 2; ++k) \
;         acc[ai][bj][m][n] = __builtin_amdgcn_mfma_f32_16x16x32_bf16(Bt[n][k], At[m][k], acc[ai][bj][m][n], 0, 0, 0); __builtin_amdgcn_s_setprio(0); } while (0)
; #define PG8_WAIT_V(n) asm volatile("s_waitcnt vmcnt(" #n ")" ::: "memory")
; #define PG8_WAIT_L(n) asm volatile("s_waitcnt lgkmcnt(" #n ")" ::: "memory")
; #define PG8_BAR __builtin_amdgcn_s_barrier()
; #define PG8_SCHED __builtin_amdgcn_sched_barrier(0)
; template <class Epi, class Sched>
; DI void gemm_phase(LAS unsigned char* lds, const int K, const Sched& S, const Epi& E) {
;     ...
;             PG8_WAIT_V(8); PG8_WAIT_L(0); PG8_BAR; PG8_MMA(1, 0, At, B0); PG8_MMA(1, 1, At, B1); PG8_BAR; PG8_SCHED;
;             PG8_LDB(B0, 1, 0); PG8_LDB(B1, 1, 1); PG8_SCHED; PG8_LDA(At, 1, 0); PG8_STAGE(PG8_SA(0, 1), a2 + hstep, voffA);
;             PG8_WAIT_V(8); PG8_WAIT_L(0); PG8_BAR; PG8_MMA(0, 0, At, B0); PG8_MMA(0, 1, At, B1); PG8_BAR; PG8_SCHED;
	s_nop 0
	s_waitcnt lgkmcnt(0)
	v_mfma_f32_16x16x32_bf16 v[62:65], v[146:149], v[182:185], v[62:65]
	v_mfma_f32_16x16x32_bf16 v[58:61], v[154:157], v[182:185], v[58:61]
	v_mfma_f32_16x16x32_bf16 v[54:57], v[146:149], v[194:197], v[54:57]
	v_mfma_f32_16x16x32_bf16 v[50:53], v[154:157], v[194:197], v[50:53]
	v_mfma_f32_16x16x32_bf16 v[38:41], v[146:149], v[202:205], v[38:41]
	v_mfma_f32_16x16x32_bf16 v[34:37], v[154:157], v[202:205], v[34:37]
	v_mfma_f32_16x16x32_bf16 v[22:25], v[146:149], v[216:219], v[22:25]
	v_mfma_f32_16x16x32_bf16 v[18:21], v[154:157], v[216:219], v[18:21]
	v_mfma_f32_16x16x32_bf16 v[62:65], v[150:153], v[190:193], v[62:65]
	v_mfma_f32_16x16x32_bf16 v[58:61], v[158:161], v[190:193], v[58:61]
	v_mfma_f32_16x16x32_bf16 v[54:57], v[150:153], v[198:201], v[54:57]
	v_mfma_f32_16x16x32_bf16 v[50:53], v[158:161], v[198:201], v[50:53]
	v_mfma_f32_16x16x32_bf16 v[38:41], v[150:153], v[212:215], v[38:41]
	v_mfma_f32_16x16x32_bf16 v[34:37], v[158:161], v[212:215], v[34:37]
	v_mfma_f32_16x16x32_bf16 v[22:25], v[150:153], v[220:223], v[22:25]
	v_mfma_f32_16x16x32_bf16 v[18:21], v[158:161], v[220:223], v[18:21]
	s_nop 0
	s_nop 0
	v_mfma_f32_16x16x32_bf16 v[46:49], v[162:165], v[182:185], v[46:49]
	v_mfma_f32_16x16x32_bf16 v[42:45], v[170:173], v[182:185], v[42:45]
	v_mfma_f32_16x16x32_bf16 v[30:33], v[162:165], v[194:197], v[30:33]
	v_mfma_f32_16x16x32_bf16 v[26:29], v[170:173], v[194:197], v[26:29]
	v_mfma_f32_16x16x32_bf16 v[14:17], v[162:165], v[202:205], v[14:17]
	v_mfma_f32_16x16x32_bf16 v[10:13], v[170:173], v[202:205], v[10:13]
	v_mfma_f32_16x16x32_bf16 v[6:9], v[162:165], v[216:219], v[6:9]
	v_mfma_f32_16x16x32_bf16 v[2:5], v[170:173], v[216:219], v[2:5]
	v_mfma_f32_16x16x32_bf16 v[46:49], v[166:169], v[190:193], v[46:49]
	v_mfma_f32_16x16x32_bf16 v[42:45], v[174:177], v[190:193], v[42:45]
	v_mfma_f32_16x16x32_bf16 v[30:33], v[166:169], v[198:201], v[30:33]
	v_mfma_f32_16x16x32_bf16 v[26:29], v[174:177], v[198:201], v[26:29]
	v_mfma_f32_16x16x32_bf16 v[14:17], v[166:169], v[212:215], v[14:17]
	v_mfma_f32_16x16x32_bf16 v[10:13], v[174:177], v[212:215], v[10:13]
	v_mfma_f32_16x16x32_bf16 v[6:9], v[166:169], v[220:223], v[6:9]
	v_mfma_f32_16x16x32_bf16 v[2:5], v[174:177], v[220:223], v[2:5]
	s_nop 0
	s_barrier
	s_add_i32 s48, 0, 0x18000
	v_add_u32_e32 v145, s48, v143
	s_add_i32 s49, 0, 0x1c000
	ds_read_b128 v[146:149], v145
	ds_read_b128 v[150:153], v145 offset:1024
	ds_read_b128 v[154:157], v145 offset:2048
	ds_read_b128 v[158:161], v145 offset:3072
	v_add_u32_e32 v145, s49, v143
	ds_read_b128 v[162:165], v145
	ds_read_b128 v[166:169], v145 offset:1024
	ds_read_b128 v[170:173], v145 offset:2048
	ds_read_b128 v[174:177], v145 offset:3072
	s_add_u32 s66, s66, 0x40000
	s_addc_u32 s67, s67, 0
	s_mov_b32 m0, s74
	v_lshl_add_u64 v[232:233], s[66:67], 0, v[136:137]
	ds_read_b128 v[182:185], v144 offset:32768
	ds_read_b128 v[190:193], v144 offset:33792
	ds_read_b128 v[194:197], v144 offset:34816
	ds_read_b128 v[198:201], v144 offset:35840
	ds_read_b128 v[202:205], v144 offset:36864
	ds_read_b128 v[212:215], v144 offset:37888
	ds_read_b128 v[216:219], v144 offset:38912
	ds_read_b128 v[220:223], v144 offset:39936
	global_load_lds_dwordx4 v[232:233], off
	v_lshl_add_u64 v[232:233], s[66:67], 0, v[132:133]
	s_mov_b32 m0, s75
	s_nop 0
	global_load_lds_dwordx4 v[232:233], off
	s_waitcnt vmcnt(8)
	s_waitcnt lgkmcnt(0)
	s_barrier
	s_nop 0
	s_waitcnt lgkmcnt(0)
	v_mfma_f32_16x16x32_bf16 v[126:129], v[146:149], v[182:185], v[126:129]
	v_mfma_f32_16x16x32_bf16 v[122:125], v[154:157], v[182:185], v[122:125]
	v_mfma_f32_16x16x32_bf16 v[118:121], v[146:149], v[194:197], v[118:121]
	v_mfma_f32_16x16x32_bf16 v[114:117], v[154:157], v[194:197], v[114:117]
	v_mfma_f32_16x16x32_bf16 v[102:105], v[146:149], v[202:205], v[102:105]
	v_mfma_f32_16x16x32_bf16 v[98:101], v[154:157], v[202:205], v[98:101]
	v_mfma_f32_16x16x32_bf16 v[86:89], v[146:149], v[216:219], v[86:89]
	v_mfma_f32_16x16x32_bf16 v[82:85], v[154:157], v[216:219], v[82:85]
	v_mfma_f32_16x16x32_bf16 v[126:129], v[150:153], v[190:193], v[126:129]
	v_mfma_f32_16x16x32_bf16 v[122:125], v[158:161], v[190:193], v[122:125]
	v_mfma_f32_16x16x32_bf16 v[118:121], v[150:153], v[198:201], v[118:121]
	v_mfma_f32_16x16x32_bf16 v[114:117], v[158:161], v[198:201], v[114:117]
	v_mfma_f32_16x16x32_bf16 v[102:105], v[150:153], v[212:215], v[102:105]
	v_mfma_f32_16x16x32_bf16 v[98:101], v[158:161], v[212:215], v[98:101]
	v_mfma_f32_16x16x32_bf16 v[86:89], v[150:153], v[220:223], v[86:89]
	v_mfma_f32_16x16x32_bf16 v[82:85], v[158:161], v[220:223], v[82:85]
	s_nop 0
	s_nop 0
	v_mfma_f32_16x16x32_bf16 v[110:113], v[162:165], v[182:185], v[110:113]
	v_mfma_f32_16x16x32_bf16 v[106:109], v[170:173], v[182:185], v[106:109]
	v_mfma_f32_16x16x32_bf16 v[94:97], v[162:165], v[194:197], v[94:97]
	v_mfma_f32_16x16x32_bf16 v[90:93], v[170:173], v[194:197], v[90:93]
	v_mfma_f32_16x16x32_bf16 v[78:81], v[162:165], v[202:205], v[78:81]
	v_mfma_f32_16x16x32_bf16 v[74:77], v[170:173], v[202:205], v[74:77]
	v_mfma_f32_16x16x32_bf16 v[70:73], v[162:165], v[216:219], v[70:73]
	v_mfma_f32_16x16x32_bf16 v[66:69], v[170:173], v[216:219], v[66:69]
	v_mfma_f32_16x16x32_bf16 v[110:113], v[166:169], v[190:193], v[110:113]
	v_mfma_f32_16x16x32_bf16 v[106:109], v[174:177], v[190:193], v[106:109]
	v_mfma_f32_16x16x32_bf16 v[94:97], v[166:169], v[198:201], v[94:97]
	v_mfma_f32_16x16x32_bf16 v[90:93], v[174:177], v[198:201], v[90:93]
	v_mfma_f32_16x16x32_bf16 v[78:81], v[166:169], v[212:215], v[78:81]
	v_mfma_f32_16x16x32_bf16 v[74:77], v[174:177], v[212:215], v[74:77]
	v_mfma_f32_16x16x32_bf16 v[70:73], v[166:169], v[220:223], v[70:73]
	v_mfma_f32_16x16x32_bf16 v[66:69], v[174:177], v[220:223], v[66:69]
	s_nop 0
	s_barrier
; #define PG8_STAGE(bufoff, gbase, voff) do { _Pragma("unroll") for (int _i = 0; _i < 2; ++_i) \
;         __builtin_amdgcn_global_load_lds((const unsigned*)((const char*)(gbase) + (voff)[_i]), (LAS unsigned*)(lds + (bufoff) + ldsw + _i * 8192), 16, 0, 0); } while (0)
; #define PG8_LDA(dst, b, h) do { _Pragma("unroll") for (int m = 0; m < 4; ++m) _Pragma("unroll") for (int k = 0; k < 2; ++k) dst[m][k] = *(const LAS bf16x8*)(lds + PG8_SA(b, h) + aoff + m * 2048 + k * 1024); } while (0)
; #define PG8_MMA(ai, bj, At, Bt) do { __builtin_amdgcn_s_setprio(1); _Pragma("unroll") for (int m = 0; m < 4; ++m) _Pragma("unroll") for (int n = 0; n < 2; ++n) _Pragma("unroll") for (int k = 0; k < 2; ++k) \
;         acc[ai][bj][m][n] = __builtin_amdgcn_mfma_f32_16x16x32_bf16(Bt[n][k], At[m][k], acc[ai][bj][m][n], 0, 0, 0); __builtin_amdgcn_s_setprio(0); } while (0)
; #define PG8_WAIT_V(n) asm volatile("s_waitcnt vmcnt(" #n ")" ::: "memory")
; #define PG8_WAIT_L(n) asm volatile("s_waitcnt lgkmcnt(" #n ")" ::: "memory")
; #define PG8_BAR __builtin_amdgcn_s_barrier()
; #define PG8_SCHED __builtin_amdgcn_sched_barrier(0)
; template <class Epi, class Sched>
; DI void gemm_phase(LAS unsigned char* lds, const int K, const Sched& S, const Epi& E) {
;     ...
;             PG8_LDA(At, 1, 1); PG8_STAGE(PG8_SB(1, 0), b3, voffB); PG8_STAGE(PG8_SB(1, 1), b3 + hstep, voffB); PG8_STAGE(PG8_SA(1, 0), a3, voffA);
;             PG8_WAIT_V(8); PG8_WAIT_L(0); PG8_BAR; PG8_MMA(1, 0, At, B0); PG8_MMA(1, 1, At, B1); PG8_BAR; PG8_SCHED;
;         }
	s_add_i32 s48, s48, s71
	v_lshl_add_u64 v[224:225], v[224:225], 0, s[90:91]
	s_mov_b32 m0, s48
	ds_read_b128 v[182:185], v144 offset:49152
	ds_read_b128 v[190:193], v144 offset:50176
	ds_read_b128 v[194:197], v144 offset:51200
	ds_read_b128 v[198:201], v144 offset:52224
	ds_read_b128 v[202:205], v144 offset:53248
	ds_read_b128 v[212:215], v144 offset:54272
	ds_read_b128 v[216:219], v144 offset:55296
	ds_read_b128 v[220:223], v144 offset:56320
	global_load_lds_dwordx4 v[224:225], off
	s_add_i32 m0, s48, 0x2000
	s_add_u32 s64, s64, 0x40080
	v_lshl_add_u64 v[224:225], v[226:227], 0, s[90:91]
	s_addc_u32 s65, s65, 0
	s_add_i32 s48, s49, s71
	global_load_lds_dwordx4 v[224:225], off
	v_lshl_add_u64 v[224:225], s[64:65], 0, v[134:135]
	s_mov_b32 m0, s48
	s_nop 0
	global_load_lds_dwordx4 v[224:225], off
	v_lshl_add_u64 v[224:225], s[64:65], 0, v[130:131]
	s_add_i32 m0, s48, 0x2000
	s_nop 0
	global_load_lds_dwordx4 v[224:225], off
	v_lshl_add_u64 v[224:225], v[228:229], 0, s[90:91]
	s_mov_b32 m0, s78
	s_nop 0
	global_load_lds_dwordx4 v[224:225], off
	v_lshl_add_u64 v[224:225], v[230:231], 0, s[90:91]
	s_mov_b32 m0, s79
	s_nop 0
	global_load_lds_dwordx4 v[224:225], off
	s_waitcnt vmcnt(8)
	s_waitcnt lgkmcnt(0)
	s_barrier
	s_nop 0
	s_waitcnt lgkmcnt(0)
	v_mfma_f32_16x16x32_bf16 v[62:65], v[146:149], v[182:185], v[62:65]
	v_mfma_f32_16x16x32_bf16 v[58:61], v[154:157], v[182:185], v[58:61]
	v_mfma_f32_16x16x32_bf16 v[54:57], v[146:149], v[194:197], v[54:57]
	v_mfma_f32_16x16x32_bf16 v[50:53], v[154:157], v[194:197], v[50:53]
	v_mfma_f32_16x16x32_bf16 v[38:41], v[146:149], v[202:205], v[38:41]
	v_mfma_f32_16x16x32_bf16 v[34:37], v[154:157], v[202:205], v[34:37]
	v_mfma_f32_16x16x32_bf16 v[22:25], v[146:149], v[216:219], v[22:25]
	v_mfma_f32_16x16x32_bf16 v[18:21], v[154:157], v[216:219], v[18:21]
	v_mfma_f32_16x16x32_bf16 v[62:65], v[150:153], v[190:193], v[62:65]
	v_mfma_f32_16x16x32_bf16 v[58:61], v[158:161], v[190:193], v[58:61]
	v_mfma_f32_16x16x32_bf16 v[54:57], v[150:153], v[198:201], v[54:57]
	v_mfma_f32_16x16x32_bf16 v[50:53], v[158:161], v[198:201], v[50:53]
	v_mfma_f32_16x16x32_bf16 v[38:41], v[150:153], v[212:215], v[38:41]
	v_mfma_f32_16x16x32_bf16 v[34:37], v[158:161], v[212:215], v[34:37]
	v_mfma_f32_16x16x32_bf16 v[22:25], v[150:153], v[220:223], v[22:25]
	v_mfma_f32_16x16x32_bf16 v[18:21], v[158:161], v[220:223], v[18:21]
	s_nop 0
	s_nop 0
	v_mfma_f32_16x16x32_bf16 v[46:49], v[162:165], v[182:185], v[46:49]
	v_mfma_f32_16x16x32_bf16 v[42:45], v[170:173], v[182:185], v[42:45]
	v_mfma_f32_16x16x32_bf16 v[30:33], v[162:165], v[194:197], v[30:33]
	v_mfma_f32_16x16x32_bf16 v[26:29], v[170:173], v[194:197], v[26:29]
	v_mfma_f32_16x16x32_bf16 v[14:17], v[162:165], v[202:205], v[14:17]
	v_mfma_f32_16x16x32_bf16 v[10:13], v[170:173], v[202:205], v[10:13]
	v_mfma_f32_16x16x32_bf16 v[6:9], v[162:165], v[216:219], v[6:9]
	v_mfma_f32_16x16x32_bf16 v[2:5], v[170:173], v[216:219], v[2:5]
	v_mfma_f32_16x16x32_bf16 v[46:49], v[166:169], v[190:193], v[46:49]
	v_mfma_f32_16x16x32_bf16 v[42:45], v[174:177], v[190:193], v[42:45]
	v_mfma_f32_16x16x32_bf16 v[30:33], v[166:169], v[198:201], v[30:33]
	v_mfma_f32_16x16x32_bf16 v[26:29], v[174:177], v[198:201], v[26:29]
	v_mfma_f32_16x16x32_bf16 v[14:17], v[166:169], v[212:215], v[14:17]
	v_mfma_f32_16x16x32_bf16 v[10:13], v[174:177], v[212:215], v[10:13]
	v_mfma_f32_16x16x32_bf16 v[6:9], v[166:169], v[220:223], v[6:9]
	v_mfma_f32_16x16x32_bf16 v[2:5], v[174:177], v[220:223], v[2:5]
	s_nop 0
	s_barrier
	s_add_i32 s83, s83, 2
	s_add_u32 s55, s55, 0x100
	s_addc_u32 s57, s57, 0
	s_add_u32 s62, s62, 0x100
	s_addc_u32 s63, s63, 0
	s_cmp_gt_u32 s83, 13
	s_cbranch_scc0 .LBB0_945
	s_and_b64 vcc, exec, s[50:51]
	s_cbranch_vccz .LBB0_948
	s_barrier

; #define PG8_STAGE(bufoff, gbase, voff) do { _Pragma("unroll") for (int _i = 0; _i < 2; ++_i) \
;         __builtin_amdgcn_global_load_lds((const unsigned*)((const char*)(gbase) + (voff)[_i]), (LAS unsigned*)(lds + (bufoff) + ldsw + _i * 8192), 16, 0, 0); } while (0)
; #define PG8_LDA(dst, b, h) do { _Pragma("unroll") for (int m = 0; m < 4; ++m) _Pragma("unroll") for (int k = 0; k < 2; ++k) dst[m][k] = *(const LAS bf16x8*)(lds + PG8_SA(b, h) + aoff + m * 2048 + k * 1024); } while (0)
; #define PG8_LDB(dst, b, h) do { _Pragma("unroll") for (int n = 0; n < 2; ++n) _Pragma("unroll") for (int k = 0; k < 2; ++k) dst[n][k] = *(const LAS bf16x8*)(lds + PG8_SB(b, h) + boff + n * 2048 + k * 1024); } while (0)
; #define PG8_MMA(ai, bj, At, Bt) do { __builtin_amdgcn_s_setprio(1); _Pragma("unroll") for (int m = 0; m < 4; ++m) _Pragma("unroll") for (int n = 0; n < 2; ++n) _Pragma("unroll") for (int k = 0; k < 2; ++k) \
;         acc[ai][bj][m][n] = __builtin_amdgcn_mfma_f32_16x16x32_bf16(Bt[n][k], At[m][k], acc[ai][bj][m][n], 0, 0, 0); __builtin_amdgcn_s_setprio(0); } while (0)
; #define PG8_WAIT_V(n) asm volatile("s_waitcnt vmcnt(" #n ")" ::: "memory")
; #define PG8_WAIT_L(n) asm volatile("s_waitcnt lgkmcnt(" #n ")" ::: "memory")
; #define PG8_BAR __builtin_amdgcn_s_barrier()
; #define PG8_SCHED __builtin_amdgcn_sched_barrier(0)
; template <class Epi, class Sched>
; DI void gemm_phase(LAS unsigned char* lds, const int K, const Sched& S, const Epi& E) {
;     ...
;             const bool last = (t == nt - 2);
;             const char* a1 = cA + (size_t)(t + 1) * kstep;
;             const char* a2 = last ? nA : cA + (size_t)(t + 2) * kstep; const char* b2 = last ? nB : cB + (size_t)(t + 2) * kstep;
;             const char* a3 = a2 + kstep; const char* b3 = b2 + kstep;
;             PG8_LDB(B0, 0, 0); PG8_LDB(B1, 0, 1); PG8_SCHED; PG8_LDA(At, 0, 0); PG8_STAGE(PG8_SA(1, 1), a1 + hstep, voffA);
;             PG8_WAIT_V(8); PG8_WAIT_L(0); PG8_BAR; PG8_MMA(0, 0, At, B0); PG8_MMA(0, 1, At, B1); PG8_BAR; PG8_SCHED;
;             PG8_LDA(At, 0, 1); PG8_STAGE(PG8_SB(0, 0), b2, voffB); PG8_STAGE(PG8_SB(0, 1), b2 + hstep, voffB); PG8_STAGE(PG8_SA(0, 0), a2, voffA);
.LBB0_1086:
	s_add_u32 s48, s68, 0xfffc0080
	s_addc_u32 s49, s69, -1
	s_add_i32 vcc_hi, 0, 0x10000
	s_cmp_eq_u32 vcc_lo, 12
	s_cselect_b32 s73, s65, s49
	s_cselect_b32 s72, s64, s48
	v_add_u32_e32 v145, vcc_hi, v143
	s_cselect_b32 s71, s67, s63
	s_cselect_b32 s70, s66, s61
	s_add_i32 s94, 0, 0x14000
	ds_read_b128 v[146:149], v145
	ds_read_b128 v[150:153], v145 offset:1024
	ds_read_b128 v[154:157], v145 offset:2048
	ds_read_b128 v[158:161], v145 offset:3072
	v_add_u32_e32 v145, s94, v143
	ds_read_b128 v[162:165], v145
	ds_read_b128 v[166:169], v145 offset:1024
	ds_read_b128 v[170:173], v145 offset:2048
	ds_read_b128 v[174:177], v145 offset:3072
	v_lshl_add_u64 v[224:225], s[68:69], 0, v[140:141]
	s_add_i32 m0, s59, 0xc000
	ds_read_b128 v[182:185], v144
	ds_read_b128 v[190:193], v144 offset:1024
	ds_read_b128 v[194:197], v144 offset:2048
	ds_read_b128 v[198:201], v144 offset:3072
	ds_read_b128 v[202:205], v144 offset:4096
	ds_read_b128 v[212:215], v144 offset:5120
	ds_read_b128 v[216:219], v144 offset:6144
	ds_read_b128 v[220:223], v144 offset:7168
	global_load_lds_dwordx4 v[224:225], off
	v_lshl_add_u64 v[224:225], s[68:69], 0, v[138:139]
	s_add_i32 m0, s59, 0xe000
	s_nop 0
	global_load_lds_dwordx4 v[224:225], off
	s_waitcnt vmcnt(8)
	s_waitcnt lgkmcnt(0)
	s_barrier
	s_nop 0
	s_waitcnt lgkmcnt(0)
	v_mfma_f32_16x16x32_bf16 v[126:129], v[146:149], v[182:185], v[126:129]
	v_mfma_f32_16x16x32_bf16 v[122:125], v[154:157], v[182:185], v[122:125]
	v_mfma_f32_16x16x32_bf16 v[118:121], v[146:149], v[194:197], v[118:121]
	v_mfma_f32_16x16x32_bf16 v[114:117], v[154:157], v[194:197], v[114:117]
	v_mfma_f32_16x16x32_bf16 v[102:105], v[146:149], v[202:205], v[102:105]
	v_mfma_f32_16x16x32_bf16 v[98:101], v[154:157], v[202:205], v[98:101]
	v_mfma_f32_16x16x32_bf16 v[86:89], v[146:149], v[216:219], v[86:89]
	v_mfma_f32_16x16x32_bf16 v[82:85], v[154:157], v[216:219], v[82:85]
	v_mfma_f32_16x16x32_bf16 v[126:129], v[150:153], v[190:193], v[126:129]
	v_mfma_f32_16x16x32_bf16 v[122:125], v[158:161], v[190:193], v[122:125]
	v_mfma_f32_16x16x32_bf16 v[118:121], v[150:153], v[198:201], v[118:121]
	v_mfma_f32_16x16x32_bf16 v[114:117], v[158:161], v[198:201], v[114:117]
	v_mfma_f32_16x16x32_bf16 v[102:105], v[150:153], v[212:215], v[102:105]
	v_mfma_f32_16x16x32_bf16 v[98:101], v[158:161], v[212:215], v[98:101]
	v_mfma_f32_16x16x32_bf16 v[86:89], v[150:153], v[220:223], v[86:89]
	v_mfma_f32_16x16x32_bf16 v[82:85], v[158:161], v[220:223], v[82:85]
	s_nop 0
	s_nop 0
	v_mfma_f32_16x16x32_bf16 v[110:113], v[162:165], v[182:185], v[110:113]
	v_mfma_f32_16x16x32_bf16 v[106:109], v[170:173], v[182:185], v[106:109]
	v_mfma_f32_16x16x32_bf16 v[94:97], v[162:165], v[194:197], v[94:97]
	v_mfma_f32_16x16x32_bf16 v[90:93], v[170:173], v[194:197], v[90:93]
	v_mfma_f32_16x16x32_bf16 v[78:81], v[162:165], v[202:205], v[78:81]
	v_mfma_f32_16x16x32_bf16 v[74:77], v[170:173], v[202:205], v[74:77]
	v_mfma_f32_16x16x32_bf16 v[70:73], v[162:165], v[216:219], v[70:73]
	v_mfma_f32_16x16x32_bf16 v[66:69], v[170:173], v[216:219], v[66:69]
	v_mfma_f32_16x16x32_bf16 v[110:113], v[166:169], v[190:193], v[110:113]
	v_mfma_f32_16x16x32_bf16 v[106:109], v[174:177], v[190:193], v[106:109]
	v_mfma_f32_16x16x32_bf16 v[94:97], v[166:169], v[198:201], v[94:97]
	v_mfma_f32_16x16x32_bf16 v[90:93], v[174:177], v[198:201], v[90:93]
	v_mfma_f32_16x16x32_bf16 v[78:81], v[166:169], v[212:215], v[78:81]
	v_mfma_f32_16x16x32_bf16 v[74:77], v[174:177], v[212:215], v[74:77]
	v_mfma_f32_16x16x32_bf16 v[70:73], v[166:169], v[220:223], v[70:73]
	v_mfma_f32_16x16x32_bf16 v[66:69], v[174:177], v[220:223], v[66:69]
	s_nop 0
	s_barrier
	s_add_i32 s48, vcc_hi, s78
	v_lshl_add_u64 v[224:225], s[70:71], 0, v[134:135]
	s_mov_b32 m0, s48
	ds_read_b128 v[182:185], v144 offset:16384
	ds_read_b128 v[190:193], v144 offset:17408
	ds_read_b128 v[194:197], v144 offset:18432
	ds_read_b128 v[198:201], v144 offset:19456
	ds_read_b128 v[202:205], v144 offset:20480
	ds_read_b128 v[212:215], v144 offset:21504
	ds_read_b128 v[216:219], v144 offset:22528
	ds_read_b128 v[220:223], v144 offset:23552
	global_load_lds_dwordx4 v[224:225], off
	s_add_i32 m0, s48, 0x2000
	s_add_u32 s48, s70, 0x40000
	v_lshl_add_u64 v[226:227], s[70:71], 0, v[130:131]
	s_addc_u32 s49, s71, 0
	s_add_i32 s94, s94, s78
	global_load_lds_dwordx4 v[226:227], off
	v_lshl_add_u64 v[228:229], s[48:49], 0, v[134:135]
	s_mov_b32 m0, s94
	v_lshl_add_u64 v[230:231], s[72:73], 0, v[132:133]
	global_load_lds_dwordx4 v[228:229], off
	v_lshl_add_u64 v[228:229], s[48:49], 0, v[130:131]
	s_add_i32 m0, s94, 0x2000
	s_nop 0
	global_load_lds_dwordx4 v[228:229], off
	v_lshl_add_u64 v[228:229], s[72:73], 0, v[136:137]
	s_mov_b32 m0, s59
	s_nop 0
	global_load_lds_dwordx4 v[228:229], off
	s_mov_b32 m0, s80
	s_nop 0
	global_load_lds_dwordx4 v[230:231], off
	s_waitcnt vmcnt(8)
	s_waitcnt lgkmcnt(0)
	s_barrier
; #define PG8_STAGE(bufoff, gbase, voff) do { _Pragma("unroll") for (int _i = 0; _i < 2; ++_i) \
;         __builtin_amdgcn_global_load_lds((const unsigned*)((const char*)(gbase) + (voff)[_i]), (LAS unsigned*)(lds + (bufoff) + ldsw + _i * 8192), 16, 0, 0); } while (0)
; #define PG8_LDA(dst, b, h) do { _Pragma("unroll") for (int m = 0; m < 4; ++m) _Pragma("unroll") for (int k = 0; k < 2; ++k) dst[m][k] = *(const LAS bf16x8*)(lds + PG8_SA(b, h) + aoff + m * 2048 + k * 1024); } while (0)
; #define PG8_LDB(dst, b, h) do { _Pragma("unroll") for (int n = 0; n < 2; ++n) _Pragma("unroll") for (int k = 0; k < 2; ++k) dst[n][k] = *(const LAS bf16x8*)(lds + PG8_SB(b, h) + boff + n * 2048 + k * 1024); } while (0)
; #define PG8_MMA(ai, bj, At, Bt) do { __builtin_amdgcn_s_setprio(1); _Pragma("unroll") for (int m = 0; m < 4; ++m) _Pragma("unroll") for (int n = 0; n < 2; ++n) _Pragma("unroll") for (int k = 0; k < 2; ++k) \
;         acc[ai][bj][m][n] = __builtin_amdgcn_mfma_f32_16x16x32_bf16(Bt[n][k], At[m][k], acc[ai][bj][m][n], 0, 0, 0); __builtin_amdgcn_s_setprio(0); } while (0)
; #define PG8_WAIT_V(n) asm volatile("s_waitcnt vmcnt(" #n ")" ::: "memory")
; #define PG8_WAIT_L(n) asm volatile("s_waitcnt lgkmcnt(" #n ")" ::: "memory")
; #define PG8_BAR __builtin_amdgcn_s_barrier()
; #define PG8_SCHED __builtin_amdgcn_sched_barrier(0)
; template <class Epi, class Sched>
; DI void gemm_phase(LAS unsigned char* lds, const int K, const Sched& S, const Epi& E) {
;     ...
;             PG8_WAIT_V(8); PG8_WAIT_L(0); PG8_BAR; PG8_MMA(1, 0, At, B0); PG8_MMA(1, 1, At, B1); PG8_BAR; PG8_SCHED;
;             PG8_LDB(B0, 1, 0); PG8_LDB(B1, 1, 1); PG8_SCHED; PG8_LDA(At, 1, 0); PG8_STAGE(PG8_SA(0, 1), a2 + hstep, voffA);
;             PG8_WAIT_V(8); PG8_WAIT_L(0); PG8_BAR; PG8_MMA(0, 0, At, B0); PG8_MMA(0, 1, At, B1); PG8_BAR; PG8_SCHED;
	s_nop 0
	s_waitcnt lgkmcnt(0)
	v_mfma_f32_16x16x32_bf16 v[62:65], v[146:149], v[182:185], v[62:65]
	v_mfma_f32_16x16x32_bf16 v[58:61], v[154:157], v[182:185], v[58:61]
	v_mfma_f32_16x16x32_bf16 v[54:57], v[146:149], v[194:197], v[54:57]
	v_mfma_f32_16x16x32_bf16 v[50:53], v[154:157], v[194:197], v[50:53]
	v_mfma_f32_16x16x32_bf16 v[38:41], v[146:149], v[202:205], v[38:41]
	v_mfma_f32_16x16x32_bf16 v[34:37], v[154:157], v[202:205], v[34:37]
	v_mfma_f32_16x16x32_bf16 v[22:25], v[146:149], v[216:219], v[22:25]
	v_mfma_f32_16x16x32_bf16 v[18:21], v[154:157], v[216:219], v[18:21]
	v_mfma_f32_16x16x32_bf16 v[62:65], v[150:153], v[190:193], v[62:65]
	v_mfma_f32_16x16x32_bf16 v[58:61], v[158:161], v[190:193], v[58:61]
	v_mfma_f32_16x16x32_bf16 v[54:57], v[150:153], v[198:201], v[54:57]
	v_mfma_f32_16x16x32_bf16 v[50:53], v[158:161], v[198:201], v[50:53]
	v_mfma_f32_16x16x32_bf16 v[38:41], v[150:153], v[212:215], v[38:41]
	v_mfma_f32_16x16x32_bf16 v[34:37], v[158:161], v[212:215], v[34:37]
	v_mfma_f32_16x16x32_bf16 v[22:25], v[150:153], v[220:223], v[22:25]
	v_mfma_f32_16x16x32_bf16 v[18:21], v[158:161], v[220:223], v[18:21]
	s_nop 0
	s_nop 0
	v_mfma_f32_16x16x32_bf16 v[46:49], v[162:165], v[182:185], v[46:49]
	v_mfma_f32_16x16x32_bf16 v[42:45], v[170:173], v[182:185], v[42:45]
	v_mfma_f32_16x16x32_bf16 v[30:33], v[162:165], v[194:197], v[30:33]
	v_mfma_f32_16x16x32_bf16 v[26:29], v[170:173], v[194:197], v[26:29]
	v_mfma_f32_16x16x32_bf16 v[14:17], v[162:165], v[202:205], v[14:17]
	v_mfma_f32_16x16x32_bf16 v[10:13], v[170:173], v[202:205], v[10:13]
	v_mfma_f32_16x16x32_bf16 v[6:9], v[162:165], v[216:219], v[6:9]
	v_mfma_f32_16x16x32_bf16 v[2:5], v[170:173], v[216:219], v[2:5]
	v_mfma_f32_16x16x32_bf16 v[46:49], v[166:169], v[190:193], v[46:49]
	v_mfma_f32_16x16x32_bf16 v[42:45], v[174:177], v[190:193], v[42:45]
	v_mfma_f32_16x16x32_bf16 v[30:33], v[166:169], v[198:201], v[30:33]
	v_mfma_f32_16x16x32_bf16 v[26:29], v[174:177], v[198:201], v[26:29]
	v_mfma_f32_16x16x32_bf16 v[14:17], v[166:169], v[212:215], v[14:17]
	v_mfma_f32_16x16x32_bf16 v[10:13], v[174:177], v[212:215], v[10:13]
	v_mfma_f32_16x16x32_bf16 v[6:9], v[166:169], v[220:223], v[6:9]
	v_mfma_f32_16x16x32_bf16 v[2:5], v[174:177], v[220:223], v[2:5]
	s_nop 0
	s_barrier
	s_add_i32 s94, 0, 0x18000
	v_add_u32_e32 v145, s94, v143
	s_add_i32 vcc_hi, 0, 0x1c000
	ds_read_b128 v[146:149], v145
	ds_read_b128 v[150:153], v145 offset:1024
	ds_read_b128 v[154:157], v145 offset:2048
	ds_read_b128 v[158:161], v145 offset:3072
	v_add_u32_e32 v145, vcc_hi, v143
	ds_read_b128 v[162:165], v145
	ds_read_b128 v[166:169], v145 offset:1024
	ds_read_b128 v[170:173], v145 offset:2048
	ds_read_b128 v[174:177], v145 offset:3072
	s_add_u32 s48, s72, 0x40000
	s_addc_u32 s49, s73, 0
	s_mov_b32 m0, s81
	v_lshl_add_u64 v[232:233], s[48:49], 0, v[136:137]
	ds_read_b128 v[182:185], v144 offset:32768
	ds_read_b128 v[190:193], v144 offset:33792
	ds_read_b128 v[194:197], v144 offset:34816
	ds_read_b128 v[198:201], v144 offset:35840
	ds_read_b128 v[202:205], v144 offset:36864
	ds_read_b128 v[212:215], v144 offset:37888
	ds_read_b128 v[216:219], v144 offset:38912
	ds_read_b128 v[220:223], v144 offset:39936
	global_load_lds_dwordx4 v[232:233], off
	v_lshl_add_u64 v[232:233], s[48:49], 0, v[132:133]
	s_mov_b32 m0, s83
	s_nop 0
	global_load_lds_dwordx4 v[232:233], off
	s_waitcnt vmcnt(8)
	s_waitcnt lgkmcnt(0)
	s_barrier
	s_nop 0
	s_waitcnt lgkmcnt(0)
	v_mfma_f32_16x16x32_bf16 v[126:129], v[146:149], v[182:185], v[126:129]
	v_mfma_f32_16x16x32_bf16 v[122:125], v[154:157], v[182:185], v[122:125]
	v_mfma_f32_16x16x32_bf16 v[118:121], v[146:149], v[194:197], v[118:121]
	v_mfma_f32_16x16x32_bf16 v[114:117], v[154:157], v[194:197], v[114:117]
	v_mfma_f32_16x16x32_bf16 v[102:105], v[146:149], v[202:205], v[102:105]
	v_mfma_f32_16x16x32_bf16 v[98:101], v[154:157], v[202:205], v[98:101]
	v_mfma_f32_16x16x32_bf16 v[86:89], v[146:149], v[216:219], v[86:89]
	v_mfma_f32_16x16x32_bf16 v[82:85], v[154:157], v[216:219], v[82:85]
	v_mfma_f32_16x16x32_bf16 v[126:129], v[150:153], v[190:193], v[126:129]
	v_mfma_f32_16x16x32_bf16 v[122:125], v[158:161], v[190:193], v[122:125]
	v_mfma_f32_16x16x32_bf16 v[118:121], v[150:153], v[198:201], v[118:121]
	v_mfma_f32_16x16x32_bf16 v[114:117], v[158:161], v[198:201], v[114:117]
	v_mfma_f32_16x16x32_bf16 v[102:105], v[150:153], v[212:215], v[102:105]
	v_mfma_f32_16x16x32_bf16 v[98:101], v[158:161], v[212:215], v[98:101]
	v_mfma_f32_16x16x32_bf16 v[86:89], v[150:153], v[220:223], v[86:89]
	v_mfma_f32_16x16x32_bf16 v[82:85], v[158:161], v[220:223], v[82:85]
	s_nop 0
	s_nop 0
	v_mfma_f32_16x16x32_bf16 v[110:113], v[162:165], v[182:185], v[110:113]
	v_mfma_f32_16x16x32_bf16 v[106:109], v[170:173], v[182:185], v[106:109]
	v_mfma_f32_16x16x32_bf16 v[94:97], v[162:165], v[194:197], v[94:97]
	v_mfma_f32_16x16x32_bf16 v[90:93], v[170:173], v[194:197], v[90:93]
	v_mfma_f32_16x16x32_bf16 v[78:81], v[162:165], v[202:205], v[78:81]
	v_mfma_f32_16x16x32_bf16 v[74:77], v[170:173], v[202:205], v[74:77]
	v_mfma_f32_16x16x32_bf16 v[70:73], v[162:165], v[216:219], v[70:73]
	v_mfma_f32_16x16x32_bf16 v[66:69], v[170:173], v[216:219], v[66:69]
	v_mfma_f32_16x16x32_bf16 v[110:113], v[166:169], v[190:193], v[110:113]
	v_mfma_f32_16x16x32_bf16 v[106:109], v[174:177], v[190:193], v[106:109]
	v_mfma_f32_16x16x32_bf16 v[94:97], v[166:169], v[198:201], v[94:97]
	v_mfma_f32_16x16x32_bf16 v[90:93], v[174:177], v[198:201], v[90:93]
	v_mfma_f32_16x16x32_bf16 v[78:81], v[166:169], v[212:215], v[78:81]
	v_mfma_f32_16x16x32_bf16 v[74:77], v[174:177], v[212:215], v[74:77]
	v_mfma_f32_16x16x32_bf16 v[70:73], v[166:169], v[220:223], v[70:73]
	v_mfma_f32_16x16x32_bf16 v[66:69], v[174:177], v[220:223], v[66:69]
	s_nop 0
	s_barrier
; #define PG8_STAGE(bufoff, gbase, voff) do { _Pragma("unroll") for (int _i = 0; _i < 2; ++_i) \
;         __builtin_amdgcn_global_load_lds((const unsigned*)((const char*)(gbase) + (voff)[_i]), (LAS unsigned*)(lds + (bufoff) + ldsw + _i * 8192), 16, 0, 0); } while (0)
; #define PG8_LDA(dst, b, h) do { _Pragma("unroll") for (int m = 0; m < 4; ++m) _Pragma("unroll") for (int k = 0; k < 2; ++k) dst[m][k] = *(const LAS bf16x8*)(lds + PG8_SA(b, h) + aoff + m * 2048 + k * 1024); } while (0)
; #define PG8_MMA(ai, bj, At, Bt) do { __builtin_amdgcn_s_setprio(1); _Pragma("unroll") for (int m = 0; m < 4; ++m) _Pragma("unroll") for (int n = 0; n < 2; ++n) _Pragma("unroll") for (int k = 0; k < 2; ++k) \
;         acc[ai][bj][m][n] = __builtin_amdgcn_mfma_f32_16x16x32_bf16(Bt[n][k], At[m][k], acc[ai][bj][m][n], 0, 0, 0); __builtin_amdgcn_s_setprio(0); } while (0)
; #define PG8_WAIT_V(n) asm volatile("s_waitcnt vmcnt(" #n ")" ::: "memory")
; #define PG8_WAIT_L(n) asm volatile("s_waitcnt lgkmcnt(" #n ")" ::: "memory")
; #define PG8_BAR __builtin_amdgcn_s_barrier()
; #define PG8_SCHED __builtin_amdgcn_sched_barrier(0)
; template <class Epi, class Sched>
; DI void gemm_phase(LAS unsigned char* lds, const int K, const Sched& S, const Epi& E) {
;     ...
;             PG8_LDA(At, 1, 1); PG8_STAGE(PG8_SB(1, 0), b3, voffB); PG8_STAGE(PG8_SB(1, 1), b3 + hstep, voffB); PG8_STAGE(PG8_SA(1, 0), a3, voffA);
;             PG8_WAIT_V(8); PG8_WAIT_L(0); PG8_BAR; PG8_MMA(1, 0, At, B0); PG8_MMA(1, 1, At, B1); PG8_BAR; PG8_SCHED;
;         }
	s_add_i32 s48, s94, s78
	v_lshl_add_u64 v[224:225], v[224:225], 0, s[90:91]
	s_mov_b32 m0, s48
	ds_read_b128 v[182:185], v144 offset:49152
	ds_read_b128 v[190:193], v144 offset:50176
	ds_read_b128 v[194:197], v144 offset:51200
	ds_read_b128 v[198:201], v144 offset:52224
	ds_read_b128 v[202:205], v144 offset:53248
	ds_read_b128 v[212:215], v144 offset:54272
	ds_read_b128 v[216:219], v144 offset:55296
	ds_read_b128 v[220:223], v144 offset:56320
	global_load_lds_dwordx4 v[224:225], off
	s_add_i32 m0, s48, 0x2000
	s_add_u32 s48, s70, 0x40080
	v_lshl_add_u64 v[224:225], v[226:227], 0, s[90:91]
	s_addc_u32 s49, s71, 0
	s_add_i32 s70, vcc_hi, s78
	global_load_lds_dwordx4 v[224:225], off
	v_lshl_add_u64 v[224:225], s[48:49], 0, v[134:135]
	s_mov_b32 m0, s70
	s_nop 0
	global_load_lds_dwordx4 v[224:225], off
	v_lshl_add_u64 v[224:225], s[48:49], 0, v[130:131]
	s_add_i32 m0, s70, 0x2000
	s_nop 0
	global_load_lds_dwordx4 v[224:225], off
	v_lshl_add_u64 v[224:225], v[228:229], 0, s[90:91]
	s_mov_b32 m0, s95
	s_nop 0
	global_load_lds_dwordx4 v[224:225], off
	v_lshl_add_u64 v[224:225], v[230:231], 0, s[90:91]
	s_mov_b32 m0, s42
	s_nop 0
	global_load_lds_dwordx4 v[224:225], off
	s_waitcnt vmcnt(8)
	s_waitcnt lgkmcnt(0)
	s_barrier
	s_nop 0
	s_waitcnt lgkmcnt(0)
	v_mfma_f32_16x16x32_bf16 v[62:65], v[146:149], v[182:185], v[62:65]
	v_mfma_f32_16x16x32_bf16 v[58:61], v[154:157], v[182:185], v[58:61]
	v_mfma_f32_16x16x32_bf16 v[54:57], v[146:149], v[194:197], v[54:57]
	v_mfma_f32_16x16x32_bf16 v[50:53], v[154:157], v[194:197], v[50:53]
	v_mfma_f32_16x16x32_bf16 v[38:41], v[146:149], v[202:205], v[38:41]
	v_mfma_f32_16x16x32_bf16 v[34:37], v[154:157], v[202:205], v[34:37]
	v_mfma_f32_16x16x32_bf16 v[22:25], v[146:149], v[216:219], v[22:25]
	v_mfma_f32_16x16x32_bf16 v[18:21], v[154:157], v[216:219], v[18:21]
	v_mfma_f32_16x16x32_bf16 v[62:65], v[150:153], v[190:193], v[62:65]
	v_mfma_f32_16x16x32_bf16 v[58:61], v[158:161], v[190:193], v[58:61]
	v_mfma_f32_16x16x32_bf16 v[54:57], v[150:153], v[198:201], v[54:57]
	v_mfma_f32_16x16x32_bf16 v[50:53], v[158:161], v[198:201], v[50:53]
	v_mfma_f32_16x16x32_bf16 v[38:41], v[150:153], v[212:215], v[38:41]
	v_mfma_f32_16x16x32_bf16 v[34:37], v[158:161], v[212:215], v[34:37]
	v_mfma_f32_16x16x32_bf16 v[22:25], v[150:153], v[220:223], v[22:25]
	v_mfma_f32_16x16x32_bf16 v[18:21], v[158:161], v[220:223], v[18:21]
	s_nop 0
	s_nop 0
	v_mfma_f32_16x16x32_bf16 v[46:49], v[162:165], v[182:185], v[46:49]
	v_mfma_f32_16x16x32_bf16 v[42:45], v[170:173], v[182:185], v[42:45]
	v_mfma_f32_16x16x32_bf16 v[30:33], v[162:165], v[194:197], v[30:33]
	v_mfma_f32_16x16x32_bf16 v[26:29], v[170:173], v[194:197], v[26:29]
	v_mfma_f32_16x16x32_bf16 v[14:17], v[162:165], v[202:205], v[14:17]
	v_mfma_f32_16x16x32_bf16 v[10:13], v[170:173], v[202:205], v[10:13]
	v_mfma_f32_16x16x32_bf16 v[6:9], v[162:165], v[216:219], v[6:9]
	v_mfma_f32_16x16x32_bf16 v[2:5], v[170:173], v[216:219], v[2:5]
	v_mfma_f32_16x16x32_bf16 v[46:49], v[166:169], v[190:193], v[46:49]
	v_mfma_f32_16x16x32_bf16 v[42:45], v[174:177], v[190:193], v[42:45]
	v_mfma_f32_16x16x32_bf16 v[30:33], v[166:169], v[198:201], v[30:33]
	v_mfma_f32_16x16x32_bf16 v[26:29], v[174:177], v[198:201], v[26:29]
	v_mfma_f32_16x16x32_bf16 v[14:17], v[166:169], v[212:215], v[14:17]
	v_mfma_f32_16x16x32_bf16 v[10:13], v[174:177], v[212:215], v[10:13]
	v_mfma_f32_16x16x32_bf16 v[6:9], v[166:169], v[220:223], v[6:9]
	v_mfma_f32_16x16x32_bf16 v[2:5], v[174:177], v[220:223], v[2:5]
	s_nop 0
	s_barrier
	s_add_i32 vcc_lo, vcc_lo, 2
	s_add_u32 s61, s61, 0x100
	s_addc_u32 s63, s63, 0
	s_add_u32 s68, s68, 0x100
	s_addc_u32 s69, s69, 0
	s_cmp_gt_u32 vcc_lo, 13
	s_cbranch_scc0 .LBB0_1086
	s_and_b64 vcc, exec, s[56:57]
	s_cbranch_vccz .LBB0_1089
	s_barrier

; #define PG8_STAGE(bufoff, gbase, voff) do { _Pragma("unroll") for (int _i = 0; _i < 2; ++_i) \
;         __builtin_amdgcn_global_load_lds((const unsigned*)((const char*)(gbase) + (voff)[_i]), (LAS unsigned*)(lds + (bufoff) + ldsw + _i * 8192), 16, 0, 0); } while (0)
; #define PG8_LDA(dst, b, h) do { _Pragma("unroll") for (int m = 0; m < 4; ++m) _Pragma("unroll") for (int k = 0; k < 2; ++k) dst[m][k] = *(const LAS bf16x8*)(lds + PG8_SA(b, h) + aoff + m * 2048 + k * 1024); } while (0)
; #define PG8_LDB(dst, b, h) do { _Pragma("unroll") for (int n = 0; n < 2; ++n) _Pragma("unroll") for (int k = 0; k < 2; ++k) dst[n][k] = *(const LAS bf16x8*)(lds + PG8_SB(b, h) + boff + n * 2048 + k * 1024); } while (0)
; #define PG8_MMA(ai, bj, At, Bt) do { __builtin_amdgcn_s_setprio(1); _Pragma("unroll") for (int m = 0; m < 4; ++m) _Pragma("unroll") for (int n = 0; n < 2; ++n) _Pragma("unroll") for (int k = 0; k < 2; ++k) \
;         acc[ai][bj][m][n] = __builtin_amdgcn_mfma_f32_16x16x32_bf16(Bt[n][k], At[m][k], acc[ai][bj][m][n], 0, 0, 0); __builtin_amdgcn_s_setprio(0); } while (0)
; #define PG8_WAIT_V(n) asm volatile("s_waitcnt vmcnt(" #n ")" ::: "memory")
; #define PG8_WAIT_L(n) asm volatile("s_waitcnt lgkmcnt(" #n ")" ::: "memory")
; #define PG8_BAR __builtin_amdgcn_s_barrier()
; #define PG8_SCHED __builtin_amdgcn_sched_barrier(0)
; template <class Epi, class Sched>
; DI void gemm_phase(LAS unsigned char* lds, const int K, const Sched& S, const Epi& E) {
;     ...
;             const bool last = (t == nt - 2);
;             const char* a1 = cA + (size_t)(t + 1) * kstep;
;             const char* a2 = last ? nA : cA + (size_t)(t + 2) * kstep; const char* b2 = last ? nB : cB + (size_t)(t + 2) * kstep;
;             const char* a3 = a2 + kstep; const char* b3 = b2 + kstep;
;             PG8_LDB(B0, 0, 0); PG8_LDB(B1, 0, 1); PG8_SCHED; PG8_LDA(At, 0, 0); PG8_STAGE(PG8_SA(1, 1), a1 + hstep, voffA);
;             PG8_WAIT_V(8); PG8_WAIT_L(0); PG8_BAR; PG8_MMA(0, 0, At, B0); PG8_MMA(0, 1, At, B1); PG8_BAR; PG8_SCHED;
;             PG8_LDA(At, 0, 1); PG8_STAGE(PG8_SB(0, 0), b2, voffB); PG8_STAGE(PG8_SB(0, 1), b2 + hstep, voffB); PG8_STAGE(PG8_SA(0, 0), a2, voffA);
.LBB0_1204:
	s_add_u32 s60, s58, 0x100
	s_addc_u32 s61, s59, 0
	s_add_i32 s48, 0, 0x10000
	s_cmp_eq_u32 s85, 40
	s_cselect_b32 s65, s55, s61
	s_cselect_b32 s64, s54, s60
	v_add_u32_e32 v145, s48, v143
	s_cselect_b32 s63, s57, s84
	s_cselect_b32 s62, s56, s83
	s_add_i32 s86, 0, 0x14000
	ds_read_b128 v[146:149], v145
	ds_read_b128 v[150:153], v145 offset:1024
	ds_read_b128 v[154:157], v145 offset:2048
	ds_read_b128 v[158:161], v145 offset:3072
	v_add_u32_e32 v145, s86, v143
	ds_read_b128 v[162:165], v145
	ds_read_b128 v[166:169], v145 offset:1024
	ds_read_b128 v[170:173], v145 offset:2048
	ds_read_b128 v[174:177], v145 offset:3072
	v_lshl_add_u64 v[224:225], s[58:59], 0, v[140:141]
	s_add_i32 m0, s71, 0xc000
	ds_read_b128 v[182:185], v144
	ds_read_b128 v[190:193], v144 offset:1024
	ds_read_b128 v[194:197], v144 offset:2048
	ds_read_b128 v[198:201], v144 offset:3072
	ds_read_b128 v[202:205], v144 offset:4096
	ds_read_b128 v[212:215], v144 offset:5120
	ds_read_b128 v[216:219], v144 offset:6144
	ds_read_b128 v[220:223], v144 offset:7168
	global_load_lds_dwordx4 v[224:225], off
	v_lshl_add_u64 v[224:225], s[58:59], 0, v[138:139]
	s_add_i32 m0, s71, 0xe000
	s_nop 0
	global_load_lds_dwordx4 v[224:225], off
	s_waitcnt vmcnt(8)
	s_waitcnt lgkmcnt(0)
	s_barrier
	s_nop 0
	s_waitcnt lgkmcnt(0)
	v_mfma_f32_16x16x32_bf16 v[126:129], v[146:149], v[182:185], v[126:129]
	v_mfma_f32_16x16x32_bf16 v[122:125], v[154:157], v[182:185], v[122:125]
	v_mfma_f32_16x16x32_bf16 v[118:121], v[146:149], v[194:197], v[118:121]
	v_mfma_f32_16x16x32_bf16 v[114:117], v[154:157], v[194:197], v[114:117]
	v_mfma_f32_16x16x32_bf16 v[102:105], v[146:149], v[202:205], v[102:105]
	v_mfma_f32_16x16x32_bf16 v[98:101], v[154:157], v[202:205], v[98:101]
	v_mfma_f32_16x16x32_bf16 v[86:89], v[146:149], v[216:219], v[86:89]
	v_mfma_f32_16x16x32_bf16 v[82:85], v[154:157], v[216:219], v[82:85]
	v_mfma_f32_16x16x32_bf16 v[126:129], v[150:153], v[190:193], v[126:129]
	v_mfma_f32_16x16x32_bf16 v[122:125], v[158:161], v[190:193], v[122:125]
	v_mfma_f32_16x16x32_bf16 v[118:121], v[150:153], v[198:201], v[118:121]
	v_mfma_f32_16x16x32_bf16 v[114:117], v[158:161], v[198:201], v[114:117]
	v_mfma_f32_16x16x32_bf16 v[102:105], v[150:153], v[212:215], v[102:105]
	v_mfma_f32_16x16x32_bf16 v[98:101], v[158:161], v[212:215], v[98:101]
	v_mfma_f32_16x16x32_bf16 v[86:89], v[150:153], v[220:223], v[86:89]
	v_mfma_f32_16x16x32_bf16 v[82:85], v[158:161], v[220:223], v[82:85]
	s_nop 0
	s_nop 0
	v_mfma_f32_16x16x32_bf16 v[110:113], v[162:165], v[182:185], v[110:113]
	v_mfma_f32_16x16x32_bf16 v[106:109], v[170:173], v[182:185], v[106:109]
	v_mfma_f32_16x16x32_bf16 v[94:97], v[162:165], v[194:197], v[94:97]
	v_mfma_f32_16x16x32_bf16 v[90:93], v[170:173], v[194:197], v[90:93]
	v_mfma_f32_16x16x32_bf16 v[78:81], v[162:165], v[202:205], v[78:81]
	v_mfma_f32_16x16x32_bf16 v[74:77], v[170:173], v[202:205], v[74:77]
	v_mfma_f32_16x16x32_bf16 v[70:73], v[162:165], v[216:219], v[70:73]
	v_mfma_f32_16x16x32_bf16 v[66:69], v[170:173], v[216:219], v[66:69]
	v_mfma_f32_16x16x32_bf16 v[110:113], v[166:169], v[190:193], v[110:113]
	v_mfma_f32_16x16x32_bf16 v[106:109], v[174:177], v[190:193], v[106:109]
	v_mfma_f32_16x16x32_bf16 v[94:97], v[166:169], v[198:201], v[94:97]
	v_mfma_f32_16x16x32_bf16 v[90:93], v[174:177], v[198:201], v[90:93]
	v_mfma_f32_16x16x32_bf16 v[78:81], v[166:169], v[212:215], v[78:81]
	v_mfma_f32_16x16x32_bf16 v[74:77], v[174:177], v[212:215], v[74:77]
	v_mfma_f32_16x16x32_bf16 v[70:73], v[166:169], v[220:223], v[70:73]
	v_mfma_f32_16x16x32_bf16 v[66:69], v[174:177], v[220:223], v[66:69]
	s_nop 0
	s_barrier
	s_add_i32 s48, s48, s69
	v_lshl_add_u64 v[224:225], s[62:63], 0, v[134:135]
	s_mov_b32 m0, s48
	ds_read_b128 v[182:185], v144 offset:16384
	ds_read_b128 v[190:193], v144 offset:17408
	ds_read_b128 v[194:197], v144 offset:18432
	ds_read_b128 v[198:201], v144 offset:19456
	ds_read_b128 v[202:205], v144 offset:20480
	ds_read_b128 v[212:215], v144 offset:21504
	ds_read_b128 v[216:219], v144 offset:22528
	ds_read_b128 v[220:223], v144 offset:23552
	global_load_lds_dwordx4 v[224:225], off
	s_add_i32 m0, s48, 0x2000
	s_add_u32 s48, s62, 0xb0000
	v_lshl_add_u64 v[226:227], s[62:63], 0, v[130:131]
	s_addc_u32 s49, s63, 0
	s_add_i32 s58, s86, s69
	global_load_lds_dwordx4 v[226:227], off
	v_lshl_add_u64 v[228:229], s[48:49], 0, v[134:135]
	s_mov_b32 m0, s58
	v_lshl_add_u64 v[230:231], s[64:65], 0, v[132:133]
	global_load_lds_dwordx4 v[228:229], off
	v_lshl_add_u64 v[228:229], s[48:49], 0, v[130:131]
	s_add_i32 m0, s58, 0x2000
	s_nop 0
	global_load_lds_dwordx4 v[228:229], off
	v_lshl_add_u64 v[228:229], s[64:65], 0, v[136:137]
	s_mov_b32 m0, s71
	s_nop 0
	global_load_lds_dwordx4 v[228:229], off
	s_mov_b32 m0, s72
	s_nop 0
	global_load_lds_dwordx4 v[230:231], off
	s_waitcnt vmcnt(8)
	s_waitcnt lgkmcnt(0)
	s_barrier
; #define PG8_STAGE(bufoff, gbase, voff) do { _Pragma("unroll") for (int _i = 0; _i < 2; ++_i) \
;         __builtin_amdgcn_global_load_lds((const unsigned*)((const char*)(gbase) + (voff)[_i]), (LAS unsigned*)(lds + (bufoff) + ldsw + _i * 8192), 16, 0, 0); } while (0)
; #define PG8_LDA(dst, b, h) do { _Pragma("unroll") for (int m = 0; m < 4; ++m) _Pragma("unroll") for (int k = 0; k < 2; ++k) dst[m][k] = *(const LAS bf16x8*)(lds + PG8_SA(b, h) + aoff + m * 2048 + k * 1024); } while (0)
; #define PG8_LDB(dst, b, h) do { _Pragma("unroll") for (int n = 0; n < 2; ++n) _Pragma("unroll") for (int k = 0; k < 2; ++k) dst[n][k] = *(const LAS bf16x8*)(lds + PG8_SB(b, h) + boff + n * 2048 + k * 1024); } while (0)
; #define PG8_MMA(ai, bj, At, Bt) do { __builtin_amdgcn_s_setprio(1); _Pragma("unroll") for (int m = 0; m < 4; ++m) _Pragma("unroll") for (int n = 0; n < 2; ++n) _Pragma("unroll") for (int k = 0; k < 2; ++k) \
;         acc[ai][bj][m][n] = __builtin_amdgcn_mfma_f32_16x16x32_bf16(Bt[n][k], At[m][k], acc[ai][bj][m][n], 0, 0, 0); __builtin_amdgcn_s_setprio(0); } while (0)
; #define PG8_WAIT_V(n) asm volatile("s_waitcnt vmcnt(" #n ")" ::: "memory")
; #define PG8_WAIT_L(n) asm volatile("s_waitcnt lgkmcnt(" #n ")" ::: "memory")
; #define PG8_BAR __builtin_amdgcn_s_barrier()
; #define PG8_SCHED __builtin_amdgcn_sched_barrier(0)
; template <class Epi, class Sched>
; DI void gemm_phase(LAS unsigned char* lds, const int K, const Sched& S, const Epi& E) {
;     ...
;             PG8_WAIT_V(8); PG8_WAIT_L(0); PG8_BAR; PG8_MMA(1, 0, At, B0); PG8_MMA(1, 1, At, B1); PG8_BAR; PG8_SCHED;
;             PG8_LDB(B0, 1, 0); PG8_LDB(B1, 1, 1); PG8_SCHED; PG8_LDA(At, 1, 0); PG8_STAGE(PG8_SA(0, 1), a2 + hstep, voffA);
;             PG8_WAIT_V(8); PG8_WAIT_L(0); PG8_BAR; PG8_MMA(0, 0, At, B0); PG8_MMA(0, 1, At, B1); PG8_BAR; PG8_SCHED;
	s_nop 0
	s_waitcnt lgkmcnt(0)
	v_mfma_f32_16x16x32_bf16 v[62:65], v[146:149], v[182:185], v[62:65]
	v_mfma_f32_16x16x32_bf16 v[58:61], v[154:157], v[182:185], v[58:61]
	v_mfma_f32_16x16x32_bf16 v[54:57], v[146:149], v[194:197], v[54:57]
	v_mfma_f32_16x16x32_bf16 v[50:53], v[154:157], v[194:197], v[50:53]
	v_mfma_f32_16x16x32_bf16 v[38:41], v[146:149], v[202:205], v[38:41]
	v_mfma_f32_16x16x32_bf16 v[34:37], v[154:157], v[202:205], v[34:37]
	v_mfma_f32_16x16x32_bf16 v[22:25], v[146:149], v[216:219], v[22:25]
	v_mfma_f32_16x16x32_bf16 v[18:21], v[154:157], v[216:219], v[18:21]
	v_mfma_f32_16x16x32_bf16 v[62:65], v[150:153], v[190:193], v[62:65]
	v_mfma_f32_16x16x32_bf16 v[58:61], v[158:161], v[190:193], v[58:61]
	v_mfma_f32_16x16x32_bf16 v[54:57], v[150:153], v[198:201], v[54:57]
	v_mfma_f32_16x16x32_bf16 v[50:53], v[158:161], v[198:201], v[50:53]
	v_mfma_f32_16x16x32_bf16 v[38:41], v[150:153], v[212:215], v[38:41]
	v_mfma_f32_16x16x32_bf16 v[34:37], v[158:161], v[212:215], v[34:37]
	v_mfma_f32_16x16x32_bf16 v[22:25], v[150:153], v[220:223], v[22:25]
	v_mfma_f32_16x16x32_bf16 v[18:21], v[158:161], v[220:223], v[18:21]
	s_nop 0
	s_nop 0
	v_mfma_f32_16x16x32_bf16 v[46:49], v[162:165], v[182:185], v[46:49]
	v_mfma_f32_16x16x32_bf16 v[42:45], v[170:173], v[182:185], v[42:45]
	v_mfma_f32_16x16x32_bf16 v[30:33], v[162:165], v[194:197], v[30:33]
	v_mfma_f32_16x16x32_bf16 v[26:29], v[170:173], v[194:197], v[26:29]
	v_mfma_f32_16x16x32_bf16 v[14:17], v[162:165], v[202:205], v[14:17]
	v_mfma_f32_16x16x32_bf16 v[10:13], v[170:173], v[202:205], v[10:13]
	v_mfma_f32_16x16x32_bf16 v[6:9], v[162:165], v[216:219], v[6:9]
	v_mfma_f32_16x16x32_bf16 v[2:5], v[170:173], v[216:219], v[2:5]
	v_mfma_f32_16x16x32_bf16 v[46:49], v[166:169], v[190:193], v[46:49]
	v_mfma_f32_16x16x32_bf16 v[42:45], v[174:177], v[190:193], v[42:45]
	v_mfma_f32_16x16x32_bf16 v[30:33], v[166:169], v[198:201], v[30:33]
	v_mfma_f32_16x16x32_bf16 v[26:29], v[174:177], v[198:201], v[26:29]
	v_mfma_f32_16x16x32_bf16 v[14:17], v[166:169], v[212:215], v[14:17]
	v_mfma_f32_16x16x32_bf16 v[10:13], v[174:177], v[212:215], v[10:13]
	v_mfma_f32_16x16x32_bf16 v[6:9], v[166:169], v[220:223], v[6:9]
	v_mfma_f32_16x16x32_bf16 v[2:5], v[174:177], v[220:223], v[2:5]
	s_nop 0
	s_barrier
	s_add_i32 s58, 0, 0x18000
	v_add_u32_e32 v145, s58, v143
	s_add_i32 s59, 0, 0x1c000
	ds_read_b128 v[146:149], v145
	ds_read_b128 v[150:153], v145 offset:1024
	ds_read_b128 v[154:157], v145 offset:2048
	ds_read_b128 v[158:161], v145 offset:3072
	v_add_u32_e32 v145, s59, v143
	ds_read_b128 v[162:165], v145
	ds_read_b128 v[166:169], v145 offset:1024
	ds_read_b128 v[170:173], v145 offset:2048
	ds_read_b128 v[174:177], v145 offset:3072
	s_add_u32 s48, s64, 0xb0000
	s_addc_u32 s49, s65, 0
	s_mov_b32 m0, s73
	v_lshl_add_u64 v[232:233], s[48:49], 0, v[136:137]
	ds_read_b128 v[182:185], v144 offset:32768
	ds_read_b128 v[190:193], v144 offset:33792
	ds_read_b128 v[194:197], v144 offset:34816
	ds_read_b128 v[198:201], v144 offset:35840
	ds_read_b128 v[202:205], v144 offset:36864
	ds_read_b128 v[212:215], v144 offset:37888
	ds_read_b128 v[216:219], v144 offset:38912
	ds_read_b128 v[220:223], v144 offset:39936
	global_load_lds_dwordx4 v[232:233], off
	v_lshl_add_u64 v[232:233], s[48:49], 0, v[132:133]
	s_mov_b32 m0, s74
	s_nop 0
	global_load_lds_dwordx4 v[232:233], off
	s_waitcnt vmcnt(8)
	s_waitcnt lgkmcnt(0)
	s_barrier
	s_nop 0
	s_waitcnt lgkmcnt(0)
	v_mfma_f32_16x16x32_bf16 v[126:129], v[146:149], v[182:185], v[126:129]
	v_mfma_f32_16x16x32_bf16 v[122:125], v[154:157], v[182:185], v[122:125]
	v_mfma_f32_16x16x32_bf16 v[118:121], v[146:149], v[194:197], v[118:121]
	v_mfma_f32_16x16x32_bf16 v[114:117], v[154:157], v[194:197], v[114:117]
	v_mfma_f32_16x16x32_bf16 v[102:105], v[146:149], v[202:205], v[102:105]
	v_mfma_f32_16x16x32_bf16 v[98:101], v[154:157], v[202:205], v[98:101]
	v_mfma_f32_16x16x32_bf16 v[86:89], v[146:149], v[216:219], v[86:89]
	v_mfma_f32_16x16x32_bf16 v[82:85], v[154:157], v[216:219], v[82:85]
	v_mfma_f32_16x16x32_bf16 v[126:129], v[150:153], v[190:193], v[126:129]
	v_mfma_f32_16x16x32_bf16 v[122:125], v[158:161], v[190:193], v[122:125]
	v_mfma_f32_16x16x32_bf16 v[118:121], v[150:153], v[198:201], v[118:121]
	v_mfma_f32_16x16x32_bf16 v[114:117], v[158:161], v[198:201], v[114:117]
	v_mfma_f32_16x16x32_bf16 v[102:105], v[150:153], v[212:215], v[102:105]
	v_mfma_f32_16x16x32_bf16 v[98:101], v[158:161], v[212:215], v[98:101]
	v_mfma_f32_16x16x32_bf16 v[86:89], v[150:153], v[220:223], v[86:89]
	v_mfma_f32_16x16x32_bf16 v[82:85], v[158:161], v[220:223], v[82:85]
	s_nop 0
	s_nop 0
	v_mfma_f32_16x16x32_bf16 v[110:113], v[162:165], v[182:185], v[110:113]
	v_mfma_f32_16x16x32_bf16 v[106:109], v[170:173], v[182:185], v[106:109]
	v_mfma_f32_16x16x32_bf16 v[94:97], v[162:165], v[194:197], v[94:97]
	v_mfma_f32_16x16x32_bf16 v[90:93], v[170:173], v[194:197], v[90:93]
	v_mfma_f32_16x16x32_bf16 v[78:81], v[162:165], v[202:205], v[78:81]
	v_mfma_f32_16x16x32_bf16 v[74:77], v[170:173], v[202:205], v[74:77]
	v_mfma_f32_16x16x32_bf16 v[70:73], v[162:165], v[216:219], v[70:73]
	v_mfma_f32_16x16x32_bf16 v[66:69], v[170:173], v[216:219], v[66:69]
	v_mfma_f32_16x16x32_bf16 v[110:113], v[166:169], v[190:193], v[110:113]
	v_mfma_f32_16x16x32_bf16 v[106:109], v[174:177], v[190:193], v[106:109]
	v_mfma_f32_16x16x32_bf16 v[94:97], v[166:169], v[198:201], v[94:97]
	v_mfma_f32_16x16x32_bf16 v[90:93], v[174:177], v[198:201], v[90:93]
	v_mfma_f32_16x16x32_bf16 v[78:81], v[166:169], v[212:215], v[78:81]
	v_mfma_f32_16x16x32_bf16 v[74:77], v[174:177], v[212:215], v[74:77]
	v_mfma_f32_16x16x32_bf16 v[70:73], v[166:169], v[220:223], v[70:73]
	v_mfma_f32_16x16x32_bf16 v[66:69], v[174:177], v[220:223], v[66:69]
	s_nop 0
	s_barrier
; #define PG8_STAGE(bufoff, gbase, voff) do { _Pragma("unroll") for (int _i = 0; _i < 2; ++_i) \
;         __builtin_amdgcn_global_load_lds((const unsigned*)((const char*)(gbase) + (voff)[_i]), (LAS unsigned*)(lds + (bufoff) + ldsw + _i * 8192), 16, 0, 0); } while (0)
; #define PG8_LDA(dst, b, h) do { _Pragma("unroll") for (int m = 0; m < 4; ++m) _Pragma("unroll") for (int k = 0; k < 2; ++k) dst[m][k] = *(const LAS bf16x8*)(lds + PG8_SA(b, h) + aoff + m * 2048 + k * 1024); } while (0)
; #define PG8_MMA(ai, bj, At, Bt) do { __builtin_amdgcn_s_setprio(1); _Pragma("unroll") for (int m = 0; m < 4; ++m) _Pragma("unroll") for (int n = 0; n < 2; ++n) _Pragma("unroll") for (int k = 0; k < 2; ++k) \
;         acc[ai][bj][m][n] = __builtin_amdgcn_mfma_f32_16x16x32_bf16(Bt[n][k], At[m][k], acc[ai][bj][m][n], 0, 0, 0); __builtin_amdgcn_s_setprio(0); } while (0)
; #define PG8_WAIT_V(n) asm volatile("s_waitcnt vmcnt(" #n ")" ::: "memory")
; #define PG8_WAIT_L(n) asm volatile("s_waitcnt lgkmcnt(" #n ")" ::: "memory")
; #define PG8_BAR __builtin_amdgcn_s_barrier()
; #define PG8_SCHED __builtin_amdgcn_sched_barrier(0)
; template <class Epi, class Sched>
; DI void gemm_phase(LAS unsigned char* lds, const int K, const Sched& S, const Epi& E) {
;     ...
;             PG8_LDA(At, 1, 1); PG8_STAGE(PG8_SB(1, 0), b3, voffB); PG8_STAGE(PG8_SB(1, 1), b3 + hstep, voffB); PG8_STAGE(PG8_SA(1, 0), a3, voffA);
;             PG8_WAIT_V(8); PG8_WAIT_L(0); PG8_BAR; PG8_MMA(1, 0, At, B0); PG8_MMA(1, 1, At, B1); PG8_BAR; PG8_SCHED;
;         }
	s_add_i32 s48, s58, s69
	v_lshl_add_u64 v[224:225], v[224:225], 0, s[90:91]
	s_mov_b32 m0, s48
	ds_read_b128 v[182:185], v144 offset:49152
	ds_read_b128 v[190:193], v144 offset:50176
	ds_read_b128 v[194:197], v144 offset:51200
	ds_read_b128 v[198:201], v144 offset:52224
	ds_read_b128 v[202:205], v144 offset:53248
	ds_read_b128 v[212:215], v144 offset:54272
	ds_read_b128 v[216:219], v144 offset:55296
	ds_read_b128 v[220:223], v144 offset:56320
	global_load_lds_dwordx4 v[224:225], off
	s_add_i32 m0, s48, 0x2000
	s_add_u32 s48, s62, 0xb0080
	v_lshl_add_u64 v[224:225], v[226:227], 0, s[90:91]
	s_addc_u32 s49, s63, 0
	s_add_i32 s58, s59, s69
	global_load_lds_dwordx4 v[224:225], off
	v_lshl_add_u64 v[224:225], s[48:49], 0, v[134:135]
	s_mov_b32 m0, s58
	s_nop 0
	global_load_lds_dwordx4 v[224:225], off
	v_lshl_add_u64 v[224:225], s[48:49], 0, v[130:131]
	s_add_i32 m0, s58, 0x2000
	s_nop 0
	global_load_lds_dwordx4 v[224:225], off
	v_lshl_add_u64 v[224:225], v[228:229], 0, s[90:91]
	s_mov_b32 m0, s77
	s_nop 0
	global_load_lds_dwordx4 v[224:225], off
	v_lshl_add_u64 v[224:225], v[230:231], 0, s[90:91]
	s_mov_b32 m0, s78
	s_nop 0
	global_load_lds_dwordx4 v[224:225], off
	s_waitcnt vmcnt(8)
	s_waitcnt lgkmcnt(0)
	s_barrier
	s_nop 0
	s_waitcnt lgkmcnt(0)
	v_mfma_f32_16x16x32_bf16 v[62:65], v[146:149], v[182:185], v[62:65]
	v_mfma_f32_16x16x32_bf16 v[58:61], v[154:157], v[182:185], v[58:61]
	v_mfma_f32_16x16x32_bf16 v[54:57], v[146:149], v[194:197], v[54:57]
	v_mfma_f32_16x16x32_bf16 v[50:53], v[154:157], v[194:197], v[50:53]
	v_mfma_f32_16x16x32_bf16 v[38:41], v[146:149], v[202:205], v[38:41]
	v_mfma_f32_16x16x32_bf16 v[34:37], v[154:157], v[202:205], v[34:37]
	v_mfma_f32_16x16x32_bf16 v[22:25], v[146:149], v[216:219], v[22:25]
	v_mfma_f32_16x16x32_bf16 v[18:21], v[154:157], v[216:219], v[18:21]
	v_mfma_f32_16x16x32_bf16 v[62:65], v[150:153], v[190:193], v[62:65]
	v_mfma_f32_16x16x32_bf16 v[58:61], v[158:161], v[190:193], v[58:61]
	v_mfma_f32_16x16x32_bf16 v[54:57], v[150:153], v[198:201], v[54:57]
	v_mfma_f32_16x16x32_bf16 v[50:53], v[158:161], v[198:201], v[50:53]
	v_mfma_f32_16x16x32_bf16 v[38:41], v[150:153], v[212:215], v[38:41]
	v_mfma_f32_16x16x32_bf16 v[34:37], v[158:161], v[212:215], v[34:37]
	v_mfma_f32_16x16x32_bf16 v[22:25], v[150:153], v[220:223], v[22:25]
	v_mfma_f32_16x16x32_bf16 v[18:21], v[158:161], v[220:223], v[18:21]
	s_nop 0
	s_nop 0
	v_mfma_f32_16x16x32_bf16 v[46:49], v[162:165], v[182:185], v[46:49]
	v_mfma_f32_16x16x32_bf16 v[42:45], v[170:173], v[182:185], v[42:45]
	v_mfma_f32_16x16x32_bf16 v[30:33], v[162:165], v[194:197], v[30:33]
	v_mfma_f32_16x16x32_bf16 v[26:29], v[170:173], v[194:197], v[26:29]
	v_mfma_f32_16x16x32_bf16 v[14:17], v[162:165], v[202:205], v[14:17]
	v_mfma_f32_16x16x32_bf16 v[10:13], v[170:173], v[202:205], v[10:13]
	v_mfma_f32_16x16x32_bf16 v[6:9], v[162:165], v[216:219], v[6:9]
	v_mfma_f32_16x16x32_bf16 v[2:5], v[170:173], v[216:219], v[2:5]
	v_mfma_f32_16x16x32_bf16 v[46:49], v[166:169], v[190:193], v[46:49]
	v_mfma_f32_16x16x32_bf16 v[42:45], v[174:177], v[190:193], v[42:45]
	v_mfma_f32_16x16x32_bf16 v[30:33], v[166:169], v[198:201], v[30:33]
	v_mfma_f32_16x16x32_bf16 v[26:29], v[174:177], v[198:201], v[26:29]
	v_mfma_f32_16x16x32_bf16 v[14:17], v[166:169], v[212:215], v[14:17]
	v_mfma_f32_16x16x32_bf16 v[10:13], v[174:177], v[212:215], v[10:13]
	v_mfma_f32_16x16x32_bf16 v[6:9], v[166:169], v[220:223], v[6:9]
	v_mfma_f32_16x16x32_bf16 v[2:5], v[174:177], v[220:223], v[2:5]
	s_nop 0
	s_barrier
	s_add_i32 s85, s85, 2
	s_add_u32 s83, s83, 0x100
	s_addc_u32 s84, s84, 0
	s_cmp_gt_u32 s85, 41
	s_mov_b64 s[58:59], s[60:61]
	s_cbranch_scc0 .LBB0_1204
	s_and_b64 vcc, exec, s[52:53]
	s_cbranch_vccz .LBB0_1207
	s_barrier
